# Hyena FFT stagger: waves 4-7 sleep 2x64 cycles after every workgroup barrier
# baseline (speedup 1.0000x reference)
; #define LAS __attribute__((address_space(3)))
; #define WG_SYNC() do { asm volatile("s_waitcnt lgkmcnt(0)" ::: "memory"); __builtin_amdgcn_s_barrier(); asm volatile("" ::: "memory"); } while (0)
; __device__ __forceinline__ void hy_stage(LAS float* plane, const bf16_t* PHY, int cg, int jc, int tid) {
;     asm volatile("" : "+v"(tid));
;     const u32x4* src = (const u32x4*)(PHY + (size_t)cg * MT * 4);
; #pragma unroll
;     for (int k = 0; k < 8; ++k) { const int i = tid + 512 * k; const u32x4 v = src[i];
;         const unsigned w0 = (jc & 2) ? v.y : v.x, w1 = (jc & 2) ? v.w : v.z;
;         f32x2 o; o.x = (jc & 1) ? bf_hi(w0) : bf_lo(w0); o.y = (jc & 1) ? bf_hi(w1) : bf_lo(w1);
;         *(LAS f32x2*)(plane + 2 * i) = o; }
; }
; __device__ __forceinline__ void hyena_fft(LAS unsigned char* lds, int layer, int G, const int wave_s) {
;     ...
;         for (int c = c_lo; c < c_hi; ++c) { const int unit = c >> 2, jc = c & 3;
;             WG_SYNC();
;             { f32x2 x[16]; const unsigned* tf = TF + (size_t)c * SEQ; const unsigned* tb = TB + (size_t)c * SEQ;
; #pragma unroll
;               for (int r = 0; r < 8; ++r) { const unsigned w = tf[n2 + 512 * r]; x[r] = (f32x2){bf_lo(w), bf_hi(w)}; }
; #pragma unroll
;               for (int r = 8; r < 16; ++r) { const int l = FN - 512 * r - n2; const unsigned w = l < SEQ ? tb[l] : 0u; x[r] = (f32x2){bf_lo(w), bf_hi(w)}; }
;               __builtin_amdgcn_sched_barrier(0); fft_fwd1<false>(x, Fb, n2, w1p); __builtin_amdgcn_sched_barrier(0); }
.Lhfft_loop:
	s_lshr_b32 s43, s80, 2
	s_mul_i32 s73, s43, 0x11000
	s_and_b32 s43, s80, 2
	s_lshl_b32 s43, s43, 1
	s_add_u32 s73, s73, s43
	s_and_b32 s43, s80, 1
	s_mov_b32 s15, 0x1000c0c
	s_cmp_eq_u32 s43, 0
	s_cselect_b32 s15, s15, 0x3020c0c
	s_lshl_b32 s43, s80, 14
	s_add_u32 s46, s36, s43
	s_addc_u32 s47, s37, 0
	s_add_u32 s50, s46, 0x4000000
	s_addc_u32 s51, s47, 0
	s_waitcnt lgkmcnt(0)
	s_barrier
	s_cbranch_vccz .Lhfft_st1
	s_sleep 2
.Lhfft_st1:
	s_add_u32 s60, s46, 0
	s_addc_u32 s61, s47, 0
	global_load_dword v176, v212, s[60:61]
	global_load_dword v178, v212, s[60:61] offset:2048
	s_add_u32 s60, s46, 0x1000
	s_addc_u32 s61, s47, 0
	global_load_dword v180, v212, s[60:61]
	global_load_dword v182, v212, s[60:61] offset:2048
	s_add_u32 s60, s46, 0x2000
	s_addc_u32 s61, s47, 0
	global_load_dword v184, v212, s[60:61]
	global_load_dword v186, v212, s[60:61] offset:2048
	s_add_u32 s60, s46, 0x3000
	s_addc_u32 s61, s47, 0
	global_load_dword v188, v212, s[60:61]
	global_load_dword v166, v212, s[60:61] offset:2048
	s_add_u32 s62, s50, 0x3000
	s_addc_u32 s63, s51, 0
	global_load_dword v177, v214, s[62:63] offset:2048
	global_load_dword v179, v214, s[62:63]
	s_add_u32 s62, s50, 0x2000
	s_addc_u32 s63, s51, 0
	global_load_dword v181, v214, s[62:63] offset:2048
	global_load_dword v183, v214, s[62:63]
	s_add_u32 s62, s50, 0x1000
	s_addc_u32 s63, s51, 0
	global_load_dword v185, v214, s[62:63] offset:2048
	global_load_dword v187, v214, s[62:63]
	s_add_u32 s62, s50, 0
	s_addc_u32 s63, s51, 0
	global_load_dword v189, v214, s[62:63] offset:2048
	global_load_dword v167, v214, s[62:63]
	s_add_u32 s56, s38, s73
	s_addc_u32 s57, s39, 0
	s_add_u32 s56, s56, 0x2200000
	s_addc_u32 s57, s57, 0
	global_load_dwordx3 v[58:60], v216, s[56:57]
	global_load_dwordx3 v[62:64], v218, s[56:57]
	global_load_dwordx3 v[66:68], v220, s[56:57]
	global_load_dwordx3 v[70:72], v222, s[56:57]
	global_load_dwordx3 v[74:76], v240, s[56:57]
	global_load_dwordx3 v[78:80], v242, s[56:57]
	global_load_dwordx3 v[82:84], v244, s[56:57]
	global_load_dwordx3 v[86:88], v61, s[56:57]
	s_waitcnt vmcnt(23)
	v_and_b32_e32 v101, 0xffff0000, v176
	v_lshlrev_b32_e32 v100, 16, v176
	s_waitcnt vmcnt(22)
	v_and_b32_e32 v103, 0xffff0000, v178
	v_lshlrev_b32_e32 v102, 16, v178
	s_waitcnt vmcnt(21)
	v_and_b32_e32 v105, 0xffff0000, v180
	v_lshlrev_b32_e32 v104, 16, v180
	s_waitcnt vmcnt(20)
	v_and_b32_e32 v107, 0xffff0000, v182
	v_lshlrev_b32_e32 v106, 16, v182
	s_waitcnt vmcnt(19)
	v_and_b32_e32 v109, 0xffff0000, v184
	v_lshlrev_b32_e32 v108, 16, v184
	s_waitcnt vmcnt(18)
	v_and_b32_e32 v111, 0xffff0000, v186
	v_lshlrev_b32_e32 v110, 16, v186
	s_waitcnt vmcnt(17)
	v_and_b32_e32 v113, 0xffff0000, v188
	v_lshlrev_b32_e32 v112, 16, v188
	s_waitcnt vmcnt(16)
	v_and_b32_e32 v115, 0xffff0000, v166
	v_lshlrev_b32_e32 v114, 16, v166
	s_waitcnt vmcnt(15)
	v_cndmask_b32_e64 v177, v177, 0, s[10:11]
	v_and_b32_e32 v117, 0xffff0000, v177
	v_lshlrev_b32_e32 v116, 16, v177
	s_waitcnt vmcnt(14)
	v_and_b32_e32 v119, 0xffff0000, v179
	v_lshlrev_b32_e32 v118, 16, v179
	s_waitcnt vmcnt(13)
	v_and_b32_e32 v121, 0xffff0000, v181
	v_lshlrev_b32_e32 v120, 16, v181
	s_waitcnt vmcnt(12)
	v_and_b32_e32 v123, 0xffff0000, v183
	v_lshlrev_b32_e32 v122, 16, v183
	s_waitcnt vmcnt(11)
	v_and_b32_e32 v125, 0xffff0000, v185
	v_lshlrev_b32_e32 v124, 16, v185
	s_waitcnt vmcnt(10)
	v_and_b32_e32 v127, 0xffff0000, v187
	v_lshlrev_b32_e32 v126, 16, v187
	s_waitcnt vmcnt(9)
	v_and_b32_e32 v129, 0xffff0000, v189
	v_lshlrev_b32_e32 v128, 16, v189
	s_waitcnt vmcnt(8)
	v_and_b32_e32 v131, 0xffff0000, v167
	v_lshlrev_b32_e32 v130, 16, v167
	v_pk_add_f32 v[168:169], v[100:101], v[116:117]
	v_pk_add_f32 v[174:175], v[100:101], v[116:117] neg_lo:[0,1] neg_hi:[0,1]
	v_pk_add_f32 v[176:177], v[108:109], v[124:125]
	v_pk_add_f32 v[178:179], v[108:109], v[124:125] neg_lo:[0,1] neg_hi:[0,1]
	v_pk_add_f32 v[100:101], v[168:169], v[176:177]
	v_pk_add_f32 v[116:117], v[168:169], v[176:177] neg_lo:[0,1] neg_hi:[0,1]
	v_pk_add_f32 v[108:109], v[174:175], v[178:179] op_sel:[0,1] op_sel_hi:[1,0] neg_hi:[0,1]
	v_pk_add_f32 v[124:125], v[174:175], v[178:179] op_sel:[0,1] op_sel_hi:[1,0] neg_lo:[0,1]
	v_pk_add_f32 v[180:181], v[102:103], v[118:119]
	v_pk_add_f32 v[182:183], v[102:103], v[118:119] neg_lo:[0,1] neg_hi:[0,1]
	v_pk_add_f32 v[184:185], v[110:111], v[126:127]
	v_pk_add_f32 v[186:187], v[110:111], v[126:127] neg_lo:[0,1] neg_hi:[0,1]
	v_pk_add_f32 v[102:103], v[180:181], v[184:185]
	v_pk_add_f32 v[118:119], v[180:181], v[184:185] neg_lo:[0,1] neg_hi:[0,1]
	v_pk_add_f32 v[110:111], v[182:183], v[186:187] op_sel:[0,1] op_sel_hi:[1,0] neg_hi:[0,1]
	v_pk_add_f32 v[126:127], v[182:183], v[186:187] op_sel:[0,1] op_sel_hi:[1,0] neg_lo:[0,1]
	v_pk_add_f32 v[188:189], v[104:105], v[120:121]
	v_pk_add_f32 v[166:167], v[104:105], v[120:121] neg_lo:[0,1] neg_hi:[0,1]
	v_pk_add_f32 v[168:169], v[112:113], v[128:129]
	v_pk_add_f32 v[174:175], v[112:113], v[128:129] neg_lo:[0,1] neg_hi:[0,1]
	v_pk_add_f32 v[104:105], v[188:189], v[168:169]
	v_pk_add_f32 v[120:121], v[188:189], v[168:169] neg_lo:[0,1] neg_hi:[0,1]
	v_pk_add_f32 v[112:113], v[166:167], v[174:175] op_sel:[0,1] op_sel_hi:[1,0] neg_hi:[0,1]
	v_pk_add_f32 v[128:129], v[166:167], v[174:175] op_sel:[0,1] op_sel_hi:[1,0] neg_lo:[0,1]
	v_pk_add_f32 v[176:177], v[106:107], v[122:123]
	v_pk_add_f32 v[178:179], v[106:107], v[122:123] neg_lo:[0,1] neg_hi:[0,1]
	v_pk_add_f32 v[180:181], v[114:115], v[130:131]
	v_pk_add_f32 v[182:183], v[114:115], v[130:131] neg_lo:[0,1] neg_hi:[0,1]
	v_pk_add_f32 v[106:107], v[176:177], v[180:181]
	v_pk_add_f32 v[122:123], v[176:177], v[180:181] neg_lo:[0,1] neg_hi:[0,1]
; #define LAS __attribute__((address_space(3)))
; __device__ __forceinline__ f32x2 cmul(f32x2 a, f32x2 b) { return (f32x2){a.x * b.x - a.y * b.y, a.x * b.y + a.y * b.x}; }
; template <bool INV> __device__ __forceinline__ f32x2 cmul_tw(f32x2 a, f32x2 w) { return INV ? cmulc(a, w) : cmul(a, w); }
; template <bool INV> __device__ __forceinline__ void dft16(f32x2 (&x)[16]) {
;     ...
;     const f32x2 w1 = {C1, -S1}, w2 = {C2, -C2}, w3 = {S1, -C1}, w4 = {0.f, -1.f}, w6 = {-C2, -C2}, w9 = {-C1, S1};
;     x[4 * 1 + 1] = cmul_tw<INV>(x[5], w1); x[4 * 1 + 2] = cmul_tw<INV>(x[6], w2); x[4 * 1 + 3] = cmul_tw<INV>(x[7], w3);
;     x[4 * 2 + 1] = cmul_tw<INV>(x[9], w2); x[4 * 2 + 2] = cmul_tw<INV>(x[10], w4); x[4 * 2 + 3] = cmul_tw<INV>(x[11], w6);
;     x[4 * 3 + 1] = cmul_tw<INV>(x[13], w3); x[4 * 3 + 2] = cmul_tw<INV>(x[14], w6); x[4 * 3 + 3] = cmul_tw<INV>(x[15], w9);
; #pragma unroll
;     for (int c = 0; c < 4; ++c) dft4<INV>(x[4 * c], x[4 * c + 1], x[4 * c + 2], x[4 * c + 3]);
;     f32x2 y[16];
; #pragma unroll
;     for (int k = 0; k < 16; ++k) y[k] = x[4 * (k & 3) + (k >> 2)];
; #pragma unroll
;     for (int k = 0; k < 16; ++k) x[k] = y[k];
; template <bool LO> __device__ __forceinline__ void fft_fwd1(f32x2 (&x)[16], LAS f32x2* B, int n2, const f32x2 (&w)[16]) {
;     asm volatile("" : "+v"(n2));
;     if (LO) dft16_fwd_lo(x); else dft16<false>(x);
;     B[fpad(n2)] = x[0];
; #pragma unroll
;     for (int k = 1; k < 16; ++k) B[fpad(512 * k + n2)] = cmul(x[k], w[k]);
; }
	v_pk_add_f32 v[114:115], v[178:179], v[182:183] op_sel:[0,1] op_sel_hi:[1,0] neg_hi:[0,1]
	v_pk_add_f32 v[130:131], v[178:179], v[182:183] op_sel:[0,1] op_sel_hi:[1,0] neg_lo:[0,1]
	v_pk_mul_f32 v[184:185], v[110:111], s[68:69] op_sel:[1,1] op_sel_hi:[0,1]
	v_pk_fma_f32 v[110:111], v[110:111], s[68:69], v[184:185] op_sel_hi:[1,0,1] neg_lo:[0,0,1]
	v_pk_mul_f32 v[186:187], v[112:113], s[84:85] op_sel:[1,1] op_sel_hi:[0,1]
	v_pk_fma_f32 v[112:113], v[112:113], s[84:85], v[186:187] op_sel_hi:[1,0,1] neg_lo:[0,0,1]
	v_pk_mul_f32 v[188:189], v[114:115], s[88:89] op_sel:[1,1] op_sel_hi:[0,1]
	v_pk_fma_f32 v[114:115], v[114:115], s[88:89], v[188:189] op_sel_hi:[1,0,1] neg_lo:[0,0,1]
	v_pk_mul_f32 v[166:167], v[118:119], s[84:85] op_sel:[1,1] op_sel_hi:[0,1]
	v_pk_fma_f32 v[118:119], v[118:119], s[84:85], v[166:167] op_sel_hi:[1,0,1] neg_lo:[0,0,1]
	v_pk_mul_f32 v[168:169], v[122:123], s[90:91] op_sel:[1,1] op_sel_hi:[0,1]
	v_pk_fma_f32 v[122:123], v[122:123], s[90:91], v[168:169] op_sel_hi:[1,0,1] neg_lo:[0,0,1]
	v_pk_mul_f32 v[174:175], v[126:127], s[88:89] op_sel:[1,1] op_sel_hi:[0,1]
	v_pk_fma_f32 v[126:127], v[126:127], s[88:89], v[174:175] op_sel_hi:[1,0,1] neg_lo:[0,0,1]
	v_pk_mul_f32 v[176:177], v[128:129], s[90:91] op_sel:[1,1] op_sel_hi:[0,1]
	v_pk_fma_f32 v[128:129], v[128:129], s[90:91], v[176:177] op_sel_hi:[1,0,1] neg_lo:[0,0,1]
	v_pk_mul_f32 v[178:179], v[130:131], s[98:99] op_sel:[1,1] op_sel_hi:[0,1]
	v_pk_fma_f32 v[130:131], v[130:131], s[98:99], v[178:179] op_sel_hi:[1,0,1] neg_lo:[0,0,1]
	v_pk_add_f32 v[180:181], v[100:101], v[104:105]
	v_pk_add_f32 v[182:183], v[100:101], v[104:105] neg_lo:[0,1] neg_hi:[0,1]
	v_pk_add_f32 v[184:185], v[102:103], v[106:107]
	v_pk_add_f32 v[186:187], v[102:103], v[106:107] neg_lo:[0,1] neg_hi:[0,1]
	v_pk_add_f32 v[100:101], v[180:181], v[184:185]
	v_pk_add_f32 v[104:105], v[180:181], v[184:185] neg_lo:[0,1] neg_hi:[0,1]
	v_pk_add_f32 v[102:103], v[182:183], v[186:187] op_sel:[0,1] op_sel_hi:[1,0] neg_hi:[0,1]
	v_pk_add_f32 v[106:107], v[182:183], v[186:187] op_sel:[0,1] op_sel_hi:[1,0] neg_lo:[0,1]
	v_pk_add_f32 v[188:189], v[108:109], v[112:113]
	v_pk_add_f32 v[166:167], v[108:109], v[112:113] neg_lo:[0,1] neg_hi:[0,1]
	v_pk_add_f32 v[168:169], v[110:111], v[114:115]
	v_pk_add_f32 v[174:175], v[110:111], v[114:115] neg_lo:[0,1] neg_hi:[0,1]
	v_pk_add_f32 v[108:109], v[188:189], v[168:169]
	v_pk_add_f32 v[112:113], v[188:189], v[168:169] neg_lo:[0,1] neg_hi:[0,1]
	v_pk_add_f32 v[110:111], v[166:167], v[174:175] op_sel:[0,1] op_sel_hi:[1,0] neg_hi:[0,1]
	v_pk_add_f32 v[114:115], v[166:167], v[174:175] op_sel:[0,1] op_sel_hi:[1,0] neg_lo:[0,1]
	v_pk_add_f32 v[176:177], v[116:117], v[120:121] op_sel:[0,1] op_sel_hi:[1,0] neg_hi:[0,1]
	v_pk_add_f32 v[178:179], v[116:117], v[120:121] op_sel:[0,1] op_sel_hi:[1,0] neg_lo:[0,1]
	v_pk_add_f32 v[180:181], v[118:119], v[122:123]
	v_pk_add_f32 v[182:183], v[118:119], v[122:123] neg_lo:[0,1] neg_hi:[0,1]
	v_pk_add_f32 v[116:117], v[176:177], v[180:181]
	v_pk_add_f32 v[120:121], v[176:177], v[180:181] neg_lo:[0,1] neg_hi:[0,1]
	v_pk_add_f32 v[118:119], v[178:179], v[182:183] op_sel:[0,1] op_sel_hi:[1,0] neg_hi:[0,1]
	v_pk_add_f32 v[122:123], v[178:179], v[182:183] op_sel:[0,1] op_sel_hi:[1,0] neg_lo:[0,1]
	v_pk_add_f32 v[184:185], v[124:125], v[128:129]
	v_pk_add_f32 v[186:187], v[124:125], v[128:129] neg_lo:[0,1] neg_hi:[0,1]
	v_pk_add_f32 v[188:189], v[126:127], v[130:131]
	v_pk_add_f32 v[166:167], v[126:127], v[130:131] neg_lo:[0,1] neg_hi:[0,1]
	v_pk_add_f32 v[124:125], v[184:185], v[188:189]
	v_pk_add_f32 v[128:129], v[184:185], v[188:189] neg_lo:[0,1] neg_hi:[0,1]
	v_pk_add_f32 v[126:127], v[186:187], v[166:167] op_sel:[0,1] op_sel_hi:[1,0] neg_hi:[0,1]
	v_pk_add_f32 v[130:131], v[186:187], v[166:167] op_sel:[0,1] op_sel_hi:[1,0] neg_lo:[0,1]
	v_add_u32_e32 v65, 0x10800, v3
	ds_write_b64 v65, v[100:101]
	v_pk_mul_f32 v[174:175], v[108:109], v[6:7] op_sel:[1,1] op_sel_hi:[0,1]
	v_pk_fma_f32 v[168:169], v[108:109], v[6:7], v[174:175] op_sel_hi:[1,0,1] neg_lo:[0,0,1]
	ds_write_b64 v65, v[168:169] offset:4224
	v_pk_mul_f32 v[178:179], v[116:117], v[8:9] op_sel:[1,1] op_sel_hi:[0,1]
	v_pk_fma_f32 v[176:177], v[116:117], v[8:9], v[178:179] op_sel_hi:[1,0,1] neg_lo:[0,0,1]
	ds_write_b64 v65, v[176:177] offset:8448
	v_pk_mul_f32 v[182:183], v[124:125], v[10:11] op_sel:[1,1] op_sel_hi:[0,1]
	v_pk_fma_f32 v[180:181], v[124:125], v[10:11], v[182:183] op_sel_hi:[1,0,1] neg_lo:[0,0,1]
	ds_write_b64 v65, v[180:181] offset:12672
	v_pk_mul_f32 v[186:187], v[102:103], v[12:13] op_sel:[1,1] op_sel_hi:[0,1]
	v_pk_fma_f32 v[184:185], v[102:103], v[12:13], v[186:187] op_sel_hi:[1,0,1] neg_lo:[0,0,1]
	ds_write_b64 v65, v[184:185] offset:16896
	v_pk_mul_f32 v[166:167], v[110:111], v[14:15] op_sel:[1,1] op_sel_hi:[0,1]
	v_pk_fma_f32 v[188:189], v[110:111], v[14:15], v[166:167] op_sel_hi:[1,0,1] neg_lo:[0,0,1]
	ds_write_b64 v65, v[188:189] offset:21120
	v_pk_mul_f32 v[168:169], v[118:119], v[16:17] op_sel:[1,1] op_sel_hi:[0,1]
	v_pk_fma_f32 v[174:175], v[118:119], v[16:17], v[168:169] op_sel_hi:[1,0,1] neg_lo:[0,0,1]
	ds_write_b64 v65, v[174:175] offset:25344
	v_pk_mul_f32 v[176:177], v[126:127], v[18:19] op_sel:[1,1] op_sel_hi:[0,1]
	v_pk_fma_f32 v[178:179], v[126:127], v[18:19], v[176:177] op_sel_hi:[1,0,1] neg_lo:[0,0,1]
	ds_write_b64 v65, v[178:179] offset:29568
	v_pk_mul_f32 v[180:181], v[104:105], v[20:21] op_sel:[1,1] op_sel_hi:[0,1]
	v_pk_fma_f32 v[182:183], v[104:105], v[20:21], v[180:181] op_sel_hi:[1,0,1] neg_lo:[0,0,1]
	ds_write_b64 v65, v[182:183] offset:33792
	v_pk_mul_f32 v[184:185], v[112:113], v[22:23] op_sel:[1,1] op_sel_hi:[0,1]
	v_pk_fma_f32 v[186:187], v[112:113], v[22:23], v[184:185] op_sel_hi:[1,0,1] neg_lo:[0,0,1]
	ds_write_b64 v65, v[186:187] offset:38016
	v_pk_mul_f32 v[188:189], v[120:121], v[24:25] op_sel:[1,1] op_sel_hi:[0,1]
	v_pk_fma_f32 v[166:167], v[120:121], v[24:25], v[188:189] op_sel_hi:[1,0,1] neg_lo:[0,0,1]
	ds_write_b64 v65, v[166:167] offset:42240
	v_pk_mul_f32 v[174:175], v[128:129], v[26:27] op_sel:[1,1] op_sel_hi:[0,1]
	v_pk_fma_f32 v[168:169], v[128:129], v[26:27], v[174:175] op_sel_hi:[1,0,1] neg_lo:[0,0,1]
	ds_write_b64 v65, v[168:169] offset:46464
	v_pk_mul_f32 v[178:179], v[106:107], v[28:29] op_sel:[1,1] op_sel_hi:[0,1]
	v_pk_fma_f32 v[176:177], v[106:107], v[28:29], v[178:179] op_sel_hi:[1,0,1] neg_lo:[0,0,1]
	ds_write_b64 v65, v[176:177] offset:50688
	v_pk_mul_f32 v[182:183], v[114:115], v[30:31] op_sel:[1,1] op_sel_hi:[0,1]
	v_pk_fma_f32 v[180:181], v[114:115], v[30:31], v[182:183] op_sel_hi:[1,0,1] neg_lo:[0,0,1]
	ds_write_b64 v65, v[180:181] offset:54912
	v_pk_mul_f32 v[186:187], v[122:123], v[32:33] op_sel:[1,1] op_sel_hi:[0,1]
	v_pk_fma_f32 v[184:185], v[122:123], v[32:33], v[186:187] op_sel_hi:[1,0,1] neg_lo:[0,0,1]
	ds_write_b64 v65, v[184:185] offset:59136
	v_pk_mul_f32 v[166:167], v[130:131], v[34:35] op_sel:[1,1] op_sel_hi:[0,1]
	v_pk_fma_f32 v[188:189], v[130:131], v[34:35], v[166:167] op_sel_hi:[1,0,1] neg_lo:[0,0,1]
	ds_write_b64 v65, v[188:189] offset:63360
	s_waitcnt vmcnt(7)
; #define LAS __attribute__((address_space(3)))
; #define WG_SYNC() do { asm volatile("s_waitcnt lgkmcnt(0)" ::: "memory"); __builtin_amdgcn_s_barrier(); asm volatile("" ::: "memory"); } while (0)
; __device__ __forceinline__ void hy_stage(LAS float* plane, const bf16_t* PHY, int cg, int jc, int tid) {
;     asm volatile("" : "+v"(tid));
;     const u32x4* src = (const u32x4*)(PHY + (size_t)cg * MT * 4);
; #pragma unroll
;     for (int k = 0; k < 8; ++k) { const int i = tid + 512 * k; const u32x4 v = src[i];
;         const unsigned w0 = (jc & 2) ? v.y : v.x, w1 = (jc & 2) ? v.w : v.z;
;         f32x2 o; o.x = (jc & 1) ? bf_hi(w0) : bf_lo(w0); o.y = (jc & 1) ? bf_hi(w1) : bf_lo(w1);
;         *(LAS f32x2*)(plane + 2 * i) = o; }
; }
; __device__ __forceinline__ void hy_sconv(const LAS float* plane, float w0, float w1, float w2, float cb, int n2, float (&u)[8][2]) {
;     asm volatile("" : "+v"(n2));
; #pragma unroll
;     for (int r = 0; r < 8; ++r)
; #pragma unroll
;         for (int b = 0; b < 2; ++b) { const int t = n2 + 512 * r, row = b * SEQ + t;
;             float a = cb + w1 * plane[row];
;             if (t > 0) a += w0 * plane[row - 1];
;             if (t < SEQ - 1) a += w2 * plane[row + 1];
;             u[r][b] = a; }
; }
; __device__ __forceinline__ void hyena_fft(LAS unsigned char* lds, int layer, int G, const int wave_s) {
;     ...
;             hy_stage(pl0, PHY, 2 * (HY / 4) + unit, jc, tid); __builtin_amdgcn_sched_barrier(0); hy_stage(pl1, PHY, unit, jc, tid); __builtin_amdgcn_sched_barrier(0);
;             WG_SYNC();
;             float uz[8][2], ux[8][2];
;             hy_sconv(pl0, cw[2 * HY + c], cw[3 * HY + 2 * HY + c], cw[6 * HY + 2 * HY + c], cb[2 * HY + c], n2, uz);
	v_perm_b32 v174, 0, v58, s15
	v_perm_b32 v175, 0, v60, s15
	ds_write_b64 v206, v[174:175]
	s_waitcnt vmcnt(6)
	v_perm_b32 v168, 0, v62, s15
	v_perm_b32 v169, 0, v64, s15
	ds_write_b64 v206, v[168:169] offset:4096
	s_waitcnt vmcnt(5)
	v_perm_b32 v178, 0, v66, s15
	v_perm_b32 v179, 0, v68, s15
	ds_write_b64 v206, v[178:179] offset:8192
	s_waitcnt vmcnt(4)
	v_perm_b32 v176, 0, v70, s15
	v_perm_b32 v177, 0, v72, s15
	ds_write_b64 v206, v[176:177] offset:12288
	s_waitcnt vmcnt(3)
	v_perm_b32 v182, 0, v74, s15
	v_perm_b32 v183, 0, v76, s15
	ds_write_b64 v206, v[182:183] offset:16384
	s_waitcnt vmcnt(2)
	v_perm_b32 v180, 0, v78, s15
	v_perm_b32 v181, 0, v80, s15
	ds_write_b64 v206, v[180:181] offset:20480
	s_waitcnt vmcnt(1)
	v_perm_b32 v186, 0, v82, s15
	v_perm_b32 v187, 0, v84, s15
	ds_write_b64 v206, v[186:187] offset:24576
	s_waitcnt vmcnt(0)
	v_perm_b32 v184, 0, v86, s15
	v_perm_b32 v185, 0, v88, s15
	ds_write_b64 v206, v[184:185] offset:28672
	s_add_u32 s56, s38, s73
	s_addc_u32 s57, s39, 0
	global_load_dwordx3 v[58:60], v216, s[56:57]
	global_load_dwordx3 v[62:64], v218, s[56:57]
	global_load_dwordx3 v[66:68], v220, s[56:57]
	global_load_dwordx3 v[70:72], v222, s[56:57]
	global_load_dwordx3 v[74:76], v240, s[56:57]
	global_load_dwordx3 v[78:80], v242, s[56:57]
	global_load_dwordx3 v[82:84], v244, s[56:57]
	global_load_dwordx3 v[86:88], v61, s[56:57]
	s_load_dwordx2 s[60:61], s[94:95], 0x48
	s_load_dwordx2 s[62:63], s[94:95], 0x50
	s_load_dwordx2 s[50:51], s[94:95], 0x88
	s_lshl_b32 s43, s80, 2
	s_mul_i32 s53, s76, 0x9000
	s_add_u32 s53, s53, s43
	s_mul_i32 s55, s76, 0x3000
	s_add_u32 s55, s55, s43
	s_waitcnt lgkmcnt(0)
	s_add_u32 s60, s60, s53
	s_addc_u32 s61, s61, 0
	s_add_u32 s62, s62, s55
	s_addc_u32 s63, s63, 0
	s_mul_i32 s53, s76, 0x2000
	s_add_u32 s53, s53, s43
	s_add_u32 s50, s50, s53
	s_addc_u32 s51, s51, 0
	s_load_dword s17, s[60:61], 0x2000
	s_load_dword s23, s[60:61], 0x5000
	s_load_dword s25, s[60:61], 0x8000
	s_load_dword s26, s[62:63], 0x2000
	s_waitcnt lgkmcnt(0)
	s_barrier
	s_cbranch_vccz .Lhfft_st2
	s_sleep 2
.Lhfft_st2:
	v_mov_b32_e32 v166, s17
	v_mov_b32_e32 v167, s23
	v_mov_b32_e32 v188, s25
	v_mov_b32_e32 v189, s26
	ds_read_b32 v174, v208
	ds_read_b32 v168, v210
	ds_read_b32 v178, v208 offset:4
	ds_read_b32 v175, v208 offset:16384
	ds_read_b32 v169, v210 offset:16384
	ds_read_b32 v179, v208 offset:16388
	ds_read_b32 v176, v208 offset:2048
	ds_read_b32 v182, v208 offset:2044
	ds_read_b32 v180, v208 offset:2052
	ds_read_b32 v177, v208 offset:18432
	ds_read_b32 v183, v208 offset:18428
	ds_read_b32 v181, v208 offset:18436
	s_waitcnt lgkmcnt(10)
	v_cndmask_b32_e64 v168, v168, 0, s[10:11]
	s_waitcnt lgkmcnt(7)
	v_cndmask_b32_e64 v169, v169, 0, s[10:11]
	v_pk_fma_f32 v[132:133], v[166:167], v[174:175], v[188:189] op_sel:[1,0,1]
	v_pk_fma_f32 v[132:133], v[166:167], v[168:169], v[132:133] op_sel_hi:[0,1,1]
	s_waitcnt lgkmcnt(6)
	v_pk_fma_f32 v[132:133], v[188:189], v[178:179], v[132:133] op_sel_hi:[0,1,1]
	s_waitcnt lgkmcnt(2)
	v_pk_fma_f32 v[134:135], v[166:167], v[176:177], v[188:189] op_sel:[1,0,1]
	s_waitcnt lgkmcnt(1)
	v_pk_fma_f32 v[134:135], v[166:167], v[182:183], v[134:135] op_sel_hi:[0,1,1]
	s_waitcnt lgkmcnt(0)
	v_pk_fma_f32 v[134:135], v[188:189], v[180:181], v[134:135] op_sel_hi:[0,1,1]
	ds_read_b32 v186, v208 offset:4096
	ds_read_b32 v184, v208 offset:4092
	ds_read_b32 v174, v208 offset:4100
	ds_read_b32 v187, v208 offset:20480
	ds_read_b32 v185, v208 offset:20476
	ds_read_b32 v175, v208 offset:20484
	ds_read_b32 v168, v208 offset:6144
	ds_read_b32 v178, v208 offset:6140
	ds_read_b32 v176, v208 offset:6148
	ds_read_b32 v169, v208 offset:22528
	ds_read_b32 v179, v208 offset:22524
	ds_read_b32 v177, v208 offset:22532
	s_waitcnt lgkmcnt(8)
	v_pk_fma_f32 v[136:137], v[166:167], v[186:187], v[188:189] op_sel:[1,0,1]
	s_waitcnt lgkmcnt(7)
	v_pk_fma_f32 v[136:137], v[166:167], v[184:185], v[136:137] op_sel_hi:[0,1,1]
	s_waitcnt lgkmcnt(6)
	v_pk_fma_f32 v[136:137], v[188:189], v[174:175], v[136:137] op_sel_hi:[0,1,1]
	s_waitcnt lgkmcnt(2)
	v_pk_fma_f32 v[138:139], v[166:167], v[168:169], v[188:189] op_sel:[1,0,1]
	s_waitcnt lgkmcnt(1)
	v_pk_fma_f32 v[138:139], v[166:167], v[178:179], v[138:139] op_sel_hi:[0,1,1]
	s_waitcnt lgkmcnt(0)
	v_pk_fma_f32 v[138:139], v[188:189], v[176:177], v[138:139] op_sel_hi:[0,1,1]
	ds_read_b32 v182, v208 offset:8192
	ds_read_b32 v180, v208 offset:8188
	ds_read_b32 v186, v208 offset:8196
	ds_read_b32 v183, v208 offset:24576
	ds_read_b32 v181, v208 offset:24572
	ds_read_b32 v187, v208 offset:24580
	ds_read_b32 v184, v208 offset:10240
	ds_read_b32 v174, v208 offset:10236
	ds_read_b32 v168, v208 offset:10244
	ds_read_b32 v185, v208 offset:26624
	ds_read_b32 v175, v208 offset:26620
	ds_read_b32 v169, v208 offset:26628
	s_waitcnt lgkmcnt(8)
	v_pk_fma_f32 v[140:141], v[166:167], v[182:183], v[188:189] op_sel:[1,0,1]
	s_waitcnt lgkmcnt(7)
	v_pk_fma_f32 v[140:141], v[166:167], v[180:181], v[140:141] op_sel_hi:[0,1,1]
	s_waitcnt lgkmcnt(6)
	v_pk_fma_f32 v[140:141], v[188:189], v[186:187], v[140:141] op_sel_hi:[0,1,1]
	s_waitcnt lgkmcnt(2)
	v_pk_fma_f32 v[142:143], v[166:167], v[184:185], v[188:189] op_sel:[1,0,1]
	s_waitcnt lgkmcnt(1)
	v_pk_fma_f32 v[142:143], v[166:167], v[174:175], v[142:143] op_sel_hi:[0,1,1]
	s_waitcnt lgkmcnt(0)
	v_pk_fma_f32 v[142:143], v[188:189], v[168:169], v[142:143] op_sel_hi:[0,1,1]
	ds_read_b32 v178, v208 offset:12288
	ds_read_b32 v176, v208 offset:12284
	ds_read_b32 v182, v208 offset:12292
	ds_read_b32 v179, v208 offset:28672
	ds_read_b32 v177, v208 offset:28668
	ds_read_b32 v183, v208 offset:28676
	ds_read_b32 v180, v208 offset:14336
	ds_read_b32 v186, v208 offset:14332
	ds_read_b32 v184, v208 offset:14340
	ds_read_b32 v181, v208 offset:30720
	ds_read_b32 v187, v208 offset:30716
	ds_read_b32 v185, v208 offset:30724
	s_waitcnt lgkmcnt(8)
; #define LAS __attribute__((address_space(3)))
; __device__ __forceinline__ void fft_fwd2(LAS f32x2* B, const LAS f32x2* TW2, int tid) {
;     asm volatile("" : "+v"(tid));
;     const int b = tid >> 5, n2 = tid & 31, base = 512 * b + n2; f32x2 x[16];
; #pragma unroll
;     for (int r = 0; r < 16; ++r) x[r] = B[fpad(base + 32 * r)];
;     dft16<false>(x);
; __device__ __forceinline__ void hy_sconv(const LAS float* plane, float w0, float w1, float w2, float cb, int n2, float (&u)[8][2]) {
;     asm volatile("" : "+v"(n2));
; #pragma unroll
;     for (int r = 0; r < 8; ++r)
; #pragma unroll
;         for (int b = 0; b < 2; ++b) { const int t = n2 + 512 * r, row = b * SEQ + t;
;             float a = cb + w1 * plane[row];
;             if (t > 0) a += w0 * plane[row - 1];
;             if (t < SEQ - 1) a += w2 * plane[row + 1];
;             u[r][b] = a; }
; }
	v_pk_fma_f32 v[144:145], v[166:167], v[178:179], v[188:189] op_sel:[1,0,1]
	s_waitcnt lgkmcnt(7)
	v_pk_fma_f32 v[144:145], v[166:167], v[176:177], v[144:145] op_sel_hi:[0,1,1]
	s_waitcnt lgkmcnt(6)
	v_pk_fma_f32 v[144:145], v[188:189], v[182:183], v[144:145] op_sel_hi:[0,1,1]
	s_waitcnt lgkmcnt(3)
	v_cndmask_b32_e64 v184, v184, 0, s[28:29]
	s_waitcnt lgkmcnt(0)
	v_cndmask_b32_e64 v185, v185, 0, s[28:29]
	v_pk_fma_f32 v[146:147], v[166:167], v[180:181], v[188:189] op_sel:[1,0,1]
	v_pk_fma_f32 v[146:147], v[166:167], v[186:187], v[146:147] op_sel_hi:[0,1,1]
	v_pk_fma_f32 v[146:147], v[188:189], v[184:185], v[146:147] op_sel_hi:[0,1,1]
	s_load_dword s17, s[60:61], 0x0
	s_load_dword s23, s[60:61], 0x3000
	s_load_dword s25, s[60:61], 0x6000
	s_load_dword s26, s[62:63], 0x0
	s_waitcnt vmcnt(7)
	v_perm_b32 v174, 0, v58, s15
	v_perm_b32 v175, 0, v60, s15
	ds_write_b64 v206, v[174:175] offset:32768
	s_waitcnt vmcnt(6)
	v_perm_b32 v168, 0, v62, s15
	v_perm_b32 v169, 0, v64, s15
	ds_write_b64 v206, v[168:169] offset:36864
	s_waitcnt vmcnt(5)
	v_perm_b32 v178, 0, v66, s15
	v_perm_b32 v179, 0, v68, s15
	ds_write_b64 v206, v[178:179] offset:40960
	s_waitcnt vmcnt(4)
	v_perm_b32 v176, 0, v70, s15
	v_perm_b32 v177, 0, v72, s15
	ds_write_b64 v206, v[176:177] offset:45056
	s_waitcnt vmcnt(3)
	v_perm_b32 v182, 0, v74, s15
	v_perm_b32 v183, 0, v76, s15
	ds_write_b64 v206, v[182:183] offset:49152
	s_waitcnt vmcnt(2)
	v_perm_b32 v180, 0, v78, s15
	v_perm_b32 v181, 0, v80, s15
	ds_write_b64 v206, v[180:181] offset:53248
	s_waitcnt vmcnt(1)
	v_perm_b32 v186, 0, v82, s15
	v_perm_b32 v187, 0, v84, s15
	ds_write_b64 v206, v[186:187] offset:57344
	s_waitcnt vmcnt(0)
	v_perm_b32 v184, 0, v86, s15
	v_perm_b32 v185, 0, v88, s15
	ds_write_b64 v206, v[184:185] offset:61440
	s_add_u32 s56, s38, s73
	s_addc_u32 s57, s39, 0
	s_add_u32 s56, s56, 0x1100000
	s_addc_u32 s57, s57, 0
	global_load_dwordx3 v[58:60], v216, s[56:57]
	global_load_dwordx3 v[62:64], v218, s[56:57]
	global_load_dwordx3 v[66:68], v220, s[56:57]
	global_load_dwordx3 v[70:72], v222, s[56:57]
	global_load_dwordx3 v[74:76], v240, s[56:57]
	global_load_dwordx3 v[78:80], v242, s[56:57]
	global_load_dwordx3 v[82:84], v244, s[56:57]
	global_load_dwordx3 v[86:88], v61, s[56:57]
	v_add_u32_e32 v65, 0x10800, v5
	ds_read_b64 v[100:101], v65
	ds_read_b64 v[102:103], v65 offset:1056
	ds_read_b64 v[104:105], v65 offset:2112
	ds_read_b64 v[106:107], v65 offset:3168
	ds_read_b64 v[108:109], v65 offset:264
	ds_read_b64 v[110:111], v65 offset:1320
	ds_read_b64 v[112:113], v65 offset:2376
	ds_read_b64 v[114:115], v65 offset:3432
	ds_read_b64 v[116:117], v65 offset:528
	ds_read_b64 v[118:119], v65 offset:1584
	ds_read_b64 v[120:121], v65 offset:2640
	ds_read_b64 v[122:123], v65 offset:3696
	s_waitcnt lgkmcnt(8)
	ds_read_b64 v[124:125], v65 offset:792
	ds_read_b64 v[126:127], v65 offset:1848
	ds_read_b64 v[128:129], v65 offset:2904
	ds_read_b64 v[130:131], v65 offset:3960
	v_pk_add_f32 v[166:167], v[100:101], v[104:105]
	v_pk_add_f32 v[188:189], v[100:101], v[104:105] neg_lo:[0,1] neg_hi:[0,1]
	v_pk_add_f32 v[174:175], v[102:103], v[106:107]
	v_pk_add_f32 v[168:169], v[102:103], v[106:107] neg_lo:[0,1] neg_hi:[0,1]
	v_pk_add_f32 v[100:101], v[166:167], v[174:175]
	v_pk_add_f32 v[104:105], v[166:167], v[174:175] neg_lo:[0,1] neg_hi:[0,1]
	v_pk_add_f32 v[102:103], v[188:189], v[168:169] op_sel:[0,1] op_sel_hi:[1,0] neg_hi:[0,1]
	v_pk_add_f32 v[106:107], v[188:189], v[168:169] op_sel:[0,1] op_sel_hi:[1,0] neg_lo:[0,1]
	s_waitcnt lgkmcnt(9)
	v_pk_add_f32 v[178:179], v[108:109], v[112:113]
	v_pk_add_f32 v[176:177], v[108:109], v[112:113] neg_lo:[0,1] neg_hi:[0,1]
	s_waitcnt lgkmcnt(8)
	v_pk_add_f32 v[182:183], v[110:111], v[114:115]
	v_pk_add_f32 v[180:181], v[110:111], v[114:115] neg_lo:[0,1] neg_hi:[0,1]
	v_pk_add_f32 v[108:109], v[178:179], v[182:183]
	v_pk_add_f32 v[112:113], v[178:179], v[182:183] neg_lo:[0,1] neg_hi:[0,1]
	v_pk_add_f32 v[110:111], v[176:177], v[180:181] op_sel:[0,1] op_sel_hi:[1,0] neg_hi:[0,1]
	v_pk_add_f32 v[114:115], v[176:177], v[180:181] op_sel:[0,1] op_sel_hi:[1,0] neg_lo:[0,1]
	s_waitcnt lgkmcnt(5)
	v_pk_add_f32 v[186:187], v[116:117], v[120:121]
	v_pk_add_f32 v[184:185], v[116:117], v[120:121] neg_lo:[0,1] neg_hi:[0,1]
	s_waitcnt lgkmcnt(4)
	v_pk_add_f32 v[166:167], v[118:119], v[122:123]
	v_pk_add_f32 v[188:189], v[118:119], v[122:123] neg_lo:[0,1] neg_hi:[0,1]
	v_pk_add_f32 v[116:117], v[186:187], v[166:167]
	v_pk_add_f32 v[120:121], v[186:187], v[166:167] neg_lo:[0,1] neg_hi:[0,1]
	v_pk_add_f32 v[118:119], v[184:185], v[188:189] op_sel:[0,1] op_sel_hi:[1,0] neg_hi:[0,1]
	v_pk_add_f32 v[122:123], v[184:185], v[188:189] op_sel:[0,1] op_sel_hi:[1,0] neg_lo:[0,1]
	s_waitcnt lgkmcnt(1)
	v_pk_add_f32 v[174:175], v[124:125], v[128:129]
	v_pk_add_f32 v[168:169], v[124:125], v[128:129] neg_lo:[0,1] neg_hi:[0,1]
	s_waitcnt lgkmcnt(0)
; #define LAS __attribute__((address_space(3)))
; __device__ __forceinline__ f32x2 cmul(f32x2 a, f32x2 b) { return (f32x2){a.x * b.x - a.y * b.y, a.x * b.y + a.y * b.x}; }
; __device__ __forceinline__ void fft_fwd2(LAS f32x2* B, const LAS f32x2* TW2, int tid) {
;     asm volatile("" : "+v"(tid));
;     const int b = tid >> 5, n2 = tid & 31, base = 512 * b + n2; f32x2 x[16];
; #pragma unroll
;     for (int r = 0; r < 16; ++r) x[r] = B[fpad(base + 32 * r)];
;     dft16<false>(x);
;     B[fpad(base)] = x[0];
; #pragma unroll
;     for (int k = 1; k < 16; ++k) B[fpad(base + 32 * k)] = cmul(x[k], TW2[k * 32 + n2]);
; }
	v_pk_add_f32 v[178:179], v[126:127], v[130:131]
	v_pk_add_f32 v[176:177], v[126:127], v[130:131] neg_lo:[0,1] neg_hi:[0,1]
	v_pk_add_f32 v[124:125], v[174:175], v[178:179]
	v_pk_add_f32 v[128:129], v[174:175], v[178:179] neg_lo:[0,1] neg_hi:[0,1]
	v_pk_add_f32 v[126:127], v[168:169], v[176:177] op_sel:[0,1] op_sel_hi:[1,0] neg_hi:[0,1]
	v_pk_add_f32 v[130:131], v[168:169], v[176:177] op_sel:[0,1] op_sel_hi:[1,0] neg_lo:[0,1]
	v_pk_mul_f32 v[182:183], v[110:111], s[68:69] op_sel:[1,1] op_sel_hi:[0,1]
	v_pk_fma_f32 v[110:111], v[110:111], s[68:69], v[182:183] op_sel_hi:[1,0,1] neg_lo:[0,0,1]
	v_pk_mul_f32 v[180:181], v[118:119], s[84:85] op_sel:[1,1] op_sel_hi:[0,1]
	v_pk_fma_f32 v[118:119], v[118:119], s[84:85], v[180:181] op_sel_hi:[1,0,1] neg_lo:[0,0,1]
	v_pk_mul_f32 v[186:187], v[126:127], s[88:89] op_sel:[1,1] op_sel_hi:[0,1]
	v_pk_fma_f32 v[126:127], v[126:127], s[88:89], v[186:187] op_sel_hi:[1,0,1] neg_lo:[0,0,1]
	v_pk_mul_f32 v[184:185], v[112:113], s[84:85] op_sel:[1,1] op_sel_hi:[0,1]
	v_pk_fma_f32 v[112:113], v[112:113], s[84:85], v[184:185] op_sel_hi:[1,0,1] neg_lo:[0,0,1]
	v_pk_mul_f32 v[166:167], v[128:129], s[90:91] op_sel:[1,1] op_sel_hi:[0,1]
	v_pk_fma_f32 v[128:129], v[128:129], s[90:91], v[166:167] op_sel_hi:[1,0,1] neg_lo:[0,0,1]
	v_pk_mul_f32 v[188:189], v[114:115], s[88:89] op_sel:[1,1] op_sel_hi:[0,1]
	v_pk_fma_f32 v[114:115], v[114:115], s[88:89], v[188:189] op_sel_hi:[1,0,1] neg_lo:[0,0,1]
	v_pk_mul_f32 v[174:175], v[122:123], s[90:91] op_sel:[1,1] op_sel_hi:[0,1]
	v_pk_fma_f32 v[122:123], v[122:123], s[90:91], v[174:175] op_sel_hi:[1,0,1] neg_lo:[0,0,1]
	v_pk_mul_f32 v[168:169], v[130:131], s[98:99] op_sel:[1,1] op_sel_hi:[0,1]
	v_pk_fma_f32 v[130:131], v[130:131], s[98:99], v[168:169] op_sel_hi:[1,0,1] neg_lo:[0,0,1]
	v_pk_add_f32 v[178:179], v[100:101], v[116:117]
	v_pk_add_f32 v[176:177], v[100:101], v[116:117] neg_lo:[0,1] neg_hi:[0,1]
	v_pk_add_f32 v[182:183], v[108:109], v[124:125]
	v_pk_add_f32 v[180:181], v[108:109], v[124:125] neg_lo:[0,1] neg_hi:[0,1]
	v_pk_add_f32 v[100:101], v[178:179], v[182:183]
	v_pk_add_f32 v[116:117], v[178:179], v[182:183] neg_lo:[0,1] neg_hi:[0,1]
	v_pk_add_f32 v[108:109], v[176:177], v[180:181] op_sel:[0,1] op_sel_hi:[1,0] neg_hi:[0,1]
	v_pk_add_f32 v[124:125], v[176:177], v[180:181] op_sel:[0,1] op_sel_hi:[1,0] neg_lo:[0,1]
	v_pk_add_f32 v[186:187], v[102:103], v[118:119]
	v_pk_add_f32 v[184:185], v[102:103], v[118:119] neg_lo:[0,1] neg_hi:[0,1]
	v_pk_add_f32 v[166:167], v[110:111], v[126:127]
	v_pk_add_f32 v[188:189], v[110:111], v[126:127] neg_lo:[0,1] neg_hi:[0,1]
	v_pk_add_f32 v[102:103], v[186:187], v[166:167]
	v_pk_add_f32 v[118:119], v[186:187], v[166:167] neg_lo:[0,1] neg_hi:[0,1]
	v_pk_add_f32 v[110:111], v[184:185], v[188:189] op_sel:[0,1] op_sel_hi:[1,0] neg_hi:[0,1]
	v_pk_add_f32 v[126:127], v[184:185], v[188:189] op_sel:[0,1] op_sel_hi:[1,0] neg_lo:[0,1]
	v_pk_add_f32 v[174:175], v[104:105], v[120:121] op_sel:[0,1] op_sel_hi:[1,0] neg_hi:[0,1]
	v_pk_add_f32 v[168:169], v[104:105], v[120:121] op_sel:[0,1] op_sel_hi:[1,0] neg_lo:[0,1]
	v_pk_add_f32 v[178:179], v[112:113], v[128:129]
	v_pk_add_f32 v[176:177], v[112:113], v[128:129] neg_lo:[0,1] neg_hi:[0,1]
	v_pk_add_f32 v[104:105], v[174:175], v[178:179]
	v_pk_add_f32 v[120:121], v[174:175], v[178:179] neg_lo:[0,1] neg_hi:[0,1]
	v_pk_add_f32 v[112:113], v[168:169], v[176:177] op_sel:[0,1] op_sel_hi:[1,0] neg_hi:[0,1]
	v_pk_add_f32 v[128:129], v[168:169], v[176:177] op_sel:[0,1] op_sel_hi:[1,0] neg_lo:[0,1]
	v_pk_add_f32 v[182:183], v[106:107], v[122:123]
	v_pk_add_f32 v[180:181], v[106:107], v[122:123] neg_lo:[0,1] neg_hi:[0,1]
	v_pk_add_f32 v[186:187], v[114:115], v[130:131]
	v_pk_add_f32 v[184:185], v[114:115], v[130:131] neg_lo:[0,1] neg_hi:[0,1]
	v_pk_add_f32 v[106:107], v[182:183], v[186:187]
	v_pk_add_f32 v[122:123], v[182:183], v[186:187] neg_lo:[0,1] neg_hi:[0,1]
	v_pk_add_f32 v[114:115], v[180:181], v[184:185] op_sel:[0,1] op_sel_hi:[1,0] neg_hi:[0,1]
	v_pk_add_f32 v[130:131], v[180:181], v[184:185] op_sel:[0,1] op_sel_hi:[1,0] neg_lo:[0,1]
	ds_write_b64 v65, v[100:101]
	ds_read_b64 v[166:167], v56 offset:256
	ds_read_b64 v[188:189], v56 offset:512
	ds_read_b64 v[174:175], v56 offset:768
	ds_read_b64 v[168:169], v56 offset:1024
	s_waitcnt lgkmcnt(3)
	v_pk_mul_f32 v[178:179], v[102:103], v[166:167] op_sel:[1,1] op_sel_hi:[0,1]
	v_pk_fma_f32 v[102:103], v[102:103], v[166:167], v[178:179] op_sel_hi:[1,0,1] neg_lo:[0,0,1]
	ds_write_b64 v65, v[102:103] offset:264
	s_waitcnt lgkmcnt(3)
	v_pk_mul_f32 v[176:177], v[104:105], v[188:189] op_sel:[1,1] op_sel_hi:[0,1]
	v_pk_fma_f32 v[104:105], v[104:105], v[188:189], v[176:177] op_sel_hi:[1,0,1] neg_lo:[0,0,1]
	ds_write_b64 v65, v[104:105] offset:528
	s_waitcnt lgkmcnt(3)
	v_pk_mul_f32 v[182:183], v[106:107], v[174:175] op_sel:[1,1] op_sel_hi:[0,1]
	v_pk_fma_f32 v[106:107], v[106:107], v[174:175], v[182:183] op_sel_hi:[1,0,1] neg_lo:[0,0,1]
	ds_write_b64 v65, v[106:107] offset:792
	s_waitcnt lgkmcnt(3)
	v_pk_mul_f32 v[180:181], v[108:109], v[168:169] op_sel:[1,1] op_sel_hi:[0,1]
	v_pk_fma_f32 v[108:109], v[108:109], v[168:169], v[180:181] op_sel_hi:[1,0,1] neg_lo:[0,0,1]
	ds_write_b64 v65, v[108:109] offset:1056
	ds_read_b64 v[186:187], v56 offset:1280
	ds_read_b64 v[184:185], v56 offset:1536
	ds_read_b64 v[178:179], v56 offset:1792
	ds_read_b64 v[176:177], v56 offset:2048
	s_waitcnt lgkmcnt(3)
	v_pk_mul_f32 v[182:183], v[110:111], v[186:187] op_sel:[1,1] op_sel_hi:[0,1]
	v_pk_fma_f32 v[110:111], v[110:111], v[186:187], v[182:183] op_sel_hi:[1,0,1] neg_lo:[0,0,1]
	ds_write_b64 v65, v[110:111] offset:1320
	s_waitcnt lgkmcnt(3)
; __device__ __forceinline__ f32x2 cmul(f32x2 a, f32x2 b) { return (f32x2){a.x * b.x - a.y * b.y, a.x * b.y + a.y * b.x}; }
; #define WG_SYNC() do { asm volatile("s_waitcnt lgkmcnt(0)" ::: "memory"); __builtin_amdgcn_s_barrier(); asm volatile("" ::: "memory"); } while (0)
; __device__ __forceinline__ void fft_fwd2(LAS f32x2* B, const LAS f32x2* TW2, int tid) {
;     ...
;     B[fpad(base)] = x[0];
; #pragma unroll
;     for (int k = 1; k < 16; ++k) B[fpad(base + 32 * k)] = cmul(x[k], TW2[k * 32 + n2]);
; }
; __device__ __forceinline__ void hyena_fft(LAS unsigned char* lds, int layer, int G, const int wave_s) {
;     ...
;             WG_SYNC();
;             float uz[8][2], ux[8][2];
;             hy_sconv(pl0, cw[2 * HY + c], cw[3 * HY + 2 * HY + c], cw[6 * HY + 2 * HY + c], cb[2 * HY + c], n2, uz);
;             __builtin_amdgcn_sched_barrier(0); hy_sconv(pl1, cw[c], cw[3 * HY + c], cw[6 * HY + c], cb[c], n2, ux); __builtin_amdgcn_sched_barrier(0);
	v_pk_mul_f32 v[180:181], v[112:113], v[184:185] op_sel:[1,1] op_sel_hi:[0,1]
	v_pk_fma_f32 v[112:113], v[112:113], v[184:185], v[180:181] op_sel_hi:[1,0,1] neg_lo:[0,0,1]
	ds_write_b64 v65, v[112:113] offset:1584
	s_waitcnt lgkmcnt(3)
	v_pk_mul_f32 v[166:167], v[114:115], v[178:179] op_sel:[1,1] op_sel_hi:[0,1]
	v_pk_fma_f32 v[114:115], v[114:115], v[178:179], v[166:167] op_sel_hi:[1,0,1] neg_lo:[0,0,1]
	ds_write_b64 v65, v[114:115] offset:1848
	s_waitcnt lgkmcnt(3)
	v_pk_mul_f32 v[188:189], v[116:117], v[176:177] op_sel:[1,1] op_sel_hi:[0,1]
	v_pk_fma_f32 v[116:117], v[116:117], v[176:177], v[188:189] op_sel_hi:[1,0,1] neg_lo:[0,0,1]
	ds_write_b64 v65, v[116:117] offset:2112
	ds_read_b64 v[174:175], v56 offset:2304
	ds_read_b64 v[168:169], v56 offset:2560
	ds_read_b64 v[182:183], v56 offset:2816
	ds_read_b64 v[180:181], v56 offset:3072
	s_waitcnt lgkmcnt(3)
	v_pk_mul_f32 v[166:167], v[118:119], v[174:175] op_sel:[1,1] op_sel_hi:[0,1]
	v_pk_fma_f32 v[118:119], v[118:119], v[174:175], v[166:167] op_sel_hi:[1,0,1] neg_lo:[0,0,1]
	ds_write_b64 v65, v[118:119] offset:2376
	s_waitcnt lgkmcnt(3)
	v_pk_mul_f32 v[188:189], v[120:121], v[168:169] op_sel:[1,1] op_sel_hi:[0,1]
	v_pk_fma_f32 v[120:121], v[120:121], v[168:169], v[188:189] op_sel_hi:[1,0,1] neg_lo:[0,0,1]
	ds_write_b64 v65, v[120:121] offset:2640
	s_waitcnt lgkmcnt(3)
	v_pk_mul_f32 v[186:187], v[122:123], v[182:183] op_sel:[1,1] op_sel_hi:[0,1]
	v_pk_fma_f32 v[122:123], v[122:123], v[182:183], v[186:187] op_sel_hi:[1,0,1] neg_lo:[0,0,1]
	ds_write_b64 v65, v[122:123] offset:2904
	s_waitcnt lgkmcnt(3)
	v_pk_mul_f32 v[184:185], v[124:125], v[180:181] op_sel:[1,1] op_sel_hi:[0,1]
	v_pk_fma_f32 v[124:125], v[124:125], v[180:181], v[184:185] op_sel_hi:[1,0,1] neg_lo:[0,0,1]
	ds_write_b64 v65, v[124:125] offset:3168
	ds_read_b64 v[178:179], v56 offset:3328
	ds_read_b64 v[176:177], v56 offset:3584
	ds_read_b64 v[166:167], v56 offset:3840
	s_waitcnt lgkmcnt(2)
	v_pk_mul_f32 v[188:189], v[126:127], v[178:179] op_sel:[1,1] op_sel_hi:[0,1]
	v_pk_fma_f32 v[126:127], v[126:127], v[178:179], v[188:189] op_sel_hi:[1,0,1] neg_lo:[0,0,1]
	ds_write_b64 v65, v[126:127] offset:3432
	s_waitcnt lgkmcnt(2)
	v_pk_mul_f32 v[186:187], v[128:129], v[176:177] op_sel:[1,1] op_sel_hi:[0,1]
	v_pk_fma_f32 v[128:129], v[128:129], v[176:177], v[186:187] op_sel_hi:[1,0,1] neg_lo:[0,0,1]
	ds_write_b64 v65, v[128:129] offset:3696
	s_waitcnt lgkmcnt(2)
	v_pk_mul_f32 v[184:185], v[130:131], v[166:167] op_sel:[1,1] op_sel_hi:[0,1]
	v_pk_fma_f32 v[130:131], v[130:131], v[166:167], v[184:185] op_sel_hi:[1,0,1] neg_lo:[0,0,1]
	ds_write_b64 v65, v[130:131] offset:3960
	s_waitcnt lgkmcnt(0)
	s_barrier
	s_cbranch_vccz .Lhfft_st3
	s_sleep 2
.Lhfft_st3:
	v_mov_b32_e32 v174, s17
	v_mov_b32_e32 v175, s23
	v_mov_b32_e32 v168, s25
	v_mov_b32_e32 v169, s26
	ds_read_b32 v182, v208 offset:32768
	ds_read_b32 v180, v210 offset:32768
	ds_read_b32 v188, v208 offset:32772
	ds_read_b32 v183, v208 offset:49152
	ds_read_b32 v181, v210 offset:49152
	ds_read_b32 v189, v208 offset:49156
	ds_read_b32 v186, v208 offset:34816
	ds_read_b32 v184, v208 offset:34812
	ds_read_b32 v178, v208 offset:34820
	ds_read_b32 v187, v208 offset:51200
	ds_read_b32 v185, v208 offset:51196
	ds_read_b32 v179, v208 offset:51204
	s_waitcnt lgkmcnt(10)
	v_cndmask_b32_e64 v180, v180, 0, s[10:11]
	s_waitcnt lgkmcnt(7)
	v_cndmask_b32_e64 v181, v181, 0, s[10:11]
	v_pk_fma_f32 v[148:149], v[174:175], v[182:183], v[168:169] op_sel:[1,0,1]
	v_pk_fma_f32 v[148:149], v[174:175], v[180:181], v[148:149] op_sel_hi:[0,1,1]
	s_waitcnt lgkmcnt(6)
	v_pk_fma_f32 v[148:149], v[168:169], v[188:189], v[148:149] op_sel_hi:[0,1,1]
	s_waitcnt lgkmcnt(2)
	v_pk_fma_f32 v[150:151], v[174:175], v[186:187], v[168:169] op_sel:[1,0,1]
	s_waitcnt lgkmcnt(1)
	v_pk_fma_f32 v[150:151], v[174:175], v[184:185], v[150:151] op_sel_hi:[0,1,1]
	s_waitcnt lgkmcnt(0)
	v_pk_fma_f32 v[150:151], v[168:169], v[178:179], v[150:151] op_sel_hi:[0,1,1]
	ds_read_b32 v176, v208 offset:36864
	ds_read_b32 v166, v208 offset:36860
	ds_read_b32 v182, v208 offset:36868
	ds_read_b32 v177, v208 offset:53248
	ds_read_b32 v167, v208 offset:53244
	ds_read_b32 v183, v208 offset:53252
	ds_read_b32 v180, v208 offset:38912
	ds_read_b32 v188, v208 offset:38908
	ds_read_b32 v186, v208 offset:38916
	ds_read_b32 v181, v208 offset:55296
	ds_read_b32 v189, v208 offset:55292
	ds_read_b32 v187, v208 offset:55300
	s_waitcnt lgkmcnt(8)
	v_pk_fma_f32 v[152:153], v[174:175], v[176:177], v[168:169] op_sel:[1,0,1]
	s_waitcnt lgkmcnt(7)
	v_pk_fma_f32 v[152:153], v[174:175], v[166:167], v[152:153] op_sel_hi:[0,1,1]
	s_waitcnt lgkmcnt(6)
	v_pk_fma_f32 v[152:153], v[168:169], v[182:183], v[152:153] op_sel_hi:[0,1,1]
	s_waitcnt lgkmcnt(2)
	v_pk_fma_f32 v[154:155], v[174:175], v[180:181], v[168:169] op_sel:[1,0,1]
	s_waitcnt lgkmcnt(1)
	v_pk_fma_f32 v[154:155], v[174:175], v[188:189], v[154:155] op_sel_hi:[0,1,1]
	s_waitcnt lgkmcnt(0)
	v_pk_fma_f32 v[154:155], v[168:169], v[186:187], v[154:155] op_sel_hi:[0,1,1]
	ds_read_b32 v184, v208 offset:40960
	ds_read_b32 v178, v208 offset:40956
	ds_read_b32 v176, v208 offset:40964
	ds_read_b32 v185, v208 offset:57344
	ds_read_b32 v179, v208 offset:57340
	ds_read_b32 v177, v208 offset:57348
	ds_read_b32 v166, v208 offset:43008
	ds_read_b32 v182, v208 offset:43004
	ds_read_b32 v180, v208 offset:43012
	ds_read_b32 v167, v208 offset:59392
	ds_read_b32 v183, v208 offset:59388
	ds_read_b32 v181, v208 offset:59396
	s_waitcnt lgkmcnt(8)
	v_pk_fma_f32 v[158:159], v[174:175], v[184:185], v[168:169] op_sel:[1,0,1]
	s_waitcnt lgkmcnt(7)
	v_pk_fma_f32 v[158:159], v[174:175], v[178:179], v[158:159] op_sel_hi:[0,1,1]
	s_waitcnt lgkmcnt(6)
; #define LAS __attribute__((address_space(3)))
; __device__ __forceinline__ f32x2 cmul(f32x2 a, f32x2 b) { return (f32x2){a.x * b.x - a.y * b.y, a.x * b.y + a.y * b.x}; }
; template <int MODE> __device__ __forceinline__ void fft_pair32(LAS f32x2* B, const LAS f32x2* F, int wave, int lane) {
;     ...
;     const int hi = lane >> 5, blk = 32 * wave + (lane & 31); const float sg = hi ? -1.f : 1.f;
;     LAS f32x2* p = B + 33 * blk; f32x2 v[16];
; #pragma unroll
;     for (int j = 0; j < 16; ++j) { const f32x2 d = p[j] + p[j + 16] * sg;
;         const f32x2 w = {hi ? CS[j] : 1.f, hi ? -SN[j] : 0.f}; v[j] = j == 0 ? d : cmul(d, w); }
;     dft16<false>(v);
; __device__ __forceinline__ void hy_sconv(const LAS float* plane, float w0, float w1, float w2, float cb, int n2, float (&u)[8][2]) {
;     asm volatile("" : "+v"(n2));
; #pragma unroll
;     for (int r = 0; r < 8; ++r)
; #pragma unroll
;         for (int b = 0; b < 2; ++b) { const int t = n2 + 512 * r, row = b * SEQ + t;
;             float a = cb + w1 * plane[row];
;             if (t > 0) a += w0 * plane[row - 1];
;             if (t < SEQ - 1) a += w2 * plane[row + 1];
;             u[r][b] = a; }
; }
	v_pk_fma_f32 v[158:159], v[168:169], v[176:177], v[158:159] op_sel_hi:[0,1,1]
	s_waitcnt lgkmcnt(2)
	v_pk_fma_f32 v[160:161], v[174:175], v[166:167], v[168:169] op_sel:[1,0,1]
	s_waitcnt lgkmcnt(1)
	v_pk_fma_f32 v[160:161], v[174:175], v[182:183], v[160:161] op_sel_hi:[0,1,1]
	s_waitcnt lgkmcnt(0)
	v_pk_fma_f32 v[160:161], v[168:169], v[180:181], v[160:161] op_sel_hi:[0,1,1]
	ds_read_b32 v188, v208 offset:45056
	ds_read_b32 v186, v208 offset:45052
	ds_read_b32 v184, v208 offset:45060
	ds_read_b32 v189, v208 offset:61440
	ds_read_b32 v187, v208 offset:61436
	ds_read_b32 v185, v208 offset:61444
	ds_read_b32 v178, v208 offset:47104
	ds_read_b32 v176, v208 offset:47100
	ds_read_b32 v166, v208 offset:47108
	ds_read_b32 v179, v208 offset:63488
	ds_read_b32 v177, v208 offset:63484
	ds_read_b32 v167, v208 offset:63492
	s_waitcnt lgkmcnt(8)
	v_pk_fma_f32 v[162:163], v[174:175], v[188:189], v[168:169] op_sel:[1,0,1]
	s_waitcnt lgkmcnt(7)
	v_pk_fma_f32 v[162:163], v[174:175], v[186:187], v[162:163] op_sel_hi:[0,1,1]
	s_waitcnt lgkmcnt(6)
	v_pk_fma_f32 v[162:163], v[168:169], v[184:185], v[162:163] op_sel_hi:[0,1,1]
	s_waitcnt lgkmcnt(3)
	v_cndmask_b32_e64 v166, v166, 0, s[28:29]
	s_waitcnt lgkmcnt(0)
	v_cndmask_b32_e64 v167, v167, 0, s[28:29]
	v_pk_fma_f32 v[164:165], v[174:175], v[178:179], v[168:169] op_sel:[1,0,1]
	v_pk_fma_f32 v[164:165], v[174:175], v[176:177], v[164:165] op_sel_hi:[0,1,1]
	v_pk_fma_f32 v[164:165], v[168:169], v[166:167], v[164:165] op_sel_hi:[0,1,1]
	s_load_dword s17, s[60:61], 0x1000
	s_load_dword s23, s[60:61], 0x4000
	s_load_dword s25, s[60:61], 0x7000
	s_load_dword s26, s[62:63], 0x1000
	v_add_u32_e32 v65, 0x10800, v156
	v_add_u32_e32 v69, 0x10800, v196
	ds_read_b64 v[100:101], v65
	ds_read_b64 v[182:183], v65 offset:128
	ds_read_b64 v[102:103], v65 offset:8
	ds_read_b64 v[180:181], v65 offset:136
	ds_read_b64 v[104:105], v65 offset:16
	ds_read_b64 v[188:189], v65 offset:144
	ds_read_b64 v[106:107], v65 offset:24
	ds_read_b64 v[186:187], v65 offset:152
	s_waitcnt lgkmcnt(0)
	v_pk_fma_f32 v[100:101], v[182:183], v[190:191], v[100:101] op_sel_hi:[1,0,1]
	v_pk_fma_f32 v[102:103], v[180:181], v[190:191], v[102:103] op_sel_hi:[1,0,1]
	v_pk_mul_f32 v[184:185], v[102:103], v[36:37] op_sel:[1,1] op_sel_hi:[0,1]
	v_pk_fma_f32 v[102:103], v[102:103], v[36:37], v[184:185] op_sel_hi:[1,0,1] neg_lo:[0,0,1]
	v_pk_fma_f32 v[104:105], v[188:189], v[190:191], v[104:105] op_sel_hi:[1,0,1]
	v_pk_mul_f32 v[178:179], v[104:105], v[38:39] op_sel:[1,1] op_sel_hi:[0,1]
	v_pk_fma_f32 v[104:105], v[104:105], v[38:39], v[178:179] op_sel_hi:[1,0,1] neg_lo:[0,0,1]
	v_pk_fma_f32 v[106:107], v[186:187], v[190:191], v[106:107] op_sel_hi:[1,0,1]
	v_pk_mul_f32 v[176:177], v[106:107], v[40:41] op_sel:[1,1] op_sel_hi:[0,1]
	v_pk_fma_f32 v[106:107], v[106:107], v[40:41], v[176:177] op_sel_hi:[1,0,1] neg_lo:[0,0,1]
	ds_read_b64 v[108:109], v65 offset:32
	ds_read_b64 v[166:167], v65 offset:160
	ds_read_b64 v[110:111], v65 offset:40
	ds_read_b64 v[174:175], v65 offset:168
	ds_read_b64 v[112:113], v65 offset:48
	ds_read_b64 v[168:169], v65 offset:176
	ds_read_b64 v[114:115], v65 offset:56
	ds_read_b64 v[184:185], v65 offset:184
	s_waitcnt lgkmcnt(6)
	v_pk_fma_f32 v[108:109], v[166:167], v[190:191], v[108:109] op_sel_hi:[1,0,1]
	v_pk_mul_f32 v[178:179], v[108:109], v[42:43] op_sel:[1,1] op_sel_hi:[0,1]
	v_pk_fma_f32 v[108:109], v[108:109], v[42:43], v[178:179] op_sel_hi:[1,0,1] neg_lo:[0,0,1]
	s_waitcnt lgkmcnt(4)
	v_pk_fma_f32 v[110:111], v[174:175], v[190:191], v[110:111] op_sel_hi:[1,0,1]
	v_pk_mul_f32 v[176:177], v[110:111], v[44:45] op_sel:[1,1] op_sel_hi:[0,1]
	v_pk_fma_f32 v[110:111], v[110:111], v[44:45], v[176:177] op_sel_hi:[1,0,1] neg_lo:[0,0,1]
	s_waitcnt lgkmcnt(2)
	v_pk_fma_f32 v[112:113], v[168:169], v[190:191], v[112:113] op_sel_hi:[1,0,1]
	v_pk_mul_f32 v[182:183], v[112:113], v[46:47] op_sel:[1,1] op_sel_hi:[0,1]
	v_pk_fma_f32 v[112:113], v[112:113], v[46:47], v[182:183] op_sel_hi:[1,0,1] neg_lo:[0,0,1]
	s_waitcnt lgkmcnt(0)
	v_pk_fma_f32 v[114:115], v[184:185], v[190:191], v[114:115] op_sel_hi:[1,0,1]
	v_pk_mul_f32 v[180:181], v[114:115], v[48:49] op_sel:[1,1] op_sel_hi:[0,1]
	v_pk_fma_f32 v[114:115], v[114:115], v[48:49], v[180:181] op_sel_hi:[1,0,1] neg_lo:[0,0,1]
	ds_read_b64 v[116:117], v65 offset:64
	ds_read_b64 v[188:189], v65 offset:192
	ds_read_b64 v[118:119], v65 offset:72
	ds_read_b64 v[186:187], v65 offset:200
	ds_read_b64 v[120:121], v65 offset:80
	ds_read_b64 v[178:179], v65 offset:208
	ds_read_b64 v[122:123], v65 offset:88
	ds_read_b64 v[176:177], v65 offset:216
	s_waitcnt lgkmcnt(6)
	v_pk_fma_f32 v[116:117], v[188:189], v[190:191], v[116:117] op_sel_hi:[1,0,1]
	v_pk_mul_f32 v[182:183], v[116:117], v[50:51] op_sel:[1,1] op_sel_hi:[0,1]
	v_pk_fma_f32 v[116:117], v[116:117], v[50:51], v[182:183] op_sel_hi:[1,0,1] neg_lo:[0,0,1]
	s_waitcnt lgkmcnt(4)
	v_pk_fma_f32 v[118:119], v[186:187], v[190:191], v[118:119] op_sel_hi:[1,0,1]
	v_pk_mul_f32 v[180:181], v[118:119], v[52:53] op_sel:[1,1] op_sel_hi:[0,1]
	v_pk_fma_f32 v[118:119], v[118:119], v[52:53], v[180:181] op_sel_hi:[1,0,1] neg_lo:[0,0,1]
	s_waitcnt lgkmcnt(2)
	v_pk_fma_f32 v[120:121], v[178:179], v[190:191], v[120:121] op_sel_hi:[1,0,1]
	v_pk_mul_f32 v[166:167], v[120:121], v[54:55] op_sel:[1,1] op_sel_hi:[0,1]
	v_pk_fma_f32 v[120:121], v[120:121], v[54:55], v[166:167] op_sel_hi:[1,0,1] neg_lo:[0,0,1]
	s_waitcnt lgkmcnt(0)
; __device__ __forceinline__ f32x2 cmul(f32x2 a, f32x2 b) { return (f32x2){a.x * b.x - a.y * b.y, a.x * b.y + a.y * b.x}; }
; template <bool INV> __device__ __forceinline__ f32x2 cmul_tw(f32x2 a, f32x2 w) { return INV ? cmulc(a, w) : cmul(a, w); }
; template <bool INV> __device__ __forceinline__ void dft16(f32x2 (&x)[16]) {
;     constexpr float C1 = 0.92387953251128674f, S1 = 0.38268343236508977f, C2 = 0.70710678118654752f;
; #pragma unroll
;     for (int b = 0; b < 4; ++b) dft4<INV>(x[b], x[4 + b], x[8 + b], x[12 + b]);
;     const f32x2 w1 = {C1, -S1}, w2 = {C2, -C2}, w3 = {S1, -C1}, w4 = {0.f, -1.f}, w6 = {-C2, -C2}, w9 = {-C1, S1};
;     x[4 * 1 + 1] = cmul_tw<INV>(x[5], w1); x[4 * 1 + 2] = cmul_tw<INV>(x[6], w2); x[4 * 1 + 3] = cmul_tw<INV>(x[7], w3);
;     x[4 * 2 + 1] = cmul_tw<INV>(x[9], w2); x[4 * 2 + 2] = cmul_tw<INV>(x[10], w4); x[4 * 2 + 3] = cmul_tw<INV>(x[11], w6);
;     x[4 * 3 + 1] = cmul_tw<INV>(x[13], w3); x[4 * 3 + 2] = cmul_tw<INV>(x[14], w6); x[4 * 3 + 3] = cmul_tw<INV>(x[15], w9);
; #pragma unroll
;     for (int c = 0; c < 4; ++c) dft4<INV>(x[4 * c], x[4 * c + 1], x[4 * c + 2], x[4 * c + 3]);
; template <int MODE> __device__ __forceinline__ void fft_pair32(LAS f32x2* B, const LAS f32x2* F, int wave, int lane) {
;     ...
;     for (int j = 0; j < 16; ++j) { const f32x2 d = p[j] + p[j + 16] * sg;
;         const f32x2 w = {hi ? CS[j] : 1.f, hi ? -SN[j] : 0.f}; v[j] = j == 0 ? d : cmul(d, w); }
;     dft16<false>(v);
	v_pk_fma_f32 v[122:123], v[176:177], v[190:191], v[122:123] op_sel_hi:[1,0,1]
	v_pk_mul_f32 v[174:175], v[122:123], v[90:91] op_sel:[1,1] op_sel_hi:[0,1]
	v_pk_fma_f32 v[122:123], v[122:123], v[90:91], v[174:175] op_sel_hi:[1,0,1] neg_lo:[0,0,1]
	ds_read_b64 v[124:125], v65 offset:96
	ds_read_b64 v[168:169], v65 offset:224
	ds_read_b64 v[126:127], v65 offset:104
	ds_read_b64 v[184:185], v65 offset:232
	ds_read_b64 v[128:129], v65 offset:112
	ds_read_b64 v[182:183], v65 offset:240
	ds_read_b64 v[130:131], v65 offset:120
	ds_read_b64 v[180:181], v65 offset:248
	s_waitcnt lgkmcnt(6)
	v_pk_fma_f32 v[124:125], v[168:169], v[190:191], v[124:125] op_sel_hi:[1,0,1]
	v_pk_mul_f32 v[166:167], v[124:125], v[92:93] op_sel:[1,1] op_sel_hi:[0,1]
	v_pk_fma_f32 v[124:125], v[124:125], v[92:93], v[166:167] op_sel_hi:[1,0,1] neg_lo:[0,0,1]
	s_waitcnt lgkmcnt(4)
	v_pk_fma_f32 v[126:127], v[184:185], v[190:191], v[126:127] op_sel_hi:[1,0,1]
	v_pk_mul_f32 v[174:175], v[126:127], v[94:95] op_sel:[1,1] op_sel_hi:[0,1]
	v_pk_fma_f32 v[126:127], v[126:127], v[94:95], v[174:175] op_sel_hi:[1,0,1] neg_lo:[0,0,1]
	s_waitcnt lgkmcnt(2)
	v_pk_fma_f32 v[128:129], v[182:183], v[190:191], v[128:129] op_sel_hi:[1,0,1]
	v_pk_mul_f32 v[188:189], v[128:129], v[96:97] op_sel:[1,1] op_sel_hi:[0,1]
	v_pk_fma_f32 v[128:129], v[128:129], v[96:97], v[188:189] op_sel_hi:[1,0,1] neg_lo:[0,0,1]
	s_waitcnt lgkmcnt(0)
	v_pk_fma_f32 v[130:131], v[180:181], v[190:191], v[130:131] op_sel_hi:[1,0,1]
	v_pk_mul_f32 v[186:187], v[130:131], v[98:99] op_sel:[1,1] op_sel_hi:[0,1]
	v_pk_fma_f32 v[130:131], v[130:131], v[98:99], v[186:187] op_sel_hi:[1,0,1] neg_lo:[0,0,1]
	v_pk_add_f32 v[178:179], v[100:101], v[116:117]
	v_pk_add_f32 v[176:177], v[100:101], v[116:117] neg_lo:[0,1] neg_hi:[0,1]
	v_pk_add_f32 v[166:167], v[108:109], v[124:125]
	v_pk_add_f32 v[174:175], v[108:109], v[124:125] neg_lo:[0,1] neg_hi:[0,1]
	v_pk_add_f32 v[100:101], v[178:179], v[166:167]
	v_pk_add_f32 v[116:117], v[178:179], v[166:167] neg_lo:[0,1] neg_hi:[0,1]
	v_pk_add_f32 v[108:109], v[176:177], v[174:175] op_sel:[0,1] op_sel_hi:[1,0] neg_hi:[0,1]
	v_pk_add_f32 v[124:125], v[176:177], v[174:175] op_sel:[0,1] op_sel_hi:[1,0] neg_lo:[0,1]
	v_pk_add_f32 v[188:189], v[102:103], v[118:119]
	v_pk_add_f32 v[186:187], v[102:103], v[118:119] neg_lo:[0,1] neg_hi:[0,1]
	v_pk_add_f32 v[168:169], v[110:111], v[126:127]
	v_pk_add_f32 v[184:185], v[110:111], v[126:127] neg_lo:[0,1] neg_hi:[0,1]
	v_pk_add_f32 v[102:103], v[188:189], v[168:169]
	v_pk_add_f32 v[118:119], v[188:189], v[168:169] neg_lo:[0,1] neg_hi:[0,1]
	v_pk_add_f32 v[110:111], v[186:187], v[184:185] op_sel:[0,1] op_sel_hi:[1,0] neg_hi:[0,1]
	v_pk_add_f32 v[126:127], v[186:187], v[184:185] op_sel:[0,1] op_sel_hi:[1,0] neg_lo:[0,1]
	v_pk_add_f32 v[182:183], v[104:105], v[120:121]
	v_pk_add_f32 v[180:181], v[104:105], v[120:121] neg_lo:[0,1] neg_hi:[0,1]
	v_pk_add_f32 v[178:179], v[112:113], v[128:129]
	v_pk_add_f32 v[176:177], v[112:113], v[128:129] neg_lo:[0,1] neg_hi:[0,1]
	v_pk_add_f32 v[104:105], v[182:183], v[178:179]
	v_pk_add_f32 v[120:121], v[182:183], v[178:179] neg_lo:[0,1] neg_hi:[0,1]
	v_pk_add_f32 v[112:113], v[180:181], v[176:177] op_sel:[0,1] op_sel_hi:[1,0] neg_hi:[0,1]
	v_pk_add_f32 v[128:129], v[180:181], v[176:177] op_sel:[0,1] op_sel_hi:[1,0] neg_lo:[0,1]
	v_pk_add_f32 v[166:167], v[106:107], v[122:123]
	v_pk_add_f32 v[174:175], v[106:107], v[122:123] neg_lo:[0,1] neg_hi:[0,1]
	v_pk_add_f32 v[188:189], v[114:115], v[130:131]
	v_pk_add_f32 v[186:187], v[114:115], v[130:131] neg_lo:[0,1] neg_hi:[0,1]
	v_pk_add_f32 v[106:107], v[166:167], v[188:189]
	v_pk_add_f32 v[122:123], v[166:167], v[188:189] neg_lo:[0,1] neg_hi:[0,1]
	v_pk_add_f32 v[114:115], v[174:175], v[186:187] op_sel:[0,1] op_sel_hi:[1,0] neg_hi:[0,1]
	v_pk_add_f32 v[130:131], v[174:175], v[186:187] op_sel:[0,1] op_sel_hi:[1,0] neg_lo:[0,1]
	v_pk_mul_f32 v[168:169], v[110:111], s[68:69] op_sel:[1,1] op_sel_hi:[0,1]
	v_pk_fma_f32 v[110:111], v[110:111], s[68:69], v[168:169] op_sel_hi:[1,0,1] neg_lo:[0,0,1]
	v_pk_mul_f32 v[184:185], v[112:113], s[84:85] op_sel:[1,1] op_sel_hi:[0,1]
	v_pk_fma_f32 v[112:113], v[112:113], s[84:85], v[184:185] op_sel_hi:[1,0,1] neg_lo:[0,0,1]
	v_pk_mul_f32 v[182:183], v[114:115], s[88:89] op_sel:[1,1] op_sel_hi:[0,1]
	v_pk_fma_f32 v[114:115], v[114:115], s[88:89], v[182:183] op_sel_hi:[1,0,1] neg_lo:[0,0,1]
	v_pk_mul_f32 v[180:181], v[118:119], s[84:85] op_sel:[1,1] op_sel_hi:[0,1]
	v_pk_fma_f32 v[118:119], v[118:119], s[84:85], v[180:181] op_sel_hi:[1,0,1] neg_lo:[0,0,1]
	v_pk_mul_f32 v[178:179], v[122:123], s[90:91] op_sel:[1,1] op_sel_hi:[0,1]
	v_pk_fma_f32 v[122:123], v[122:123], s[90:91], v[178:179] op_sel_hi:[1,0,1] neg_lo:[0,0,1]
	v_pk_mul_f32 v[176:177], v[126:127], s[88:89] op_sel:[1,1] op_sel_hi:[0,1]
	v_pk_fma_f32 v[126:127], v[126:127], s[88:89], v[176:177] op_sel_hi:[1,0,1] neg_lo:[0,0,1]
	v_pk_mul_f32 v[166:167], v[128:129], s[90:91] op_sel:[1,1] op_sel_hi:[0,1]
	v_pk_fma_f32 v[128:129], v[128:129], s[90:91], v[166:167] op_sel_hi:[1,0,1] neg_lo:[0,0,1]
	v_pk_mul_f32 v[174:175], v[130:131], s[98:99] op_sel:[1,1] op_sel_hi:[0,1]
	v_pk_fma_f32 v[130:131], v[130:131], s[98:99], v[174:175] op_sel_hi:[1,0,1] neg_lo:[0,0,1]
	v_pk_add_f32 v[188:189], v[100:101], v[104:105]
	v_pk_add_f32 v[186:187], v[100:101], v[104:105] neg_lo:[0,1] neg_hi:[0,1]
	v_pk_add_f32 v[168:169], v[102:103], v[106:107]
	v_pk_add_f32 v[184:185], v[102:103], v[106:107] neg_lo:[0,1] neg_hi:[0,1]
	v_pk_add_f32 v[100:101], v[188:189], v[168:169]
	v_pk_add_f32 v[104:105], v[188:189], v[168:169] neg_lo:[0,1] neg_hi:[0,1]
	v_pk_add_f32 v[102:103], v[186:187], v[184:185] op_sel:[0,1] op_sel_hi:[1,0] neg_hi:[0,1]
; __device__ __forceinline__ f32x2 cmul(f32x2 a, f32x2 b) { return (f32x2){a.x * b.x - a.y * b.y, a.x * b.y + a.y * b.x}; }
; __device__ __forceinline__ void dft16_fwd_lo(f32x2 (&x)[16]) {
;     constexpr float C1 = 0.92387953251128674f, S1 = 0.38268343236508977f, C2 = 0.70710678118654752f;
; #pragma unroll
;     for (int b = 0; b < 4; ++b) { const f32x2 x0 = x[b], x1 = x[4 + b]; const f32x2 j1 = {x1.y, -x1.x};
;         x[b] = x0 + x1; x[4 + b] = x0 + j1; x[8 + b] = x0 - x1; x[12 + b] = x0 - j1; }
;     const f32x2 w1 = {C1, -S1}, w2 = {C2, -C2}, w3 = {S1, -C1}, w4 = {0.f, -1.f}, w6 = {-C2, -C2}, w9 = {-C1, S1};
;     x[5] = cmul(x[5], w1); x[6] = cmul(x[6], w2); x[7] = cmul(x[7], w3);
;     x[9] = cmul(x[9], w2); x[10] = cmul(x[10], w4); x[11] = cmul(x[11], w6);
;     x[13] = cmul(x[13], w3); x[14] = cmul(x[14], w6); x[15] = cmul(x[15], w9);
; template <int MODE> __device__ __forceinline__ void fft_pair32(LAS f32x2* B, const LAS f32x2* F, int wave, int lane) {
;     ...
;     if (MODE == 2) {
; #pragma unroll
;         for (int k = 0; k < 16; ++k) p[2 * k + hi] = v[k];
;         return; }
	v_pk_add_f32 v[106:107], v[186:187], v[184:185] op_sel:[0,1] op_sel_hi:[1,0] neg_lo:[0,1]
	v_pk_add_f32 v[182:183], v[108:109], v[112:113]
	v_pk_add_f32 v[180:181], v[108:109], v[112:113] neg_lo:[0,1] neg_hi:[0,1]
	v_pk_add_f32 v[178:179], v[110:111], v[114:115]
	v_pk_add_f32 v[176:177], v[110:111], v[114:115] neg_lo:[0,1] neg_hi:[0,1]
	v_pk_add_f32 v[108:109], v[182:183], v[178:179]
	v_pk_add_f32 v[112:113], v[182:183], v[178:179] neg_lo:[0,1] neg_hi:[0,1]
	v_pk_add_f32 v[110:111], v[180:181], v[176:177] op_sel:[0,1] op_sel_hi:[1,0] neg_hi:[0,1]
	v_pk_add_f32 v[114:115], v[180:181], v[176:177] op_sel:[0,1] op_sel_hi:[1,0] neg_lo:[0,1]
	v_pk_add_f32 v[166:167], v[116:117], v[120:121] op_sel:[0,1] op_sel_hi:[1,0] neg_hi:[0,1]
	v_pk_add_f32 v[174:175], v[116:117], v[120:121] op_sel:[0,1] op_sel_hi:[1,0] neg_lo:[0,1]
	v_pk_add_f32 v[188:189], v[118:119], v[122:123]
	v_pk_add_f32 v[186:187], v[118:119], v[122:123] neg_lo:[0,1] neg_hi:[0,1]
	v_pk_add_f32 v[116:117], v[166:167], v[188:189]
	v_pk_add_f32 v[120:121], v[166:167], v[188:189] neg_lo:[0,1] neg_hi:[0,1]
	v_pk_add_f32 v[118:119], v[174:175], v[186:187] op_sel:[0,1] op_sel_hi:[1,0] neg_hi:[0,1]
	v_pk_add_f32 v[122:123], v[174:175], v[186:187] op_sel:[0,1] op_sel_hi:[1,0] neg_lo:[0,1]
	v_pk_add_f32 v[168:169], v[124:125], v[128:129]
	v_pk_add_f32 v[184:185], v[124:125], v[128:129] neg_lo:[0,1] neg_hi:[0,1]
	v_pk_add_f32 v[182:183], v[126:127], v[130:131]
	v_pk_add_f32 v[180:181], v[126:127], v[130:131] neg_lo:[0,1] neg_hi:[0,1]
	v_pk_add_f32 v[124:125], v[168:169], v[182:183]
	v_pk_add_f32 v[128:129], v[168:169], v[182:183] neg_lo:[0,1] neg_hi:[0,1]
	v_pk_add_f32 v[126:127], v[184:185], v[180:181] op_sel:[0,1] op_sel_hi:[1,0] neg_hi:[0,1]
	v_pk_add_f32 v[130:131], v[184:185], v[180:181] op_sel:[0,1] op_sel_hi:[1,0] neg_lo:[0,1]
	v_pk_mul_f32 v[100:101], v[100:101], v[192:193] op_sel_hi:[1,0]
	ds_write_b64 v69, v[100:101]
	v_pk_mul_f32 v[108:109], v[108:109], v[192:193] op_sel_hi:[1,0]
	ds_write_b64 v69, v[108:109] offset:16
	v_pk_mul_f32 v[116:117], v[116:117], v[192:193] op_sel_hi:[1,0]
	ds_write_b64 v69, v[116:117] offset:32
	v_pk_mul_f32 v[124:125], v[124:125], v[192:193] op_sel_hi:[1,0]
	ds_write_b64 v69, v[124:125] offset:48
	v_pk_mul_f32 v[102:103], v[102:103], v[192:193] op_sel_hi:[1,0]
	ds_write_b64 v69, v[102:103] offset:64
	v_pk_mul_f32 v[110:111], v[110:111], v[192:193] op_sel_hi:[1,0]
	ds_write_b64 v69, v[110:111] offset:80
	v_pk_mul_f32 v[118:119], v[118:119], v[192:193] op_sel_hi:[1,0]
	ds_write_b64 v69, v[118:119] offset:96
	v_pk_mul_f32 v[126:127], v[126:127], v[192:193] op_sel_hi:[1,0]
	ds_write_b64 v69, v[126:127] offset:112
	v_pk_mul_f32 v[104:105], v[104:105], v[192:193] op_sel_hi:[1,0]
	ds_write_b64 v69, v[104:105] offset:128
	v_pk_mul_f32 v[112:113], v[112:113], v[192:193] op_sel_hi:[1,0]
	ds_write_b64 v69, v[112:113] offset:144
	v_pk_mul_f32 v[120:121], v[120:121], v[192:193] op_sel_hi:[1,0]
	ds_write_b64 v69, v[120:121] offset:160
	v_pk_mul_f32 v[128:129], v[128:129], v[192:193] op_sel_hi:[1,0]
	ds_write_b64 v69, v[128:129] offset:176
	v_pk_mul_f32 v[106:107], v[106:107], v[192:193] op_sel_hi:[1,0]
	ds_write_b64 v69, v[106:107] offset:192
	v_pk_mul_f32 v[114:115], v[114:115], v[192:193] op_sel_hi:[1,0]
	ds_write_b64 v69, v[114:115] offset:208
	v_pk_mul_f32 v[122:123], v[122:123], v[192:193] op_sel_hi:[1,0]
	ds_write_b64 v69, v[122:123] offset:224
	v_pk_mul_f32 v[130:131], v[130:131], v[192:193] op_sel_hi:[1,0]
	ds_write_b64 v69, v[130:131] offset:240
	s_waitcnt lgkmcnt(0)
	s_barrier
	s_cbranch_vccz .Lhfft_st4
	s_sleep 2
.Lhfft_st4:
	v_pk_add_f32 v[104:105], v[132:133], v[140:141] neg_lo:[0,1] neg_hi:[0,1]
	v_pk_add_f32 v[106:107], v[132:133], v[140:141] op_sel:[0,1] op_sel_hi:[1,0] neg_lo:[0,1]
	v_pk_add_f32 v[178:179], v[132:133], v[140:141] op_sel:[0,1] op_sel_hi:[1,0] neg_hi:[0,1]
	v_pk_add_f32 v[100:101], v[132:133], v[140:141]
	v_pk_add_f32 v[112:113], v[134:135], v[142:143] neg_lo:[0,1] neg_hi:[0,1]
	v_pk_add_f32 v[114:115], v[134:135], v[142:143] op_sel:[0,1] op_sel_hi:[1,0] neg_lo:[0,1]
	v_pk_add_f32 v[176:177], v[134:135], v[142:143] op_sel:[0,1] op_sel_hi:[1,0] neg_hi:[0,1]
	v_pk_add_f32 v[108:109], v[134:135], v[142:143]
	v_pk_add_f32 v[120:121], v[136:137], v[144:145] neg_lo:[0,1] neg_hi:[0,1]
	v_pk_add_f32 v[122:123], v[136:137], v[144:145] op_sel:[0,1] op_sel_hi:[1,0] neg_lo:[0,1]
	v_pk_add_f32 v[166:167], v[136:137], v[144:145] op_sel:[0,1] op_sel_hi:[1,0] neg_hi:[0,1]
	v_pk_add_f32 v[116:117], v[136:137], v[144:145]
	v_pk_add_f32 v[128:129], v[138:139], v[146:147] neg_lo:[0,1] neg_hi:[0,1]
	v_pk_add_f32 v[130:131], v[138:139], v[146:147] op_sel:[0,1] op_sel_hi:[1,0] neg_lo:[0,1]
	v_pk_add_f32 v[174:175], v[138:139], v[146:147] op_sel:[0,1] op_sel_hi:[1,0] neg_hi:[0,1]
	v_pk_add_f32 v[124:125], v[138:139], v[146:147]
	v_pk_mul_f32 v[188:189], v[176:177], s[68:69] op_sel:[1,1] op_sel_hi:[0,1]
	v_pk_fma_f32 v[176:177], v[176:177], s[68:69], v[188:189] op_sel_hi:[1,0,1] neg_lo:[0,0,1]
	v_pk_mul_f32 v[186:187], v[166:167], s[84:85] op_sel:[1,1] op_sel_hi:[0,1]
	v_pk_fma_f32 v[166:167], v[166:167], s[84:85], v[186:187] op_sel_hi:[1,0,1] neg_lo:[0,0,1]
	v_pk_mul_f32 v[168:169], v[174:175], s[88:89] op_sel:[1,1] op_sel_hi:[0,1]
	v_pk_fma_f32 v[174:175], v[174:175], s[88:89], v[168:169] op_sel_hi:[1,0,1] neg_lo:[0,0,1]
	v_pk_mul_f32 v[184:185], v[112:113], s[84:85] op_sel:[1,1] op_sel_hi:[0,1]
	v_pk_fma_f32 v[112:113], v[112:113], s[84:85], v[184:185] op_sel_hi:[1,0,1] neg_lo:[0,0,1]
	v_pk_mul_f32 v[182:183], v[128:129], s[90:91] op_sel:[1,1] op_sel_hi:[0,1]
	v_pk_fma_f32 v[128:129], v[128:129], s[90:91], v[182:183] op_sel_hi:[1,0,1] neg_lo:[0,0,1]
; __device__ __forceinline__ f32x2 cmul(f32x2 a, f32x2 b) { return (f32x2){a.x * b.x - a.y * b.y, a.x * b.y + a.y * b.x}; }
; __device__ __forceinline__ void dft16_fwd_lo(f32x2 (&x)[16]) {
;     ...
;     for (int b = 0; b < 4; ++b) { const f32x2 x0 = x[b], x1 = x[4 + b]; const f32x2 j1 = {x1.y, -x1.x};
;         x[b] = x0 + x1; x[4 + b] = x0 + j1; x[8 + b] = x0 - x1; x[12 + b] = x0 - j1; }
;     const f32x2 w1 = {C1, -S1}, w2 = {C2, -C2}, w3 = {S1, -C1}, w4 = {0.f, -1.f}, w6 = {-C2, -C2}, w9 = {-C1, S1};
;     x[5] = cmul(x[5], w1); x[6] = cmul(x[6], w2); x[7] = cmul(x[7], w3);
;     x[9] = cmul(x[9], w2); x[10] = cmul(x[10], w4); x[11] = cmul(x[11], w6);
;     x[13] = cmul(x[13], w3); x[14] = cmul(x[14], w6); x[15] = cmul(x[15], w9);
; #pragma unroll
;     for (int c = 0; c < 4; ++c) dft4<false>(x[4 * c], x[4 * c + 1], x[4 * c + 2], x[4 * c + 3]);
;     f32x2 y[16];
; #pragma unroll
;     for (int k = 0; k < 16; ++k) y[k] = x[4 * (k & 3) + (k >> 2)];
; #pragma unroll
;     for (int k = 0; k < 16; ++k) x[k] = y[k];
; }
; template <bool LO> __device__ __forceinline__ void fft_fwd1(f32x2 (&x)[16], LAS f32x2* B, int n2, const f32x2 (&w)[16]) {
;     ...
;     if (LO) dft16_fwd_lo(x); else dft16<false>(x);
;     B[fpad(n2)] = x[0];
; #pragma unroll
;     for (int k = 1; k < 16; ++k) B[fpad(512 * k + n2)] = cmul(x[k], w[k]);
	v_pk_mul_f32 v[180:181], v[114:115], s[88:89] op_sel:[1,1] op_sel_hi:[0,1]
	v_pk_fma_f32 v[114:115], v[114:115], s[88:89], v[180:181] op_sel_hi:[1,0,1] neg_lo:[0,0,1]
	v_pk_mul_f32 v[102:103], v[122:123], s[90:91] op_sel:[1,1] op_sel_hi:[0,1]
	v_pk_fma_f32 v[122:123], v[122:123], s[90:91], v[102:103] op_sel_hi:[1,0,1] neg_lo:[0,0,1]
	v_pk_mul_f32 v[110:111], v[130:131], s[98:99] op_sel:[1,1] op_sel_hi:[0,1]
	v_pk_fma_f32 v[130:131], v[130:131], s[98:99], v[110:111] op_sel_hi:[1,0,1] neg_lo:[0,0,1]
	v_pk_add_f32 v[118:119], v[100:101], v[116:117]
	v_pk_add_f32 v[126:127], v[100:101], v[116:117] neg_lo:[0,1] neg_hi:[0,1]
	v_pk_add_f32 v[188:189], v[108:109], v[124:125]
	v_pk_add_f32 v[186:187], v[108:109], v[124:125] neg_lo:[0,1] neg_hi:[0,1]
	v_pk_add_f32 v[100:101], v[118:119], v[188:189]
	v_pk_add_f32 v[116:117], v[118:119], v[188:189] neg_lo:[0,1] neg_hi:[0,1]
	v_pk_add_f32 v[108:109], v[126:127], v[186:187] op_sel:[0,1] op_sel_hi:[1,0] neg_hi:[0,1]
	v_pk_add_f32 v[124:125], v[126:127], v[186:187] op_sel:[0,1] op_sel_hi:[1,0] neg_lo:[0,1]
	v_pk_add_f32 v[168:169], v[178:179], v[166:167]
	v_pk_add_f32 v[184:185], v[178:179], v[166:167] neg_lo:[0,1] neg_hi:[0,1]
	v_pk_add_f32 v[182:183], v[176:177], v[174:175]
	v_pk_add_f32 v[180:181], v[176:177], v[174:175] neg_lo:[0,1] neg_hi:[0,1]
	v_pk_add_f32 v[178:179], v[168:169], v[182:183]
	v_pk_add_f32 v[166:167], v[168:169], v[182:183] neg_lo:[0,1] neg_hi:[0,1]
	v_pk_add_f32 v[176:177], v[184:185], v[180:181] op_sel:[0,1] op_sel_hi:[1,0] neg_hi:[0,1]
	v_pk_add_f32 v[174:175], v[184:185], v[180:181] op_sel:[0,1] op_sel_hi:[1,0] neg_lo:[0,1]
	v_pk_add_f32 v[102:103], v[104:105], v[120:121] op_sel:[0,1] op_sel_hi:[1,0] neg_hi:[0,1]
	v_pk_add_f32 v[110:111], v[104:105], v[120:121] op_sel:[0,1] op_sel_hi:[1,0] neg_lo:[0,1]
	v_pk_add_f32 v[118:119], v[112:113], v[128:129]
	v_pk_add_f32 v[126:127], v[112:113], v[128:129] neg_lo:[0,1] neg_hi:[0,1]
	v_pk_add_f32 v[104:105], v[102:103], v[118:119]
	v_pk_add_f32 v[120:121], v[102:103], v[118:119] neg_lo:[0,1] neg_hi:[0,1]
	v_pk_add_f32 v[112:113], v[110:111], v[126:127] op_sel:[0,1] op_sel_hi:[1,0] neg_hi:[0,1]
	v_pk_add_f32 v[128:129], v[110:111], v[126:127] op_sel:[0,1] op_sel_hi:[1,0] neg_lo:[0,1]
	v_pk_add_f32 v[188:189], v[106:107], v[122:123]
	v_pk_add_f32 v[186:187], v[106:107], v[122:123] neg_lo:[0,1] neg_hi:[0,1]
	v_pk_add_f32 v[168:169], v[114:115], v[130:131]
	v_pk_add_f32 v[184:185], v[114:115], v[130:131] neg_lo:[0,1] neg_hi:[0,1]
	v_pk_add_f32 v[106:107], v[188:189], v[168:169]
	v_pk_add_f32 v[122:123], v[188:189], v[168:169] neg_lo:[0,1] neg_hi:[0,1]
	v_pk_add_f32 v[114:115], v[186:187], v[184:185] op_sel:[0,1] op_sel_hi:[1,0] neg_hi:[0,1]
	v_pk_add_f32 v[130:131], v[186:187], v[184:185] op_sel:[0,1] op_sel_hi:[1,0] neg_lo:[0,1]
	ds_write_b64 v3, v[100:101]
	v_pk_mul_f32 v[180:181], v[178:179], v[6:7] op_sel:[1,1] op_sel_hi:[0,1]
	v_pk_fma_f32 v[182:183], v[178:179], v[6:7], v[180:181] op_sel_hi:[1,0,1] neg_lo:[0,0,1]
	ds_write_b64 v3, v[182:183] offset:4224
	v_pk_mul_f32 v[110:111], v[104:105], v[8:9] op_sel:[1,1] op_sel_hi:[0,1]
	v_pk_fma_f32 v[102:103], v[104:105], v[8:9], v[110:111] op_sel_hi:[1,0,1] neg_lo:[0,0,1]
	ds_write_b64 v3, v[102:103] offset:8448
	v_pk_mul_f32 v[126:127], v[106:107], v[10:11] op_sel:[1,1] op_sel_hi:[0,1]
	v_pk_fma_f32 v[118:119], v[106:107], v[10:11], v[126:127] op_sel_hi:[1,0,1] neg_lo:[0,0,1]
	ds_write_b64 v3, v[118:119] offset:12672
	v_pk_mul_f32 v[186:187], v[108:109], v[12:13] op_sel:[1,1] op_sel_hi:[0,1]
	v_pk_fma_f32 v[188:189], v[108:109], v[12:13], v[186:187] op_sel_hi:[1,0,1] neg_lo:[0,0,1]
	ds_write_b64 v3, v[188:189] offset:16896
	v_pk_mul_f32 v[184:185], v[176:177], v[14:15] op_sel:[1,1] op_sel_hi:[0,1]
	v_pk_fma_f32 v[168:169], v[176:177], v[14:15], v[184:185] op_sel_hi:[1,0,1] neg_lo:[0,0,1]
	ds_write_b64 v3, v[168:169] offset:21120
	v_pk_mul_f32 v[182:183], v[112:113], v[16:17] op_sel:[1,1] op_sel_hi:[0,1]
	v_pk_fma_f32 v[180:181], v[112:113], v[16:17], v[182:183] op_sel_hi:[1,0,1] neg_lo:[0,0,1]
	ds_write_b64 v3, v[180:181] offset:25344
	v_pk_mul_f32 v[102:103], v[114:115], v[18:19] op_sel:[1,1] op_sel_hi:[0,1]
	v_pk_fma_f32 v[110:111], v[114:115], v[18:19], v[102:103] op_sel_hi:[1,0,1] neg_lo:[0,0,1]
	ds_write_b64 v3, v[110:111] offset:29568
	v_pk_mul_f32 v[118:119], v[116:117], v[20:21] op_sel:[1,1] op_sel_hi:[0,1]
	v_pk_fma_f32 v[126:127], v[116:117], v[20:21], v[118:119] op_sel_hi:[1,0,1] neg_lo:[0,0,1]
	ds_write_b64 v3, v[126:127] offset:33792
	v_pk_mul_f32 v[188:189], v[166:167], v[22:23] op_sel:[1,1] op_sel_hi:[0,1]
	v_pk_fma_f32 v[186:187], v[166:167], v[22:23], v[188:189] op_sel_hi:[1,0,1] neg_lo:[0,0,1]
	ds_write_b64 v3, v[186:187] offset:38016
	v_pk_mul_f32 v[168:169], v[120:121], v[24:25] op_sel:[1,1] op_sel_hi:[0,1]
	v_pk_fma_f32 v[184:185], v[120:121], v[24:25], v[168:169] op_sel_hi:[1,0,1] neg_lo:[0,0,1]
	ds_write_b64 v3, v[184:185] offset:42240
	v_pk_mul_f32 v[180:181], v[122:123], v[26:27] op_sel:[1,1] op_sel_hi:[0,1]
	v_pk_fma_f32 v[182:183], v[122:123], v[26:27], v[180:181] op_sel_hi:[1,0,1] neg_lo:[0,0,1]
	ds_write_b64 v3, v[182:183] offset:46464
	v_pk_mul_f32 v[110:111], v[124:125], v[28:29] op_sel:[1,1] op_sel_hi:[0,1]
	v_pk_fma_f32 v[102:103], v[124:125], v[28:29], v[110:111] op_sel_hi:[1,0,1] neg_lo:[0,0,1]
	ds_write_b64 v3, v[102:103] offset:50688
	v_pk_mul_f32 v[126:127], v[174:175], v[30:31] op_sel:[1,1] op_sel_hi:[0,1]
	v_pk_fma_f32 v[118:119], v[174:175], v[30:31], v[126:127] op_sel_hi:[1,0,1] neg_lo:[0,0,1]
	ds_write_b64 v3, v[118:119] offset:54912
	v_pk_mul_f32 v[186:187], v[128:129], v[32:33] op_sel:[1,1] op_sel_hi:[0,1]
	v_pk_fma_f32 v[188:189], v[128:129], v[32:33], v[186:187] op_sel_hi:[1,0,1] neg_lo:[0,0,1]
	ds_write_b64 v3, v[188:189] offset:59136
	v_pk_mul_f32 v[184:185], v[130:131], v[34:35] op_sel:[1,1] op_sel_hi:[0,1]
	v_pk_fma_f32 v[168:169], v[130:131], v[34:35], v[184:185] op_sel_hi:[1,0,1] neg_lo:[0,0,1]
	ds_write_b64 v3, v[168:169] offset:63360
	s_waitcnt lgkmcnt(0)
	s_barrier
	s_cbranch_vccz .Lhfft_st5
	s_sleep 2
; #define LAS __attribute__((address_space(3)))
; __device__ __forceinline__ f32x2 cmul(f32x2 a, f32x2 b) { return (f32x2){a.x * b.x - a.y * b.y, a.x * b.y + a.y * b.x}; }
; template <bool INV> __device__ __forceinline__ f32x2 cmul_tw(f32x2 a, f32x2 w) { return INV ? cmulc(a, w) : cmul(a, w); }
; template <bool INV> __device__ __forceinline__ void dft16(f32x2 (&x)[16]) {
;     constexpr float C1 = 0.92387953251128674f, S1 = 0.38268343236508977f, C2 = 0.70710678118654752f;
; #pragma unroll
;     for (int b = 0; b < 4; ++b) dft4<INV>(x[b], x[4 + b], x[8 + b], x[12 + b]);
;     const f32x2 w1 = {C1, -S1}, w2 = {C2, -C2}, w3 = {S1, -C1}, w4 = {0.f, -1.f}, w6 = {-C2, -C2}, w9 = {-C1, S1};
;     x[4 * 1 + 1] = cmul_tw<INV>(x[5], w1); x[4 * 1 + 2] = cmul_tw<INV>(x[6], w2); x[4 * 1 + 3] = cmul_tw<INV>(x[7], w3);
;     x[4 * 2 + 1] = cmul_tw<INV>(x[9], w2); x[4 * 2 + 2] = cmul_tw<INV>(x[10], w4); x[4 * 2 + 3] = cmul_tw<INV>(x[11], w6);
;     x[4 * 3 + 1] = cmul_tw<INV>(x[13], w3); x[4 * 3 + 2] = cmul_tw<INV>(x[14], w6); x[4 * 3 + 3] = cmul_tw<INV>(x[15], w9);
; #pragma unroll
;     for (int c = 0; c < 4; ++c) dft4<INV>(x[4 * c], x[4 * c + 1], x[4 * c + 2], x[4 * c + 3]);
;     f32x2 y[16];
; #pragma unroll
;     for (int k = 0; k < 16; ++k) y[k] = x[4 * (k & 3) + (k >> 2)];
; #pragma unroll
;     for (int k = 0; k < 16; ++k) x[k] = y[k];
; __device__ __forceinline__ void fft_fwd2(LAS f32x2* B, const LAS f32x2* TW2, int tid) {
;     asm volatile("" : "+v"(tid));
;     const int b = tid >> 5, n2 = tid & 31, base = 512 * b + n2; f32x2 x[16];
; #pragma unroll
;     for (int r = 0; r < 16; ++r) x[r] = B[fpad(base + 32 * r)];
;     dft16<false>(x);
;     B[fpad(base)] = x[0];
; #pragma unroll
;     for (int k = 1; k < 16; ++k) B[fpad(base + 32 * k)] = cmul(x[k], TW2[k * 32 + n2]);
; }
.Lhfft_st5:
	ds_read_b64 v[100:101], v5
	ds_read_b64 v[108:109], v5 offset:1056
	ds_read_b64 v[116:117], v5 offset:2112
	ds_read_b64 v[124:125], v5 offset:3168
	ds_read_b64 v[178:179], v5 offset:264
	ds_read_b64 v[176:177], v5 offset:1320
	ds_read_b64 v[166:167], v5 offset:2376
	ds_read_b64 v[174:175], v5 offset:3432
	ds_read_b64 v[104:105], v5 offset:528
	ds_read_b64 v[112:113], v5 offset:1584
	ds_read_b64 v[120:121], v5 offset:2640
	ds_read_b64 v[128:129], v5 offset:3696
	s_waitcnt lgkmcnt(8)
	ds_read_b64 v[106:107], v5 offset:792
	ds_read_b64 v[114:115], v5 offset:1848
	ds_read_b64 v[122:123], v5 offset:2904
	ds_read_b64 v[130:131], v5 offset:3960
	v_pk_add_f32 v[180:181], v[100:101], v[116:117]
	v_pk_add_f32 v[182:183], v[100:101], v[116:117] neg_lo:[0,1] neg_hi:[0,1]
	v_pk_add_f32 v[110:111], v[108:109], v[124:125]
	v_pk_add_f32 v[102:103], v[108:109], v[124:125] neg_lo:[0,1] neg_hi:[0,1]
	v_pk_add_f32 v[100:101], v[180:181], v[110:111]
	v_pk_add_f32 v[116:117], v[180:181], v[110:111] neg_lo:[0,1] neg_hi:[0,1]
	v_pk_add_f32 v[108:109], v[182:183], v[102:103] op_sel:[0,1] op_sel_hi:[1,0] neg_hi:[0,1]
	v_pk_add_f32 v[124:125], v[182:183], v[102:103] op_sel:[0,1] op_sel_hi:[1,0] neg_lo:[0,1]
	s_waitcnt lgkmcnt(9)
	v_pk_add_f32 v[126:127], v[178:179], v[166:167]
	v_pk_add_f32 v[118:119], v[178:179], v[166:167] neg_lo:[0,1] neg_hi:[0,1]
	s_waitcnt lgkmcnt(8)
	v_pk_add_f32 v[186:187], v[176:177], v[174:175]
	v_pk_add_f32 v[188:189], v[176:177], v[174:175] neg_lo:[0,1] neg_hi:[0,1]
	v_pk_add_f32 v[178:179], v[126:127], v[186:187]
	v_pk_add_f32 v[166:167], v[126:127], v[186:187] neg_lo:[0,1] neg_hi:[0,1]
	v_pk_add_f32 v[176:177], v[118:119], v[188:189] op_sel:[0,1] op_sel_hi:[1,0] neg_hi:[0,1]
	v_pk_add_f32 v[174:175], v[118:119], v[188:189] op_sel:[0,1] op_sel_hi:[1,0] neg_lo:[0,1]
	s_waitcnt lgkmcnt(5)
	v_pk_add_f32 v[184:185], v[104:105], v[120:121]
	v_pk_add_f32 v[168:169], v[104:105], v[120:121] neg_lo:[0,1] neg_hi:[0,1]
	s_waitcnt lgkmcnt(4)
	v_pk_add_f32 v[180:181], v[112:113], v[128:129]
	v_pk_add_f32 v[182:183], v[112:113], v[128:129] neg_lo:[0,1] neg_hi:[0,1]
	v_pk_add_f32 v[104:105], v[184:185], v[180:181]
	v_pk_add_f32 v[120:121], v[184:185], v[180:181] neg_lo:[0,1] neg_hi:[0,1]
	v_pk_add_f32 v[112:113], v[168:169], v[182:183] op_sel:[0,1] op_sel_hi:[1,0] neg_hi:[0,1]
	v_pk_add_f32 v[128:129], v[168:169], v[182:183] op_sel:[0,1] op_sel_hi:[1,0] neg_lo:[0,1]
	s_waitcnt lgkmcnt(1)
	v_pk_add_f32 v[110:111], v[106:107], v[122:123]
	v_pk_add_f32 v[102:103], v[106:107], v[122:123] neg_lo:[0,1] neg_hi:[0,1]
	s_waitcnt lgkmcnt(0)
	v_pk_add_f32 v[126:127], v[114:115], v[130:131]
	v_pk_add_f32 v[118:119], v[114:115], v[130:131] neg_lo:[0,1] neg_hi:[0,1]
	v_pk_add_f32 v[106:107], v[110:111], v[126:127]
	v_pk_add_f32 v[122:123], v[110:111], v[126:127] neg_lo:[0,1] neg_hi:[0,1]
	v_pk_add_f32 v[114:115], v[102:103], v[118:119] op_sel:[0,1] op_sel_hi:[1,0] neg_hi:[0,1]
	v_pk_add_f32 v[130:131], v[102:103], v[118:119] op_sel:[0,1] op_sel_hi:[1,0] neg_lo:[0,1]
	v_pk_mul_f32 v[186:187], v[176:177], s[68:69] op_sel:[1,1] op_sel_hi:[0,1]
	v_pk_fma_f32 v[176:177], v[176:177], s[68:69], v[186:187] op_sel_hi:[1,0,1] neg_lo:[0,0,1]
	v_pk_mul_f32 v[188:189], v[112:113], s[84:85] op_sel:[1,1] op_sel_hi:[0,1]
	v_pk_fma_f32 v[112:113], v[112:113], s[84:85], v[188:189] op_sel_hi:[1,0,1] neg_lo:[0,0,1]
	v_pk_mul_f32 v[184:185], v[114:115], s[88:89] op_sel:[1,1] op_sel_hi:[0,1]
	v_pk_fma_f32 v[114:115], v[114:115], s[88:89], v[184:185] op_sel_hi:[1,0,1] neg_lo:[0,0,1]
	v_pk_mul_f32 v[168:169], v[166:167], s[84:85] op_sel:[1,1] op_sel_hi:[0,1]
	v_pk_fma_f32 v[166:167], v[166:167], s[84:85], v[168:169] op_sel_hi:[1,0,1] neg_lo:[0,0,1]
	v_pk_mul_f32 v[180:181], v[122:123], s[90:91] op_sel:[1,1] op_sel_hi:[0,1]
	v_pk_fma_f32 v[122:123], v[122:123], s[90:91], v[180:181] op_sel_hi:[1,0,1] neg_lo:[0,0,1]
	v_pk_mul_f32 v[182:183], v[174:175], s[88:89] op_sel:[1,1] op_sel_hi:[0,1]
	v_pk_fma_f32 v[174:175], v[174:175], s[88:89], v[182:183] op_sel_hi:[1,0,1] neg_lo:[0,0,1]
	v_pk_mul_f32 v[110:111], v[128:129], s[90:91] op_sel:[1,1] op_sel_hi:[0,1]
	v_pk_fma_f32 v[128:129], v[128:129], s[90:91], v[110:111] op_sel_hi:[1,0,1] neg_lo:[0,0,1]
	v_pk_mul_f32 v[102:103], v[130:131], s[98:99] op_sel:[1,1] op_sel_hi:[0,1]
	v_pk_fma_f32 v[130:131], v[130:131], s[98:99], v[102:103] op_sel_hi:[1,0,1] neg_lo:[0,0,1]
	v_pk_add_f32 v[126:127], v[100:101], v[104:105]
	v_pk_add_f32 v[118:119], v[100:101], v[104:105] neg_lo:[0,1] neg_hi:[0,1]
	v_pk_add_f32 v[186:187], v[178:179], v[106:107]
	v_pk_add_f32 v[188:189], v[178:179], v[106:107] neg_lo:[0,1] neg_hi:[0,1]
	v_pk_add_f32 v[100:101], v[126:127], v[186:187]
	v_pk_add_f32 v[104:105], v[126:127], v[186:187] neg_lo:[0,1] neg_hi:[0,1]
	v_pk_add_f32 v[178:179], v[118:119], v[188:189] op_sel:[0,1] op_sel_hi:[1,0] neg_hi:[0,1]
	v_pk_add_f32 v[106:107], v[118:119], v[188:189] op_sel:[0,1] op_sel_hi:[1,0] neg_lo:[0,1]
	v_pk_add_f32 v[184:185], v[108:109], v[112:113]
	v_pk_add_f32 v[168:169], v[108:109], v[112:113] neg_lo:[0,1] neg_hi:[0,1]
	v_pk_add_f32 v[180:181], v[176:177], v[114:115]
	v_pk_add_f32 v[182:183], v[176:177], v[114:115] neg_lo:[0,1] neg_hi:[0,1]
	v_pk_add_f32 v[108:109], v[184:185], v[180:181]
	v_pk_add_f32 v[112:113], v[184:185], v[180:181] neg_lo:[0,1] neg_hi:[0,1]
	v_pk_add_f32 v[176:177], v[168:169], v[182:183] op_sel:[0,1] op_sel_hi:[1,0] neg_hi:[0,1]
	v_pk_add_f32 v[114:115], v[168:169], v[182:183] op_sel:[0,1] op_sel_hi:[1,0] neg_lo:[0,1]
	v_pk_add_f32 v[110:111], v[116:117], v[120:121] op_sel:[0,1] op_sel_hi:[1,0] neg_hi:[0,1]
	v_pk_add_f32 v[102:103], v[116:117], v[120:121] op_sel:[0,1] op_sel_hi:[1,0] neg_lo:[0,1]
	v_pk_add_f32 v[126:127], v[166:167], v[122:123]
	v_pk_add_f32 v[118:119], v[166:167], v[122:123] neg_lo:[0,1] neg_hi:[0,1]
	v_pk_add_f32 v[116:117], v[110:111], v[126:127]
	v_pk_add_f32 v[120:121], v[110:111], v[126:127] neg_lo:[0,1] neg_hi:[0,1]
	v_pk_add_f32 v[166:167], v[102:103], v[118:119] op_sel:[0,1] op_sel_hi:[1,0] neg_hi:[0,1]
	v_pk_add_f32 v[122:123], v[102:103], v[118:119] op_sel:[0,1] op_sel_hi:[1,0] neg_lo:[0,1]
	v_pk_add_f32 v[186:187], v[124:125], v[128:129]
	v_pk_add_f32 v[188:189], v[124:125], v[128:129] neg_lo:[0,1] neg_hi:[0,1]
	v_pk_add_f32 v[184:185], v[174:175], v[130:131]
	v_pk_add_f32 v[168:169], v[174:175], v[130:131] neg_lo:[0,1] neg_hi:[0,1]
	v_pk_add_f32 v[124:125], v[186:187], v[184:185]
	v_pk_add_f32 v[128:129], v[186:187], v[184:185] neg_lo:[0,1] neg_hi:[0,1]
	v_pk_add_f32 v[174:175], v[188:189], v[168:169] op_sel:[0,1] op_sel_hi:[1,0] neg_hi:[0,1]
	v_pk_add_f32 v[130:131], v[188:189], v[168:169] op_sel:[0,1] op_sel_hi:[1,0] neg_lo:[0,1]
	ds_write_b64 v5, v[100:101]
	ds_read_b64 v[180:181], v56 offset:256
	ds_read_b64 v[182:183], v56 offset:512
	ds_read_b64 v[110:111], v56 offset:768
	ds_read_b64 v[102:103], v56 offset:1024
	s_waitcnt lgkmcnt(3)
; #define LAS __attribute__((address_space(3)))
; __device__ __forceinline__ f32x2 cmul(f32x2 a, f32x2 b) { return (f32x2){a.x * b.x - a.y * b.y, a.x * b.y + a.y * b.x}; }
; __device__ __forceinline__ void fft_fwd2(LAS f32x2* B, const LAS f32x2* TW2, int tid) {
;     ...
;     B[fpad(base)] = x[0];
; #pragma unroll
;     for (int k = 1; k < 16; ++k) B[fpad(base + 32 * k)] = cmul(x[k], TW2[k * 32 + n2]);
; }
; template <int MODE> __device__ __forceinline__ void fft_pair32(LAS f32x2* B, const LAS f32x2* F, int wave, int lane) {
;     ...
;     const int hi = lane >> 5, blk = 32 * wave + (lane & 31); const float sg = hi ? -1.f : 1.f;
;     LAS f32x2* p = B + 33 * blk; f32x2 v[16];
; #pragma unroll
;     for (int j = 0; j < 16; ++j) { const f32x2 d = p[j] + p[j + 16] * sg;
;         const f32x2 w = {hi ? CS[j] : 1.f, hi ? -SN[j] : 0.f}; v[j] = j == 0 ? d : cmul(d, w); }
;     dft16<false>(v);
	v_pk_mul_f32 v[126:127], v[108:109], v[180:181] op_sel:[1,1] op_sel_hi:[0,1]
	v_pk_fma_f32 v[108:109], v[108:109], v[180:181], v[126:127] op_sel_hi:[1,0,1] neg_lo:[0,0,1]
	ds_write_b64 v5, v[108:109] offset:264
	s_waitcnt lgkmcnt(3)
	v_pk_mul_f32 v[118:119], v[116:117], v[182:183] op_sel:[1,1] op_sel_hi:[0,1]
	v_pk_fma_f32 v[116:117], v[116:117], v[182:183], v[118:119] op_sel_hi:[1,0,1] neg_lo:[0,0,1]
	ds_write_b64 v5, v[116:117] offset:528
	s_waitcnt lgkmcnt(3)
	v_pk_mul_f32 v[186:187], v[124:125], v[110:111] op_sel:[1,1] op_sel_hi:[0,1]
	v_pk_fma_f32 v[124:125], v[124:125], v[110:111], v[186:187] op_sel_hi:[1,0,1] neg_lo:[0,0,1]
	ds_write_b64 v5, v[124:125] offset:792
	s_waitcnt lgkmcnt(3)
	v_pk_mul_f32 v[188:189], v[178:179], v[102:103] op_sel:[1,1] op_sel_hi:[0,1]
	v_pk_fma_f32 v[178:179], v[178:179], v[102:103], v[188:189] op_sel_hi:[1,0,1] neg_lo:[0,0,1]
	ds_write_b64 v5, v[178:179] offset:1056
	ds_read_b64 v[184:185], v56 offset:1280
	ds_read_b64 v[168:169], v56 offset:1536
	ds_read_b64 v[126:127], v56 offset:1792
	ds_read_b64 v[118:119], v56 offset:2048
	s_waitcnt lgkmcnt(3)
	v_pk_mul_f32 v[186:187], v[176:177], v[184:185] op_sel:[1,1] op_sel_hi:[0,1]
	v_pk_fma_f32 v[176:177], v[176:177], v[184:185], v[186:187] op_sel_hi:[1,0,1] neg_lo:[0,0,1]
	ds_write_b64 v5, v[176:177] offset:1320
	s_waitcnt lgkmcnt(3)
	v_pk_mul_f32 v[188:189], v[166:167], v[168:169] op_sel:[1,1] op_sel_hi:[0,1]
	v_pk_fma_f32 v[166:167], v[166:167], v[168:169], v[188:189] op_sel_hi:[1,0,1] neg_lo:[0,0,1]
	ds_write_b64 v5, v[166:167] offset:1584
	s_waitcnt lgkmcnt(3)
	v_pk_mul_f32 v[180:181], v[174:175], v[126:127] op_sel:[1,1] op_sel_hi:[0,1]
	v_pk_fma_f32 v[174:175], v[174:175], v[126:127], v[180:181] op_sel_hi:[1,0,1] neg_lo:[0,0,1]
	ds_write_b64 v5, v[174:175] offset:1848
	s_waitcnt lgkmcnt(3)
	v_pk_mul_f32 v[182:183], v[104:105], v[118:119] op_sel:[1,1] op_sel_hi:[0,1]
	v_pk_fma_f32 v[104:105], v[104:105], v[118:119], v[182:183] op_sel_hi:[1,0,1] neg_lo:[0,0,1]
	ds_write_b64 v5, v[104:105] offset:2112
	ds_read_b64 v[110:111], v56 offset:2304
	ds_read_b64 v[102:103], v56 offset:2560
	ds_read_b64 v[186:187], v56 offset:2816
	ds_read_b64 v[188:189], v56 offset:3072
	s_waitcnt lgkmcnt(3)
	v_pk_mul_f32 v[180:181], v[112:113], v[110:111] op_sel:[1,1] op_sel_hi:[0,1]
	v_pk_fma_f32 v[112:113], v[112:113], v[110:111], v[180:181] op_sel_hi:[1,0,1] neg_lo:[0,0,1]
	ds_write_b64 v5, v[112:113] offset:2376
	s_waitcnt lgkmcnt(3)
	v_pk_mul_f32 v[182:183], v[120:121], v[102:103] op_sel:[1,1] op_sel_hi:[0,1]
	v_pk_fma_f32 v[120:121], v[120:121], v[102:103], v[182:183] op_sel_hi:[1,0,1] neg_lo:[0,0,1]
	ds_write_b64 v5, v[120:121] offset:2640
	s_waitcnt lgkmcnt(3)
	v_pk_mul_f32 v[184:185], v[128:129], v[186:187] op_sel:[1,1] op_sel_hi:[0,1]
	v_pk_fma_f32 v[128:129], v[128:129], v[186:187], v[184:185] op_sel_hi:[1,0,1] neg_lo:[0,0,1]
	ds_write_b64 v5, v[128:129] offset:2904
	s_waitcnt lgkmcnt(3)
	v_pk_mul_f32 v[168:169], v[106:107], v[188:189] op_sel:[1,1] op_sel_hi:[0,1]
	v_pk_fma_f32 v[106:107], v[106:107], v[188:189], v[168:169] op_sel_hi:[1,0,1] neg_lo:[0,0,1]
	ds_write_b64 v5, v[106:107] offset:3168
	ds_read_b64 v[126:127], v56 offset:3328
	ds_read_b64 v[118:119], v56 offset:3584
	ds_read_b64 v[180:181], v56 offset:3840
	s_waitcnt lgkmcnt(2)
	v_pk_mul_f32 v[182:183], v[114:115], v[126:127] op_sel:[1,1] op_sel_hi:[0,1]
	v_pk_fma_f32 v[114:115], v[114:115], v[126:127], v[182:183] op_sel_hi:[1,0,1] neg_lo:[0,0,1]
	ds_write_b64 v5, v[114:115] offset:3432
	s_waitcnt lgkmcnt(2)
	v_pk_mul_f32 v[184:185], v[122:123], v[118:119] op_sel:[1,1] op_sel_hi:[0,1]
	v_pk_fma_f32 v[122:123], v[122:123], v[118:119], v[184:185] op_sel_hi:[1,0,1] neg_lo:[0,0,1]
	ds_write_b64 v5, v[122:123] offset:3696
	s_waitcnt lgkmcnt(2)
	v_pk_mul_f32 v[168:169], v[130:131], v[180:181] op_sel:[1,1] op_sel_hi:[0,1]
	v_pk_fma_f32 v[130:131], v[130:131], v[180:181], v[168:169] op_sel_hi:[1,0,1] neg_lo:[0,0,1]
	ds_write_b64 v5, v[130:131] offset:3960
	s_waitcnt lgkmcnt(0)
	ds_read_b64 v[100:101], v156
	ds_read_b64 v[110:111], v156 offset:128
	ds_read_b64 v[108:109], v156 offset:8
	ds_read_b64 v[102:103], v156 offset:136
	ds_read_b64 v[116:117], v156 offset:16
	ds_read_b64 v[186:187], v156 offset:144
	ds_read_b64 v[124:125], v156 offset:24
	ds_read_b64 v[188:189], v156 offset:152
	s_waitcnt lgkmcnt(6)
	v_pk_fma_f32 v[100:101], v[110:111], v[190:191], v[100:101] op_sel_hi:[1,0,1]
	s_waitcnt lgkmcnt(4)
	v_pk_fma_f32 v[108:109], v[102:103], v[190:191], v[108:109] op_sel_hi:[1,0,1]
	v_pk_mul_f32 v[182:183], v[108:109], v[36:37] op_sel:[1,1] op_sel_hi:[0,1]
	v_pk_fma_f32 v[108:109], v[108:109], v[36:37], v[182:183] op_sel_hi:[1,0,1] neg_lo:[0,0,1]
	s_waitcnt lgkmcnt(2)
	v_pk_fma_f32 v[116:117], v[186:187], v[190:191], v[116:117] op_sel_hi:[1,0,1]
	v_pk_mul_f32 v[184:185], v[116:117], v[38:39] op_sel:[1,1] op_sel_hi:[0,1]
	v_pk_fma_f32 v[116:117], v[116:117], v[38:39], v[184:185] op_sel_hi:[1,0,1] neg_lo:[0,0,1]
	s_waitcnt lgkmcnt(0)
	v_pk_fma_f32 v[124:125], v[188:189], v[190:191], v[124:125] op_sel_hi:[1,0,1]
	v_pk_mul_f32 v[168:169], v[124:125], v[40:41] op_sel:[1,1] op_sel_hi:[0,1]
	v_pk_fma_f32 v[124:125], v[124:125], v[40:41], v[168:169] op_sel_hi:[1,0,1] neg_lo:[0,0,1]
	ds_read_b64 v[178:179], v156 offset:32
	ds_read_b64 v[126:127], v156 offset:160
	ds_read_b64 v[176:177], v156 offset:40
	ds_read_b64 v[118:119], v156 offset:168
	ds_read_b64 v[166:167], v156 offset:48
	ds_read_b64 v[180:181], v156 offset:176
	ds_read_b64 v[174:175], v156 offset:56
	ds_read_b64 v[182:183], v156 offset:184
	s_waitcnt lgkmcnt(6)
; #define LAS __attribute__((address_space(3)))
; __device__ __forceinline__ f32x2 cmul(f32x2 a, f32x2 b) { return (f32x2){a.x * b.x - a.y * b.y, a.x * b.y + a.y * b.x}; }
; template <bool INV> __device__ __forceinline__ f32x2 cmul_tw(f32x2 a, f32x2 w) { return INV ? cmulc(a, w) : cmul(a, w); }
; template <bool INV> __device__ __forceinline__ void dft16(f32x2 (&x)[16]) {
;     constexpr float C1 = 0.92387953251128674f, S1 = 0.38268343236508977f, C2 = 0.70710678118654752f;
; #pragma unroll
;     for (int b = 0; b < 4; ++b) dft4<INV>(x[b], x[4 + b], x[8 + b], x[12 + b]);
;     const f32x2 w1 = {C1, -S1}, w2 = {C2, -C2}, w3 = {S1, -C1}, w4 = {0.f, -1.f}, w6 = {-C2, -C2}, w9 = {-C1, S1};
;     x[4 * 1 + 1] = cmul_tw<INV>(x[5], w1); x[4 * 1 + 2] = cmul_tw<INV>(x[6], w2); x[4 * 1 + 3] = cmul_tw<INV>(x[7], w3);
;     x[4 * 2 + 1] = cmul_tw<INV>(x[9], w2); x[4 * 2 + 2] = cmul_tw<INV>(x[10], w4); x[4 * 2 + 3] = cmul_tw<INV>(x[11], w6);
;     x[4 * 3 + 1] = cmul_tw<INV>(x[13], w3); x[4 * 3 + 2] = cmul_tw<INV>(x[14], w6); x[4 * 3 + 3] = cmul_tw<INV>(x[15], w9);
; #pragma unroll
;     for (int c = 0; c < 4; ++c) dft4<INV>(x[4 * c], x[4 * c + 1], x[4 * c + 2], x[4 * c + 3]);
; template <int MODE> __device__ __forceinline__ void fft_pair32(LAS f32x2* B, const LAS f32x2* F, int wave, int lane) {
;     ...
;     const int hi = lane >> 5, blk = 32 * wave + (lane & 31); const float sg = hi ? -1.f : 1.f;
;     LAS f32x2* p = B + 33 * blk; f32x2 v[16];
; #pragma unroll
;     for (int j = 0; j < 16; ++j) { const f32x2 d = p[j] + p[j + 16] * sg;
;         const f32x2 w = {hi ? CS[j] : 1.f, hi ? -SN[j] : 0.f}; v[j] = j == 0 ? d : cmul(d, w); }
;     dft16<false>(v);
	v_pk_fma_f32 v[178:179], v[126:127], v[190:191], v[178:179] op_sel_hi:[1,0,1]
	v_pk_mul_f32 v[184:185], v[178:179], v[42:43] op_sel:[1,1] op_sel_hi:[0,1]
	v_pk_fma_f32 v[178:179], v[178:179], v[42:43], v[184:185] op_sel_hi:[1,0,1] neg_lo:[0,0,1]
	s_waitcnt lgkmcnt(4)
	v_pk_fma_f32 v[176:177], v[118:119], v[190:191], v[176:177] op_sel_hi:[1,0,1]
	v_pk_mul_f32 v[168:169], v[176:177], v[44:45] op_sel:[1,1] op_sel_hi:[0,1]
	v_pk_fma_f32 v[176:177], v[176:177], v[44:45], v[168:169] op_sel_hi:[1,0,1] neg_lo:[0,0,1]
	s_waitcnt lgkmcnt(2)
	v_pk_fma_f32 v[166:167], v[180:181], v[190:191], v[166:167] op_sel_hi:[1,0,1]
	v_pk_mul_f32 v[110:111], v[166:167], v[46:47] op_sel:[1,1] op_sel_hi:[0,1]
	v_pk_fma_f32 v[166:167], v[166:167], v[46:47], v[110:111] op_sel_hi:[1,0,1] neg_lo:[0,0,1]
	s_waitcnt lgkmcnt(0)
	v_pk_fma_f32 v[174:175], v[182:183], v[190:191], v[174:175] op_sel_hi:[1,0,1]
	v_pk_mul_f32 v[102:103], v[174:175], v[48:49] op_sel:[1,1] op_sel_hi:[0,1]
	v_pk_fma_f32 v[174:175], v[174:175], v[48:49], v[102:103] op_sel_hi:[1,0,1] neg_lo:[0,0,1]
	ds_read_b64 v[104:105], v156 offset:64
	ds_read_b64 v[186:187], v156 offset:192
	ds_read_b64 v[112:113], v156 offset:72
	ds_read_b64 v[188:189], v156 offset:200
	ds_read_b64 v[120:121], v156 offset:80
	ds_read_b64 v[184:185], v156 offset:208
	ds_read_b64 v[128:129], v156 offset:88
	ds_read_b64 v[168:169], v156 offset:216
	s_waitcnt lgkmcnt(6)
	v_pk_fma_f32 v[104:105], v[186:187], v[190:191], v[104:105] op_sel_hi:[1,0,1]
	v_pk_mul_f32 v[110:111], v[104:105], v[50:51] op_sel:[1,1] op_sel_hi:[0,1]
	v_pk_fma_f32 v[104:105], v[104:105], v[50:51], v[110:111] op_sel_hi:[1,0,1] neg_lo:[0,0,1]
	s_waitcnt lgkmcnt(4)
	v_pk_fma_f32 v[112:113], v[188:189], v[190:191], v[112:113] op_sel_hi:[1,0,1]
	v_pk_mul_f32 v[102:103], v[112:113], v[52:53] op_sel:[1,1] op_sel_hi:[0,1]
	v_pk_fma_f32 v[112:113], v[112:113], v[52:53], v[102:103] op_sel_hi:[1,0,1] neg_lo:[0,0,1]
	s_waitcnt lgkmcnt(2)
	v_pk_fma_f32 v[120:121], v[184:185], v[190:191], v[120:121] op_sel_hi:[1,0,1]
	v_pk_mul_f32 v[126:127], v[120:121], v[54:55] op_sel:[1,1] op_sel_hi:[0,1]
	v_pk_fma_f32 v[120:121], v[120:121], v[54:55], v[126:127] op_sel_hi:[1,0,1] neg_lo:[0,0,1]
	s_waitcnt lgkmcnt(0)
	v_pk_fma_f32 v[128:129], v[168:169], v[190:191], v[128:129] op_sel_hi:[1,0,1]
	v_pk_mul_f32 v[118:119], v[128:129], v[90:91] op_sel:[1,1] op_sel_hi:[0,1]
	v_pk_fma_f32 v[128:129], v[128:129], v[90:91], v[118:119] op_sel_hi:[1,0,1] neg_lo:[0,0,1]
	ds_read_b64 v[106:107], v156 offset:96
	ds_read_b64 v[180:181], v156 offset:224
	ds_read_b64 v[114:115], v156 offset:104
	ds_read_b64 v[182:183], v156 offset:232
	ds_read_b64 v[122:123], v156 offset:112
	ds_read_b64 v[110:111], v156 offset:240
	ds_read_b64 v[130:131], v156 offset:120
	ds_read_b64 v[102:103], v156 offset:248
	s_waitcnt lgkmcnt(6)
	v_pk_fma_f32 v[106:107], v[180:181], v[190:191], v[106:107] op_sel_hi:[1,0,1]
	v_pk_mul_f32 v[126:127], v[106:107], v[92:93] op_sel:[1,1] op_sel_hi:[0,1]
	v_pk_fma_f32 v[106:107], v[106:107], v[92:93], v[126:127] op_sel_hi:[1,0,1] neg_lo:[0,0,1]
	s_waitcnt lgkmcnt(4)
	v_pk_fma_f32 v[114:115], v[182:183], v[190:191], v[114:115] op_sel_hi:[1,0,1]
	v_pk_mul_f32 v[118:119], v[114:115], v[94:95] op_sel:[1,1] op_sel_hi:[0,1]
	v_pk_fma_f32 v[114:115], v[114:115], v[94:95], v[118:119] op_sel_hi:[1,0,1] neg_lo:[0,0,1]
	s_waitcnt lgkmcnt(2)
	v_pk_fma_f32 v[122:123], v[110:111], v[190:191], v[122:123] op_sel_hi:[1,0,1]
	v_pk_mul_f32 v[186:187], v[122:123], v[96:97] op_sel:[1,1] op_sel_hi:[0,1]
	v_pk_fma_f32 v[122:123], v[122:123], v[96:97], v[186:187] op_sel_hi:[1,0,1] neg_lo:[0,0,1]
	s_waitcnt lgkmcnt(0)
	v_pk_fma_f32 v[130:131], v[102:103], v[190:191], v[130:131] op_sel_hi:[1,0,1]
	v_pk_mul_f32 v[188:189], v[130:131], v[98:99] op_sel:[1,1] op_sel_hi:[0,1]
	v_pk_fma_f32 v[130:131], v[130:131], v[98:99], v[188:189] op_sel_hi:[1,0,1] neg_lo:[0,0,1]
	v_pk_add_f32 v[184:185], v[100:101], v[104:105]
	v_pk_add_f32 v[168:169], v[100:101], v[104:105] neg_lo:[0,1] neg_hi:[0,1]
	v_pk_add_f32 v[126:127], v[178:179], v[106:107]
	v_pk_add_f32 v[118:119], v[178:179], v[106:107] neg_lo:[0,1] neg_hi:[0,1]
	v_pk_add_f32 v[100:101], v[184:185], v[126:127]
	v_pk_add_f32 v[104:105], v[184:185], v[126:127] neg_lo:[0,1] neg_hi:[0,1]
	v_pk_add_f32 v[178:179], v[168:169], v[118:119] op_sel:[0,1] op_sel_hi:[1,0] neg_hi:[0,1]
	v_pk_add_f32 v[106:107], v[168:169], v[118:119] op_sel:[0,1] op_sel_hi:[1,0] neg_lo:[0,1]
	v_pk_add_f32 v[186:187], v[108:109], v[112:113]
	v_pk_add_f32 v[188:189], v[108:109], v[112:113] neg_lo:[0,1] neg_hi:[0,1]
	v_pk_add_f32 v[180:181], v[176:177], v[114:115]
	v_pk_add_f32 v[182:183], v[176:177], v[114:115] neg_lo:[0,1] neg_hi:[0,1]
	v_pk_add_f32 v[108:109], v[186:187], v[180:181]
	v_pk_add_f32 v[112:113], v[186:187], v[180:181] neg_lo:[0,1] neg_hi:[0,1]
	v_pk_add_f32 v[176:177], v[188:189], v[182:183] op_sel:[0,1] op_sel_hi:[1,0] neg_hi:[0,1]
	v_pk_add_f32 v[114:115], v[188:189], v[182:183] op_sel:[0,1] op_sel_hi:[1,0] neg_lo:[0,1]
	v_pk_add_f32 v[110:111], v[116:117], v[120:121]
	v_pk_add_f32 v[102:103], v[116:117], v[120:121] neg_lo:[0,1] neg_hi:[0,1]
	v_pk_add_f32 v[184:185], v[166:167], v[122:123]
	v_pk_add_f32 v[168:169], v[166:167], v[122:123] neg_lo:[0,1] neg_hi:[0,1]
	v_pk_add_f32 v[116:117], v[110:111], v[184:185]
	v_pk_add_f32 v[120:121], v[110:111], v[184:185] neg_lo:[0,1] neg_hi:[0,1]
	v_pk_add_f32 v[166:167], v[102:103], v[168:169] op_sel:[0,1] op_sel_hi:[1,0] neg_hi:[0,1]
	v_pk_add_f32 v[122:123], v[102:103], v[168:169] op_sel:[0,1] op_sel_hi:[1,0] neg_lo:[0,1]
	v_pk_add_f32 v[126:127], v[124:125], v[128:129]
	v_pk_add_f32 v[118:119], v[124:125], v[128:129] neg_lo:[0,1] neg_hi:[0,1]
; #define LAS __attribute__((address_space(3)))
; __device__ __forceinline__ f32x2 cmul(f32x2 a, f32x2 b) { return (f32x2){a.x * b.x - a.y * b.y, a.x * b.y + a.y * b.x}; }
; template <bool INV> __device__ __forceinline__ f32x2 cmul_tw(f32x2 a, f32x2 w) { return INV ? cmulc(a, w) : cmul(a, w); }
; template <bool INV> __device__ __forceinline__ void dft16(f32x2 (&x)[16]) {
;     constexpr float C1 = 0.92387953251128674f, S1 = 0.38268343236508977f, C2 = 0.70710678118654752f;
; #pragma unroll
;     for (int b = 0; b < 4; ++b) dft4<INV>(x[b], x[4 + b], x[8 + b], x[12 + b]);
;     const f32x2 w1 = {C1, -S1}, w2 = {C2, -C2}, w3 = {S1, -C1}, w4 = {0.f, -1.f}, w6 = {-C2, -C2}, w9 = {-C1, S1};
;     x[4 * 1 + 1] = cmul_tw<INV>(x[5], w1); x[4 * 1 + 2] = cmul_tw<INV>(x[6], w2); x[4 * 1 + 3] = cmul_tw<INV>(x[7], w3);
;     x[4 * 2 + 1] = cmul_tw<INV>(x[9], w2); x[4 * 2 + 2] = cmul_tw<INV>(x[10], w4); x[4 * 2 + 3] = cmul_tw<INV>(x[11], w6);
;     x[4 * 3 + 1] = cmul_tw<INV>(x[13], w3); x[4 * 3 + 2] = cmul_tw<INV>(x[14], w6); x[4 * 3 + 3] = cmul_tw<INV>(x[15], w9);
; #pragma unroll
;     for (int c = 0; c < 4; ++c) dft4<INV>(x[4 * c], x[4 * c + 1], x[4 * c + 2], x[4 * c + 3]);
;     f32x2 y[16];
; #pragma unroll
;     for (int k = 0; k < 16; ++k) y[k] = x[4 * (k & 3) + (k >> 2)];
; #pragma unroll
;     for (int k = 0; k < 16; ++k) x[k] = y[k];
; template <int MODE> __device__ __forceinline__ void fft_pair32(LAS f32x2* B, const LAS f32x2* F, int wave, int lane) {
;     ...
;     const int k1 = blk >> 4, k2 = blk & 15, kb1 = (16 - k1) & 15, b1 = k1 != 0 ? 1 : 0, kb2 = (16 - k2 - b1) & 15, b2 = (k2 != 0 || b1) ? 1 : 0;
;     const LAS f32x2* fa = F + 33 * blk; const LAS f32x2* fb = F + 33 * (16 * kb1 + kb2);
;     const LAS f32x2* fah = fa + hi; const LAS f32x2* fbh = fb + (1 - b2) - hi;
;     constexpr float SC = 1.0f / (2.0f * (float)FN);
; #pragma unroll
;     for (int k = 0; k < 16; ++k) { const f32x2 A = fah[2 * k]; f32x2 Bm = fbh[31 - 2 * k];
;         if (k == 0) { const f32x2 m0 = b2 ? fb[31] : fa[0]; Bm = hi ? Bm : m0; }
;         const f32x2 H = MODE == 0 ? (f32x2){(A.x + Bm.x) * SC, (A.y - Bm.y) * SC} : (f32x2){(A.y + Bm.y) * SC, (Bm.x - A.x) * SC};
;         v[k] = cmul(v[k], H); }
	v_pk_add_f32 v[186:187], v[174:175], v[130:131]
	v_pk_add_f32 v[188:189], v[174:175], v[130:131] neg_lo:[0,1] neg_hi:[0,1]
	v_pk_add_f32 v[124:125], v[126:127], v[186:187]
	v_pk_add_f32 v[128:129], v[126:127], v[186:187] neg_lo:[0,1] neg_hi:[0,1]
	v_pk_add_f32 v[174:175], v[118:119], v[188:189] op_sel:[0,1] op_sel_hi:[1,0] neg_hi:[0,1]
	v_pk_add_f32 v[130:131], v[118:119], v[188:189] op_sel:[0,1] op_sel_hi:[1,0] neg_lo:[0,1]
	v_pk_mul_f32 v[180:181], v[176:177], s[68:69] op_sel:[1,1] op_sel_hi:[0,1]
	v_pk_fma_f32 v[176:177], v[176:177], s[68:69], v[180:181] op_sel_hi:[1,0,1] neg_lo:[0,0,1]
	v_pk_mul_f32 v[182:183], v[166:167], s[84:85] op_sel:[1,1] op_sel_hi:[0,1]
	v_pk_fma_f32 v[166:167], v[166:167], s[84:85], v[182:183] op_sel_hi:[1,0,1] neg_lo:[0,0,1]
	v_pk_mul_f32 v[110:111], v[174:175], s[88:89] op_sel:[1,1] op_sel_hi:[0,1]
	v_pk_fma_f32 v[174:175], v[174:175], s[88:89], v[110:111] op_sel_hi:[1,0,1] neg_lo:[0,0,1]
	v_pk_mul_f32 v[102:103], v[112:113], s[84:85] op_sel:[1,1] op_sel_hi:[0,1]
	v_pk_fma_f32 v[112:113], v[112:113], s[84:85], v[102:103] op_sel_hi:[1,0,1] neg_lo:[0,0,1]
	v_pk_mul_f32 v[184:185], v[128:129], s[90:91] op_sel:[1,1] op_sel_hi:[0,1]
	v_pk_fma_f32 v[128:129], v[128:129], s[90:91], v[184:185] op_sel_hi:[1,0,1] neg_lo:[0,0,1]
	v_pk_mul_f32 v[168:169], v[114:115], s[88:89] op_sel:[1,1] op_sel_hi:[0,1]
	v_pk_fma_f32 v[114:115], v[114:115], s[88:89], v[168:169] op_sel_hi:[1,0,1] neg_lo:[0,0,1]
	v_pk_mul_f32 v[126:127], v[122:123], s[90:91] op_sel:[1,1] op_sel_hi:[0,1]
	v_pk_fma_f32 v[122:123], v[122:123], s[90:91], v[126:127] op_sel_hi:[1,0,1] neg_lo:[0,0,1]
	v_pk_mul_f32 v[118:119], v[130:131], s[98:99] op_sel:[1,1] op_sel_hi:[0,1]
	v_pk_fma_f32 v[130:131], v[130:131], s[98:99], v[118:119] op_sel_hi:[1,0,1] neg_lo:[0,0,1]
	v_pk_add_f32 v[186:187], v[100:101], v[116:117]
	v_pk_add_f32 v[188:189], v[100:101], v[116:117] neg_lo:[0,1] neg_hi:[0,1]
	v_pk_add_f32 v[180:181], v[108:109], v[124:125]
	v_pk_add_f32 v[182:183], v[108:109], v[124:125] neg_lo:[0,1] neg_hi:[0,1]
	v_pk_add_f32 v[100:101], v[186:187], v[180:181]
	v_pk_add_f32 v[116:117], v[186:187], v[180:181] neg_lo:[0,1] neg_hi:[0,1]
	v_pk_add_f32 v[108:109], v[188:189], v[182:183] op_sel:[0,1] op_sel_hi:[1,0] neg_hi:[0,1]
	v_pk_add_f32 v[124:125], v[188:189], v[182:183] op_sel:[0,1] op_sel_hi:[1,0] neg_lo:[0,1]
	v_pk_add_f32 v[110:111], v[178:179], v[166:167]
	v_pk_add_f32 v[102:103], v[178:179], v[166:167] neg_lo:[0,1] neg_hi:[0,1]
	v_pk_add_f32 v[184:185], v[176:177], v[174:175]
	v_pk_add_f32 v[168:169], v[176:177], v[174:175] neg_lo:[0,1] neg_hi:[0,1]
	v_pk_add_f32 v[178:179], v[110:111], v[184:185]
	v_pk_add_f32 v[166:167], v[110:111], v[184:185] neg_lo:[0,1] neg_hi:[0,1]
	v_pk_add_f32 v[176:177], v[102:103], v[168:169] op_sel:[0,1] op_sel_hi:[1,0] neg_hi:[0,1]
	v_pk_add_f32 v[174:175], v[102:103], v[168:169] op_sel:[0,1] op_sel_hi:[1,0] neg_lo:[0,1]
	v_pk_add_f32 v[126:127], v[104:105], v[120:121] op_sel:[0,1] op_sel_hi:[1,0] neg_hi:[0,1]
	v_pk_add_f32 v[118:119], v[104:105], v[120:121] op_sel:[0,1] op_sel_hi:[1,0] neg_lo:[0,1]
	v_pk_add_f32 v[186:187], v[112:113], v[128:129]
	v_pk_add_f32 v[188:189], v[112:113], v[128:129] neg_lo:[0,1] neg_hi:[0,1]
	v_pk_add_f32 v[104:105], v[126:127], v[186:187]
	v_pk_add_f32 v[120:121], v[126:127], v[186:187] neg_lo:[0,1] neg_hi:[0,1]
	v_pk_add_f32 v[112:113], v[118:119], v[188:189] op_sel:[0,1] op_sel_hi:[1,0] neg_hi:[0,1]
	v_pk_add_f32 v[128:129], v[118:119], v[188:189] op_sel:[0,1] op_sel_hi:[1,0] neg_lo:[0,1]
	v_pk_add_f32 v[180:181], v[106:107], v[122:123]
	v_pk_add_f32 v[182:183], v[106:107], v[122:123] neg_lo:[0,1] neg_hi:[0,1]
	v_pk_add_f32 v[110:111], v[114:115], v[130:131]
	v_pk_add_f32 v[102:103], v[114:115], v[130:131] neg_lo:[0,1] neg_hi:[0,1]
	v_pk_add_f32 v[106:107], v[180:181], v[110:111]
	v_pk_add_f32 v[122:123], v[180:181], v[110:111] neg_lo:[0,1] neg_hi:[0,1]
	v_pk_add_f32 v[114:115], v[182:183], v[102:103] op_sel:[0,1] op_sel_hi:[1,0] neg_hi:[0,1]
	v_pk_add_f32 v[130:131], v[182:183], v[102:103] op_sel:[0,1] op_sel_hi:[1,0] neg_lo:[0,1]
	ds_read_b64 v[184:185], v200
	ds_read_b64 v[186:187], v204
	ds_read_b64 v[168:169], v200 offset:16
	ds_read_b64 v[188:189], v202 offset:232
	ds_read_b64 v[126:127], v200 offset:32
	ds_read_b64 v[180:181], v202 offset:216
	ds_read_b64 v[118:119], v200 offset:48
	ds_read_b64 v[182:183], v202 offset:200
	s_waitcnt lgkmcnt(6)
	v_pk_add_f32 v[184:185], v[184:185], v[186:187] neg_hi:[0,1]
	v_pk_mul_f32 v[110:111], v[100:101], v[184:185] op_sel:[1,1] op_sel_hi:[0,1]
	v_pk_fma_f32 v[100:101], v[100:101], v[184:185], v[110:111] op_sel_hi:[1,0,1] neg_lo:[0,0,1]
	s_waitcnt lgkmcnt(4)
	v_pk_add_f32 v[168:169], v[168:169], v[188:189] neg_hi:[0,1]
	v_pk_mul_f32 v[102:103], v[178:179], v[168:169] op_sel:[1,1] op_sel_hi:[0,1]
	v_pk_fma_f32 v[178:179], v[178:179], v[168:169], v[102:103] op_sel_hi:[1,0,1] neg_lo:[0,0,1]
	s_waitcnt lgkmcnt(2)
	v_pk_add_f32 v[126:127], v[126:127], v[180:181] neg_hi:[0,1]
	v_pk_mul_f32 v[110:111], v[104:105], v[126:127] op_sel:[1,1] op_sel_hi:[0,1]
	v_pk_fma_f32 v[104:105], v[104:105], v[126:127], v[110:111] op_sel_hi:[1,0,1] neg_lo:[0,0,1]
	s_waitcnt lgkmcnt(0)
	v_pk_add_f32 v[118:119], v[118:119], v[182:183] neg_hi:[0,1]
	v_pk_mul_f32 v[102:103], v[106:107], v[118:119] op_sel:[1,1] op_sel_hi:[0,1]
	v_pk_fma_f32 v[106:107], v[106:107], v[118:119], v[102:103] op_sel_hi:[1,0,1] neg_lo:[0,0,1]
	ds_read_b64 v[110:111], v200 offset:64
	ds_read_b64 v[126:127], v202 offset:184
	ds_read_b64 v[102:103], v200 offset:80
	ds_read_b64 v[118:119], v202 offset:168
	ds_read_b64 v[184:185], v200 offset:96
	ds_read_b64 v[186:187], v202 offset:152
	ds_read_b64 v[168:169], v200 offset:112
	ds_read_b64 v[188:189], v202 offset:136
	s_waitcnt lgkmcnt(6)
; __device__ __forceinline__ f32x2 cmul(f32x2 a, f32x2 b) { return (f32x2){a.x * b.x - a.y * b.y, a.x * b.y + a.y * b.x}; }
; template <bool INV> __device__ __forceinline__ f32x2 cmul_tw(f32x2 a, f32x2 w) { return INV ? cmulc(a, w) : cmul(a, w); }
; template <bool INV> __device__ __forceinline__ void dft16(f32x2 (&x)[16]) {
;     constexpr float C1 = 0.92387953251128674f, S1 = 0.38268343236508977f, C2 = 0.70710678118654752f;
; #pragma unroll
;     for (int b = 0; b < 4; ++b) dft4<INV>(x[b], x[4 + b], x[8 + b], x[12 + b]);
;     const f32x2 w1 = {C1, -S1}, w2 = {C2, -C2}, w3 = {S1, -C1}, w4 = {0.f, -1.f}, w6 = {-C2, -C2}, w9 = {-C1, S1};
;     x[4 * 1 + 1] = cmul_tw<INV>(x[5], w1); x[4 * 1 + 2] = cmul_tw<INV>(x[6], w2); x[4 * 1 + 3] = cmul_tw<INV>(x[7], w3);
;     x[4 * 2 + 1] = cmul_tw<INV>(x[9], w2); x[4 * 2 + 2] = cmul_tw<INV>(x[10], w4); x[4 * 2 + 3] = cmul_tw<INV>(x[11], w6);
;     x[4 * 3 + 1] = cmul_tw<INV>(x[13], w3); x[4 * 3 + 2] = cmul_tw<INV>(x[14], w6); x[4 * 3 + 3] = cmul_tw<INV>(x[15], w9);
; #pragma unroll
;     for (int c = 0; c < 4; ++c) dft4<INV>(x[4 * c], x[4 * c + 1], x[4 * c + 2], x[4 * c + 3]);
; template <int MODE> __device__ __forceinline__ void fft_pair32(LAS f32x2* B, const LAS f32x2* F, int wave, int lane) {
;     ...
;     for (int k = 0; k < 16; ++k) { const f32x2 A = fah[2 * k]; f32x2 Bm = fbh[31 - 2 * k];
;         if (k == 0) { const f32x2 m0 = b2 ? fb[31] : fa[0]; Bm = hi ? Bm : m0; }
;         const f32x2 H = MODE == 0 ? (f32x2){(A.x + Bm.x) * SC, (A.y - Bm.y) * SC} : (f32x2){(A.y + Bm.y) * SC, (Bm.x - A.x) * SC};
;         v[k] = cmul(v[k], H); }
;     dft16<true>(v);
	v_pk_add_f32 v[110:111], v[110:111], v[126:127] neg_hi:[0,1]
	v_pk_mul_f32 v[180:181], v[108:109], v[110:111] op_sel:[1,1] op_sel_hi:[0,1]
	v_pk_fma_f32 v[108:109], v[108:109], v[110:111], v[180:181] op_sel_hi:[1,0,1] neg_lo:[0,0,1]
	s_waitcnt lgkmcnt(4)
	v_pk_add_f32 v[102:103], v[102:103], v[118:119] neg_hi:[0,1]
	v_pk_mul_f32 v[182:183], v[176:177], v[102:103] op_sel:[1,1] op_sel_hi:[0,1]
	v_pk_fma_f32 v[176:177], v[176:177], v[102:103], v[182:183] op_sel_hi:[1,0,1] neg_lo:[0,0,1]
	s_waitcnt lgkmcnt(2)
	v_pk_add_f32 v[184:185], v[184:185], v[186:187] neg_hi:[0,1]
	v_pk_mul_f32 v[180:181], v[112:113], v[184:185] op_sel:[1,1] op_sel_hi:[0,1]
	v_pk_fma_f32 v[112:113], v[112:113], v[184:185], v[180:181] op_sel_hi:[1,0,1] neg_lo:[0,0,1]
	s_waitcnt lgkmcnt(0)
	v_pk_add_f32 v[168:169], v[168:169], v[188:189] neg_hi:[0,1]
	v_pk_mul_f32 v[182:183], v[114:115], v[168:169] op_sel:[1,1] op_sel_hi:[0,1]
	v_pk_fma_f32 v[114:115], v[114:115], v[168:169], v[182:183] op_sel_hi:[1,0,1] neg_lo:[0,0,1]
	ds_read_b64 v[180:181], v200 offset:128
	ds_read_b64 v[184:185], v202 offset:120
	ds_read_b64 v[182:183], v200 offset:144
	ds_read_b64 v[168:169], v202 offset:104
	ds_read_b64 v[110:111], v200 offset:160
	ds_read_b64 v[126:127], v202 offset:88
	ds_read_b64 v[102:103], v200 offset:176
	ds_read_b64 v[118:119], v202 offset:72
	s_waitcnt lgkmcnt(6)
	v_pk_add_f32 v[180:181], v[180:181], v[184:185] neg_hi:[0,1]
	v_pk_mul_f32 v[186:187], v[116:117], v[180:181] op_sel:[1,1] op_sel_hi:[0,1]
	v_pk_fma_f32 v[116:117], v[116:117], v[180:181], v[186:187] op_sel_hi:[1,0,1] neg_lo:[0,0,1]
	s_waitcnt lgkmcnt(4)
	v_pk_add_f32 v[182:183], v[182:183], v[168:169] neg_hi:[0,1]
	v_pk_mul_f32 v[188:189], v[166:167], v[182:183] op_sel:[1,1] op_sel_hi:[0,1]
	v_pk_fma_f32 v[166:167], v[166:167], v[182:183], v[188:189] op_sel_hi:[1,0,1] neg_lo:[0,0,1]
	s_waitcnt lgkmcnt(2)
	v_pk_add_f32 v[110:111], v[110:111], v[126:127] neg_hi:[0,1]
	v_pk_mul_f32 v[186:187], v[120:121], v[110:111] op_sel:[1,1] op_sel_hi:[0,1]
	v_pk_fma_f32 v[120:121], v[120:121], v[110:111], v[186:187] op_sel_hi:[1,0,1] neg_lo:[0,0,1]
	s_waitcnt lgkmcnt(0)
	v_pk_add_f32 v[102:103], v[102:103], v[118:119] neg_hi:[0,1]
	v_pk_mul_f32 v[188:189], v[122:123], v[102:103] op_sel:[1,1] op_sel_hi:[0,1]
	v_pk_fma_f32 v[122:123], v[122:123], v[102:103], v[188:189] op_sel_hi:[1,0,1] neg_lo:[0,0,1]
	ds_read_b64 v[186:187], v200 offset:192
	ds_read_b64 v[110:111], v202 offset:56
	ds_read_b64 v[188:189], v200 offset:208
	ds_read_b64 v[102:103], v202 offset:40
	ds_read_b64 v[180:181], v200 offset:224
	ds_read_b64 v[184:185], v202 offset:24
	ds_read_b64 v[182:183], v200 offset:240
	ds_read_b64 v[168:169], v202 offset:8
	s_waitcnt lgkmcnt(6)
	v_pk_add_f32 v[186:187], v[186:187], v[110:111] neg_hi:[0,1]
	v_pk_mul_f32 v[126:127], v[124:125], v[186:187] op_sel:[1,1] op_sel_hi:[0,1]
	v_pk_fma_f32 v[124:125], v[124:125], v[186:187], v[126:127] op_sel_hi:[1,0,1] neg_lo:[0,0,1]
	s_waitcnt lgkmcnt(4)
	v_pk_add_f32 v[188:189], v[188:189], v[102:103] neg_hi:[0,1]
	v_pk_mul_f32 v[118:119], v[174:175], v[188:189] op_sel:[1,1] op_sel_hi:[0,1]
	v_pk_fma_f32 v[174:175], v[174:175], v[188:189], v[118:119] op_sel_hi:[1,0,1] neg_lo:[0,0,1]
	s_waitcnt lgkmcnt(2)
	v_pk_add_f32 v[180:181], v[180:181], v[184:185] neg_hi:[0,1]
	v_pk_mul_f32 v[126:127], v[128:129], v[180:181] op_sel:[1,1] op_sel_hi:[0,1]
	v_pk_fma_f32 v[128:129], v[128:129], v[180:181], v[126:127] op_sel_hi:[1,0,1] neg_lo:[0,0,1]
	s_waitcnt lgkmcnt(0)
	v_pk_add_f32 v[182:183], v[182:183], v[168:169] neg_hi:[0,1]
	v_pk_mul_f32 v[118:119], v[130:131], v[182:183] op_sel:[1,1] op_sel_hi:[0,1]
	v_pk_fma_f32 v[130:131], v[130:131], v[182:183], v[118:119] op_sel_hi:[1,0,1] neg_lo:[0,0,1]
	v_pk_add_f32 v[126:127], v[100:101], v[116:117]
	v_pk_add_f32 v[118:119], v[100:101], v[116:117] neg_lo:[0,1] neg_hi:[0,1]
	v_pk_add_f32 v[186:187], v[108:109], v[124:125]
	v_pk_add_f32 v[188:189], v[108:109], v[124:125] neg_lo:[0,1] neg_hi:[0,1]
	v_pk_add_f32 v[100:101], v[126:127], v[186:187]
	v_pk_add_f32 v[116:117], v[126:127], v[186:187] neg_lo:[0,1] neg_hi:[0,1]
	v_pk_add_f32 v[108:109], v[118:119], v[188:189] op_sel:[0,1] op_sel_hi:[1,0] neg_lo:[0,1]
	v_pk_add_f32 v[124:125], v[118:119], v[188:189] op_sel:[0,1] op_sel_hi:[1,0] neg_hi:[0,1]
	v_pk_add_f32 v[180:181], v[178:179], v[166:167]
	v_pk_add_f32 v[182:183], v[178:179], v[166:167] neg_lo:[0,1] neg_hi:[0,1]
	v_pk_add_f32 v[110:111], v[176:177], v[174:175]
	v_pk_add_f32 v[102:103], v[176:177], v[174:175] neg_lo:[0,1] neg_hi:[0,1]
	v_pk_add_f32 v[178:179], v[180:181], v[110:111]
	v_pk_add_f32 v[166:167], v[180:181], v[110:111] neg_lo:[0,1] neg_hi:[0,1]
	v_pk_add_f32 v[176:177], v[182:183], v[102:103] op_sel:[0,1] op_sel_hi:[1,0] neg_lo:[0,1]
	v_pk_add_f32 v[174:175], v[182:183], v[102:103] op_sel:[0,1] op_sel_hi:[1,0] neg_hi:[0,1]
	v_pk_add_f32 v[184:185], v[104:105], v[120:121]
	v_pk_add_f32 v[168:169], v[104:105], v[120:121] neg_lo:[0,1] neg_hi:[0,1]
	v_pk_add_f32 v[126:127], v[112:113], v[128:129]
	v_pk_add_f32 v[118:119], v[112:113], v[128:129] neg_lo:[0,1] neg_hi:[0,1]
	v_pk_add_f32 v[104:105], v[184:185], v[126:127]
	v_pk_add_f32 v[120:121], v[184:185], v[126:127] neg_lo:[0,1] neg_hi:[0,1]
	v_pk_add_f32 v[112:113], v[168:169], v[118:119] op_sel:[0,1] op_sel_hi:[1,0] neg_lo:[0,1]
	v_pk_add_f32 v[128:129], v[168:169], v[118:119] op_sel:[0,1] op_sel_hi:[1,0] neg_hi:[0,1]
	v_pk_add_f32 v[186:187], v[106:107], v[122:123]
	v_pk_add_f32 v[188:189], v[106:107], v[122:123] neg_lo:[0,1] neg_hi:[0,1]
	v_pk_add_f32 v[180:181], v[114:115], v[130:131]
	v_pk_add_f32 v[182:183], v[114:115], v[130:131] neg_lo:[0,1] neg_hi:[0,1]
	v_pk_add_f32 v[106:107], v[186:187], v[180:181]
; __device__ __forceinline__ f32x2 cmulc(f32x2 a, f32x2 b) { return (f32x2){a.x * b.x + a.y * b.y, a.y * b.x - a.x * b.y}; }
; template <bool INV> __device__ __forceinline__ f32x2 cmul_tw(f32x2 a, f32x2 w) { return INV ? cmulc(a, w) : cmul(a, w); }
; template <bool INV> __device__ __forceinline__ void dft16(f32x2 (&x)[16]) {
;     constexpr float C1 = 0.92387953251128674f, S1 = 0.38268343236508977f, C2 = 0.70710678118654752f;
; #pragma unroll
;     for (int b = 0; b < 4; ++b) dft4<INV>(x[b], x[4 + b], x[8 + b], x[12 + b]);
;     const f32x2 w1 = {C1, -S1}, w2 = {C2, -C2}, w3 = {S1, -C1}, w4 = {0.f, -1.f}, w6 = {-C2, -C2}, w9 = {-C1, S1};
;     x[4 * 1 + 1] = cmul_tw<INV>(x[5], w1); x[4 * 1 + 2] = cmul_tw<INV>(x[6], w2); x[4 * 1 + 3] = cmul_tw<INV>(x[7], w3);
;     x[4 * 2 + 1] = cmul_tw<INV>(x[9], w2); x[4 * 2 + 2] = cmul_tw<INV>(x[10], w4); x[4 * 2 + 3] = cmul_tw<INV>(x[11], w6);
;     x[4 * 3 + 1] = cmul_tw<INV>(x[13], w3); x[4 * 3 + 2] = cmul_tw<INV>(x[14], w6); x[4 * 3 + 3] = cmul_tw<INV>(x[15], w9);
; #pragma unroll
;     for (int c = 0; c < 4; ++c) dft4<INV>(x[4 * c], x[4 * c + 1], x[4 * c + 2], x[4 * c + 3]);
;     f32x2 y[16];
; #pragma unroll
;     for (int k = 0; k < 16; ++k) y[k] = x[4 * (k & 3) + (k >> 2)];
; #pragma unroll
;     for (int k = 0; k < 16; ++k) x[k] = y[k];
; template <int MODE> __device__ __forceinline__ void fft_pair32(LAS f32x2* B, const LAS f32x2* F, int wave, int lane) {
;     ...
;     dft16<true>(v);
; #pragma unroll
;     for (int j = 0; j < 16; ++j) { const f32x2 w = {hi ? CS[j] : 1.f, hi ? -SN[j] : 0.f}; const f32x2 u = j == 0 ? v[j] : cmulc(v[j], w);
;         const auto rx = __builtin_amdgcn_permlane32_swap(__float_as_uint(u.x), __float_as_uint(u.x), false, false);
;         const auto ry = __builtin_amdgcn_permlane32_swap(__float_as_uint(u.y), __float_as_uint(u.y), false, false);
;         const f32x2 a = {__uint_as_float(rx[0]), __uint_as_float(ry[0])}, b = {__uint_as_float(rx[1]), __uint_as_float(ry[1])};
;         p[16 * hi + j] = a + b * sg; }
	v_pk_add_f32 v[122:123], v[186:187], v[180:181] neg_lo:[0,1] neg_hi:[0,1]
	v_pk_add_f32 v[114:115], v[188:189], v[182:183] op_sel:[0,1] op_sel_hi:[1,0] neg_lo:[0,1]
	v_pk_add_f32 v[130:131], v[188:189], v[182:183] op_sel:[0,1] op_sel_hi:[1,0] neg_hi:[0,1]
	v_pk_mul_f32 v[110:111], v[176:177], s[68:69] op_sel:[1,1] op_sel_hi:[0,1]
	v_pk_fma_f32 v[176:177], v[176:177], s[68:69], v[110:111] op_sel_hi:[1,0,1] neg_hi:[0,0,1]
	v_pk_mul_f32 v[102:103], v[112:113], s[84:85] op_sel:[1,1] op_sel_hi:[0,1]
	v_pk_fma_f32 v[112:113], v[112:113], s[84:85], v[102:103] op_sel_hi:[1,0,1] neg_hi:[0,0,1]
	v_pk_mul_f32 v[184:185], v[114:115], s[88:89] op_sel:[1,1] op_sel_hi:[0,1]
	v_pk_fma_f32 v[114:115], v[114:115], s[88:89], v[184:185] op_sel_hi:[1,0,1] neg_hi:[0,0,1]
	v_pk_mul_f32 v[168:169], v[166:167], s[84:85] op_sel:[1,1] op_sel_hi:[0,1]
	v_pk_fma_f32 v[166:167], v[166:167], s[84:85], v[168:169] op_sel_hi:[1,0,1] neg_hi:[0,0,1]
	v_pk_mul_f32 v[126:127], v[122:123], s[90:91] op_sel:[1,1] op_sel_hi:[0,1]
	v_pk_fma_f32 v[122:123], v[122:123], s[90:91], v[126:127] op_sel_hi:[1,0,1] neg_hi:[0,0,1]
	v_pk_mul_f32 v[118:119], v[174:175], s[88:89] op_sel:[1,1] op_sel_hi:[0,1]
	v_pk_fma_f32 v[174:175], v[174:175], s[88:89], v[118:119] op_sel_hi:[1,0,1] neg_hi:[0,0,1]
	v_pk_mul_f32 v[186:187], v[128:129], s[90:91] op_sel:[1,1] op_sel_hi:[0,1]
	v_pk_fma_f32 v[128:129], v[128:129], s[90:91], v[186:187] op_sel_hi:[1,0,1] neg_hi:[0,0,1]
	v_pk_mul_f32 v[188:189], v[130:131], s[98:99] op_sel:[1,1] op_sel_hi:[0,1]
	v_pk_fma_f32 v[130:131], v[130:131], s[98:99], v[188:189] op_sel_hi:[1,0,1] neg_hi:[0,0,1]
	v_pk_add_f32 v[180:181], v[100:101], v[104:105]
	v_pk_add_f32 v[182:183], v[100:101], v[104:105] neg_lo:[0,1] neg_hi:[0,1]
	v_pk_add_f32 v[110:111], v[178:179], v[106:107]
	v_pk_add_f32 v[102:103], v[178:179], v[106:107] neg_lo:[0,1] neg_hi:[0,1]
	v_pk_add_f32 v[100:101], v[180:181], v[110:111]
	v_pk_add_f32 v[104:105], v[180:181], v[110:111] neg_lo:[0,1] neg_hi:[0,1]
	v_pk_add_f32 v[178:179], v[182:183], v[102:103] op_sel:[0,1] op_sel_hi:[1,0] neg_lo:[0,1]
	v_pk_add_f32 v[106:107], v[182:183], v[102:103] op_sel:[0,1] op_sel_hi:[1,0] neg_hi:[0,1]
	v_pk_add_f32 v[184:185], v[108:109], v[112:113]
	v_pk_add_f32 v[168:169], v[108:109], v[112:113] neg_lo:[0,1] neg_hi:[0,1]
	v_pk_add_f32 v[126:127], v[176:177], v[114:115]
	v_pk_add_f32 v[118:119], v[176:177], v[114:115] neg_lo:[0,1] neg_hi:[0,1]
	v_pk_add_f32 v[108:109], v[184:185], v[126:127]
	v_pk_add_f32 v[112:113], v[184:185], v[126:127] neg_lo:[0,1] neg_hi:[0,1]
	v_pk_add_f32 v[176:177], v[168:169], v[118:119] op_sel:[0,1] op_sel_hi:[1,0] neg_lo:[0,1]
	v_pk_add_f32 v[114:115], v[168:169], v[118:119] op_sel:[0,1] op_sel_hi:[1,0] neg_hi:[0,1]
	v_pk_add_f32 v[186:187], v[116:117], v[120:121] op_sel:[0,1] op_sel_hi:[1,0] neg_lo:[0,1]
	v_pk_add_f32 v[188:189], v[116:117], v[120:121] op_sel:[0,1] op_sel_hi:[1,0] neg_hi:[0,1]
	v_pk_add_f32 v[180:181], v[166:167], v[122:123]
	v_pk_add_f32 v[182:183], v[166:167], v[122:123] neg_lo:[0,1] neg_hi:[0,1]
	v_pk_add_f32 v[116:117], v[186:187], v[180:181]
	v_pk_add_f32 v[120:121], v[186:187], v[180:181] neg_lo:[0,1] neg_hi:[0,1]
	v_pk_add_f32 v[166:167], v[188:189], v[182:183] op_sel:[0,1] op_sel_hi:[1,0] neg_lo:[0,1]
	v_pk_add_f32 v[122:123], v[188:189], v[182:183] op_sel:[0,1] op_sel_hi:[1,0] neg_hi:[0,1]
	v_pk_add_f32 v[110:111], v[124:125], v[128:129]
	v_pk_add_f32 v[102:103], v[124:125], v[128:129] neg_lo:[0,1] neg_hi:[0,1]
	v_pk_add_f32 v[184:185], v[174:175], v[130:131]
	v_pk_add_f32 v[168:169], v[174:175], v[130:131] neg_lo:[0,1] neg_hi:[0,1]
	v_pk_add_f32 v[124:125], v[110:111], v[184:185]
	v_pk_add_f32 v[128:129], v[110:111], v[184:185] neg_lo:[0,1] neg_hi:[0,1]
	v_pk_add_f32 v[174:175], v[102:103], v[168:169] op_sel:[0,1] op_sel_hi:[1,0] neg_lo:[0,1]
	v_pk_add_f32 v[130:131], v[102:103], v[168:169] op_sel:[0,1] op_sel_hi:[1,0] neg_hi:[0,1]
	v_mov_b32_e32 v126, v100
	v_mov_b32_e32 v127, v101
	v_pk_mul_f32 v[180:181], v[108:109], v[36:37] op_sel:[1,1] op_sel_hi:[0,1]
	v_pk_fma_f32 v[118:119], v[108:109], v[36:37], v[180:181] op_sel_hi:[1,0,1] neg_hi:[0,0,1]
	v_pk_fma_f32 v[108:109], v[108:109], v[36:37], v[180:181] op_sel_hi:[1,0,1] neg_hi:[0,0,1]
	v_pk_mul_f32 v[182:183], v[116:117], v[38:39] op_sel:[1,1] op_sel_hi:[0,1]
	v_pk_fma_f32 v[186:187], v[116:117], v[38:39], v[182:183] op_sel_hi:[1,0,1] neg_hi:[0,0,1]
	v_pk_fma_f32 v[116:117], v[116:117], v[38:39], v[182:183] op_sel_hi:[1,0,1] neg_hi:[0,0,1]
	v_pk_mul_f32 v[110:111], v[124:125], v[40:41] op_sel:[1,1] op_sel_hi:[0,1]
	v_pk_fma_f32 v[188:189], v[124:125], v[40:41], v[110:111] op_sel_hi:[1,0,1] neg_hi:[0,0,1]
	v_pk_fma_f32 v[124:125], v[124:125], v[40:41], v[110:111] op_sel_hi:[1,0,1] neg_hi:[0,0,1]
	s_nop 1
	v_permlane32_swap_b32_e32 v100, v126
	v_permlane32_swap_b32_e32 v101, v127
	v_permlane32_swap_b32_e32 v108, v118
	v_permlane32_swap_b32_e32 v109, v119
	v_permlane32_swap_b32_e32 v116, v186
	v_permlane32_swap_b32_e32 v117, v187
	v_permlane32_swap_b32_e32 v124, v188
	v_permlane32_swap_b32_e32 v125, v189
	v_pk_fma_f32 v[100:101], v[126:127], v[190:191], v[100:101] op_sel_hi:[1,0,1]
	ds_write_b64 v198, v[100:101]
	v_pk_fma_f32 v[108:109], v[118:119], v[190:191], v[108:109] op_sel_hi:[1,0,1]
	ds_write_b64 v198, v[108:109] offset:8
	v_pk_fma_f32 v[116:117], v[186:187], v[190:191], v[116:117] op_sel_hi:[1,0,1]
	ds_write_b64 v198, v[116:117] offset:16
	v_pk_fma_f32 v[124:125], v[188:189], v[190:191], v[124:125] op_sel_hi:[1,0,1]
	ds_write_b64 v198, v[124:125] offset:24
	v_pk_mul_f32 v[182:183], v[178:179], v[42:43] op_sel:[1,1] op_sel_hi:[0,1]
	v_pk_fma_f32 v[102:103], v[178:179], v[42:43], v[182:183] op_sel_hi:[1,0,1] neg_hi:[0,0,1]
; #define LAS __attribute__((address_space(3)))
; __device__ __forceinline__ f32x2 cmulc(f32x2 a, f32x2 b) { return (f32x2){a.x * b.x + a.y * b.y, a.y * b.x - a.x * b.y}; }
; __device__ __forceinline__ void fft_inv2(LAS f32x2* B, const LAS f32x2* TW2, int tid) {
;     asm volatile("" : "+v"(tid));
;     const int b = tid >> 5, n2 = tid & 31, base = 512 * b + n2; f32x2 x[16];
;     x[0] = B[fpad(base)];
; #pragma unroll
;     for (int k = 1; k < 16; ++k) x[k] = cmulc(B[fpad(base + 32 * k)], TW2[k * 32 + n2]);
; template <int MODE> __device__ __forceinline__ void fft_pair32(LAS f32x2* B, const LAS f32x2* F, int wave, int lane) {
;     ...
; #pragma unroll
;     for (int j = 0; j < 16; ++j) { const f32x2 w = {hi ? CS[j] : 1.f, hi ? -SN[j] : 0.f}; const f32x2 u = j == 0 ? v[j] : cmulc(v[j], w);
;         const auto rx = __builtin_amdgcn_permlane32_swap(__float_as_uint(u.x), __float_as_uint(u.x), false, false);
;         const auto ry = __builtin_amdgcn_permlane32_swap(__float_as_uint(u.y), __float_as_uint(u.y), false, false);
;         const f32x2 a = {__uint_as_float(rx[0]), __uint_as_float(ry[0])}, b = {__uint_as_float(rx[1]), __uint_as_float(ry[1])};
;         p[16 * hi + j] = a + b * sg; }
	v_pk_fma_f32 v[178:179], v[178:179], v[42:43], v[182:183] op_sel_hi:[1,0,1] neg_hi:[0,0,1]
	v_pk_mul_f32 v[110:111], v[176:177], v[44:45] op_sel:[1,1] op_sel_hi:[0,1]
	v_pk_fma_f32 v[184:185], v[176:177], v[44:45], v[110:111] op_sel_hi:[1,0,1] neg_hi:[0,0,1]
	v_pk_fma_f32 v[176:177], v[176:177], v[44:45], v[110:111] op_sel_hi:[1,0,1] neg_hi:[0,0,1]
	v_pk_mul_f32 v[126:127], v[166:167], v[46:47] op_sel:[1,1] op_sel_hi:[0,1]
	v_pk_fma_f32 v[168:169], v[166:167], v[46:47], v[126:127] op_sel_hi:[1,0,1] neg_hi:[0,0,1]
	v_pk_fma_f32 v[166:167], v[166:167], v[46:47], v[126:127] op_sel_hi:[1,0,1] neg_hi:[0,0,1]
	v_pk_mul_f32 v[118:119], v[174:175], v[48:49] op_sel:[1,1] op_sel_hi:[0,1]
	v_pk_fma_f32 v[180:181], v[174:175], v[48:49], v[118:119] op_sel_hi:[1,0,1] neg_hi:[0,0,1]
	v_pk_fma_f32 v[174:175], v[174:175], v[48:49], v[118:119] op_sel_hi:[1,0,1] neg_hi:[0,0,1]
	s_nop 1
	v_permlane32_swap_b32_e32 v178, v102
	v_permlane32_swap_b32_e32 v179, v103
	v_permlane32_swap_b32_e32 v176, v184
	v_permlane32_swap_b32_e32 v177, v185
	v_permlane32_swap_b32_e32 v166, v168
	v_permlane32_swap_b32_e32 v167, v169
	v_permlane32_swap_b32_e32 v174, v180
	v_permlane32_swap_b32_e32 v175, v181
	v_pk_fma_f32 v[178:179], v[102:103], v[190:191], v[178:179] op_sel_hi:[1,0,1]
	ds_write_b64 v198, v[178:179] offset:32
	v_pk_fma_f32 v[176:177], v[184:185], v[190:191], v[176:177] op_sel_hi:[1,0,1]
	ds_write_b64 v198, v[176:177] offset:40
	v_pk_fma_f32 v[166:167], v[168:169], v[190:191], v[166:167] op_sel_hi:[1,0,1]
	ds_write_b64 v198, v[166:167] offset:48
	v_pk_fma_f32 v[174:175], v[180:181], v[190:191], v[174:175] op_sel_hi:[1,0,1]
	ds_write_b64 v198, v[174:175] offset:56
	v_pk_mul_f32 v[126:127], v[104:105], v[50:51] op_sel:[1,1] op_sel_hi:[0,1]
	v_pk_fma_f32 v[186:187], v[104:105], v[50:51], v[126:127] op_sel_hi:[1,0,1] neg_hi:[0,0,1]
	v_pk_fma_f32 v[104:105], v[104:105], v[50:51], v[126:127] op_sel_hi:[1,0,1] neg_hi:[0,0,1]
	v_pk_mul_f32 v[118:119], v[112:113], v[52:53] op_sel:[1,1] op_sel_hi:[0,1]
	v_pk_fma_f32 v[188:189], v[112:113], v[52:53], v[118:119] op_sel_hi:[1,0,1] neg_hi:[0,0,1]
	v_pk_fma_f32 v[112:113], v[112:113], v[52:53], v[118:119] op_sel_hi:[1,0,1] neg_hi:[0,0,1]
	v_pk_mul_f32 v[102:103], v[120:121], v[54:55] op_sel:[1,1] op_sel_hi:[0,1]
	v_pk_fma_f32 v[182:183], v[120:121], v[54:55], v[102:103] op_sel_hi:[1,0,1] neg_hi:[0,0,1]
	v_pk_fma_f32 v[120:121], v[120:121], v[54:55], v[102:103] op_sel_hi:[1,0,1] neg_hi:[0,0,1]
	v_pk_mul_f32 v[184:185], v[128:129], v[90:91] op_sel:[1,1] op_sel_hi:[0,1]
	v_pk_fma_f32 v[110:111], v[128:129], v[90:91], v[184:185] op_sel_hi:[1,0,1] neg_hi:[0,0,1]
	v_pk_fma_f32 v[128:129], v[128:129], v[90:91], v[184:185] op_sel_hi:[1,0,1] neg_hi:[0,0,1]
	s_nop 1
	v_permlane32_swap_b32_e32 v104, v186
	v_permlane32_swap_b32_e32 v105, v187
	v_permlane32_swap_b32_e32 v112, v188
	v_permlane32_swap_b32_e32 v113, v189
	v_permlane32_swap_b32_e32 v120, v182
	v_permlane32_swap_b32_e32 v121, v183
	v_permlane32_swap_b32_e32 v128, v110
	v_permlane32_swap_b32_e32 v129, v111
	v_pk_fma_f32 v[104:105], v[186:187], v[190:191], v[104:105] op_sel_hi:[1,0,1]
	ds_write_b64 v198, v[104:105] offset:64
	v_pk_fma_f32 v[112:113], v[188:189], v[190:191], v[112:113] op_sel_hi:[1,0,1]
	ds_write_b64 v198, v[112:113] offset:72
	v_pk_fma_f32 v[120:121], v[182:183], v[190:191], v[120:121] op_sel_hi:[1,0,1]
	ds_write_b64 v198, v[120:121] offset:80
	v_pk_fma_f32 v[128:129], v[110:111], v[190:191], v[128:129] op_sel_hi:[1,0,1]
	ds_write_b64 v198, v[128:129] offset:88
	v_pk_mul_f32 v[102:103], v[106:107], v[92:93] op_sel:[1,1] op_sel_hi:[0,1]
	v_pk_fma_f32 v[168:169], v[106:107], v[92:93], v[102:103] op_sel_hi:[1,0,1] neg_hi:[0,0,1]
	v_pk_fma_f32 v[106:107], v[106:107], v[92:93], v[102:103] op_sel_hi:[1,0,1] neg_hi:[0,0,1]
	v_pk_mul_f32 v[184:185], v[114:115], v[94:95] op_sel:[1,1] op_sel_hi:[0,1]
	v_pk_fma_f32 v[180:181], v[114:115], v[94:95], v[184:185] op_sel_hi:[1,0,1] neg_hi:[0,0,1]
	v_pk_fma_f32 v[114:115], v[114:115], v[94:95], v[184:185] op_sel_hi:[1,0,1] neg_hi:[0,0,1]
	v_pk_mul_f32 v[186:187], v[122:123], v[96:97] op_sel:[1,1] op_sel_hi:[0,1]
	v_pk_fma_f32 v[126:127], v[122:123], v[96:97], v[186:187] op_sel_hi:[1,0,1] neg_hi:[0,0,1]
	v_pk_fma_f32 v[122:123], v[122:123], v[96:97], v[186:187] op_sel_hi:[1,0,1] neg_hi:[0,0,1]
	v_pk_mul_f32 v[188:189], v[130:131], v[98:99] op_sel:[1,1] op_sel_hi:[0,1]
	v_pk_fma_f32 v[118:119], v[130:131], v[98:99], v[188:189] op_sel_hi:[1,0,1] neg_hi:[0,0,1]
	v_pk_fma_f32 v[130:131], v[130:131], v[98:99], v[188:189] op_sel_hi:[1,0,1] neg_hi:[0,0,1]
	s_nop 1
	v_permlane32_swap_b32_e32 v106, v168
	v_permlane32_swap_b32_e32 v107, v169
	v_permlane32_swap_b32_e32 v114, v180
	v_permlane32_swap_b32_e32 v115, v181
	v_permlane32_swap_b32_e32 v122, v126
	v_permlane32_swap_b32_e32 v123, v127
	v_permlane32_swap_b32_e32 v130, v118
	v_permlane32_swap_b32_e32 v131, v119
	v_pk_fma_f32 v[106:107], v[168:169], v[190:191], v[106:107] op_sel_hi:[1,0,1]
	ds_write_b64 v198, v[106:107] offset:96
	v_pk_fma_f32 v[114:115], v[180:181], v[190:191], v[114:115] op_sel_hi:[1,0,1]
	ds_write_b64 v198, v[114:115] offset:104
	v_pk_fma_f32 v[122:123], v[126:127], v[190:191], v[122:123] op_sel_hi:[1,0,1]
	ds_write_b64 v198, v[122:123] offset:112
	v_pk_fma_f32 v[130:131], v[118:119], v[190:191], v[130:131] op_sel_hi:[1,0,1]
	ds_write_b64 v198, v[130:131] offset:120
	s_waitcnt lgkmcnt(0)
	ds_read_b64 v[100:101], v5
	ds_read_b64 v[108:109], v5 offset:264
	ds_read_b64 v[182:183], v56 offset:256
	ds_read_b64 v[116:117], v5 offset:528
	ds_read_b64 v[110:111], v56 offset:512
	ds_read_b64 v[124:125], v5 offset:792
	ds_read_b64 v[102:103], v56 offset:768
	ds_read_b64 v[178:179], v5 offset:1056
	ds_read_b64 v[184:185], v56 offset:1024
	ds_read_b64 v[176:177], v5 offset:1320
	ds_read_b64 v[186:187], v56 offset:1280
	s_waitcnt lgkmcnt(8)
; #define LAS __attribute__((address_space(3)))
; __device__ __forceinline__ f32x2 cmulc(f32x2 a, f32x2 b) { return (f32x2){a.x * b.x + a.y * b.y, a.y * b.x - a.x * b.y}; }
; template <bool INV> __device__ __forceinline__ f32x2 cmul_tw(f32x2 a, f32x2 w) { return INV ? cmulc(a, w) : cmul(a, w); }
; template <bool INV> __device__ __forceinline__ void dft16(f32x2 (&x)[16]) {
;     constexpr float C1 = 0.92387953251128674f, S1 = 0.38268343236508977f, C2 = 0.70710678118654752f;
; #pragma unroll
;     for (int b = 0; b < 4; ++b) dft4<INV>(x[b], x[4 + b], x[8 + b], x[12 + b]);
;     const f32x2 w1 = {C1, -S1}, w2 = {C2, -C2}, w3 = {S1, -C1}, w4 = {0.f, -1.f}, w6 = {-C2, -C2}, w9 = {-C1, S1};
;     x[4 * 1 + 1] = cmul_tw<INV>(x[5], w1); x[4 * 1 + 2] = cmul_tw<INV>(x[6], w2); x[4 * 1 + 3] = cmul_tw<INV>(x[7], w3);
;     x[4 * 2 + 1] = cmul_tw<INV>(x[9], w2); x[4 * 2 + 2] = cmul_tw<INV>(x[10], w4); x[4 * 2 + 3] = cmul_tw<INV>(x[11], w6);
;     x[4 * 3 + 1] = cmul_tw<INV>(x[13], w3); x[4 * 3 + 2] = cmul_tw<INV>(x[14], w6); x[4 * 3 + 3] = cmul_tw<INV>(x[15], w9);
; #pragma unroll
;     for (int c = 0; c < 4; ++c) dft4<INV>(x[4 * c], x[4 * c + 1], x[4 * c + 2], x[4 * c + 3]);
; __device__ __forceinline__ void fft_inv2(LAS f32x2* B, const LAS f32x2* TW2, int tid) {
;     asm volatile("" : "+v"(tid));
;     const int b = tid >> 5, n2 = tid & 31, base = 512 * b + n2; f32x2 x[16];
;     x[0] = B[fpad(base)];
; #pragma unroll
;     for (int k = 1; k < 16; ++k) x[k] = cmulc(B[fpad(base + 32 * k)], TW2[k * 32 + n2]);
;     dft16<true>(x);
	v_pk_mul_f32 v[188:189], v[108:109], v[182:183] op_sel:[1,1] op_sel_hi:[0,1]
	v_pk_fma_f32 v[108:109], v[108:109], v[182:183], v[188:189] op_sel_hi:[1,0,1] neg_hi:[0,0,1]
	s_waitcnt lgkmcnt(6)
	v_pk_mul_f32 v[168:169], v[116:117], v[110:111] op_sel:[1,1] op_sel_hi:[0,1]
	v_pk_fma_f32 v[116:117], v[116:117], v[110:111], v[168:169] op_sel_hi:[1,0,1] neg_hi:[0,0,1]
	s_waitcnt lgkmcnt(4)
	v_pk_mul_f32 v[180:181], v[124:125], v[102:103] op_sel:[1,1] op_sel_hi:[0,1]
	v_pk_fma_f32 v[124:125], v[124:125], v[102:103], v[180:181] op_sel_hi:[1,0,1] neg_hi:[0,0,1]
	s_waitcnt lgkmcnt(2)
	v_pk_mul_f32 v[126:127], v[178:179], v[184:185] op_sel:[1,1] op_sel_hi:[0,1]
	v_pk_fma_f32 v[178:179], v[178:179], v[184:185], v[126:127] op_sel_hi:[1,0,1] neg_hi:[0,0,1]
	s_waitcnt lgkmcnt(0)
	v_pk_mul_f32 v[118:119], v[176:177], v[186:187] op_sel:[1,1] op_sel_hi:[0,1]
	v_pk_fma_f32 v[176:177], v[176:177], v[186:187], v[118:119] op_sel_hi:[1,0,1] neg_hi:[0,0,1]
	ds_read_b64 v[166:167], v5 offset:1584
	ds_read_b64 v[188:189], v56 offset:1536
	ds_read_b64 v[174:175], v5 offset:1848
	ds_read_b64 v[168:169], v56 offset:1792
	ds_read_b64 v[104:105], v5 offset:2112
	ds_read_b64 v[180:181], v56 offset:2048
	ds_read_b64 v[112:113], v5 offset:2376
	ds_read_b64 v[126:127], v56 offset:2304
	ds_read_b64 v[120:121], v5 offset:2640
	ds_read_b64 v[118:119], v56 offset:2560
	s_waitcnt lgkmcnt(8)
	v_pk_mul_f32 v[182:183], v[166:167], v[188:189] op_sel:[1,1] op_sel_hi:[0,1]
	v_pk_fma_f32 v[166:167], v[166:167], v[188:189], v[182:183] op_sel_hi:[1,0,1] neg_hi:[0,0,1]
	s_waitcnt lgkmcnt(6)
	v_pk_mul_f32 v[110:111], v[174:175], v[168:169] op_sel:[1,1] op_sel_hi:[0,1]
	v_pk_fma_f32 v[174:175], v[174:175], v[168:169], v[110:111] op_sel_hi:[1,0,1] neg_hi:[0,0,1]
	s_waitcnt lgkmcnt(4)
	v_pk_mul_f32 v[102:103], v[104:105], v[180:181] op_sel:[1,1] op_sel_hi:[0,1]
	v_pk_fma_f32 v[104:105], v[104:105], v[180:181], v[102:103] op_sel_hi:[1,0,1] neg_hi:[0,0,1]
	s_waitcnt lgkmcnt(2)
	v_pk_mul_f32 v[184:185], v[112:113], v[126:127] op_sel:[1,1] op_sel_hi:[0,1]
	v_pk_fma_f32 v[112:113], v[112:113], v[126:127], v[184:185] op_sel_hi:[1,0,1] neg_hi:[0,0,1]
	s_waitcnt lgkmcnt(0)
	v_pk_mul_f32 v[186:187], v[120:121], v[118:119] op_sel:[1,1] op_sel_hi:[0,1]
	v_pk_fma_f32 v[120:121], v[120:121], v[118:119], v[186:187] op_sel_hi:[1,0,1] neg_hi:[0,0,1]
	ds_read_b64 v[128:129], v5 offset:2904
	ds_read_b64 v[182:183], v56 offset:2816
	ds_read_b64 v[106:107], v5 offset:3168
	ds_read_b64 v[110:111], v56 offset:3072
	ds_read_b64 v[114:115], v5 offset:3432
	ds_read_b64 v[102:103], v56 offset:3328
	ds_read_b64 v[122:123], v5 offset:3696
	ds_read_b64 v[184:185], v56 offset:3584
	ds_read_b64 v[130:131], v5 offset:3960
	ds_read_b64 v[186:187], v56 offset:3840
	s_waitcnt lgkmcnt(8)
	v_pk_mul_f32 v[188:189], v[128:129], v[182:183] op_sel:[1,1] op_sel_hi:[0,1]
	v_pk_fma_f32 v[128:129], v[128:129], v[182:183], v[188:189] op_sel_hi:[1,0,1] neg_hi:[0,0,1]
	s_waitcnt lgkmcnt(6)
	v_pk_mul_f32 v[168:169], v[106:107], v[110:111] op_sel:[1,1] op_sel_hi:[0,1]
	v_pk_fma_f32 v[106:107], v[106:107], v[110:111], v[168:169] op_sel_hi:[1,0,1] neg_hi:[0,0,1]
	s_waitcnt lgkmcnt(4)
	v_pk_mul_f32 v[180:181], v[114:115], v[102:103] op_sel:[1,1] op_sel_hi:[0,1]
	v_pk_fma_f32 v[114:115], v[114:115], v[102:103], v[180:181] op_sel_hi:[1,0,1] neg_hi:[0,0,1]
	s_waitcnt lgkmcnt(2)
	v_pk_mul_f32 v[126:127], v[122:123], v[184:185] op_sel:[1,1] op_sel_hi:[0,1]
	v_pk_fma_f32 v[122:123], v[122:123], v[184:185], v[126:127] op_sel_hi:[1,0,1] neg_hi:[0,0,1]
	s_waitcnt lgkmcnt(0)
	v_pk_mul_f32 v[118:119], v[130:131], v[186:187] op_sel:[1,1] op_sel_hi:[0,1]
	v_pk_fma_f32 v[130:131], v[130:131], v[186:187], v[118:119] op_sel_hi:[1,0,1] neg_hi:[0,0,1]
	v_pk_add_f32 v[188:189], v[100:101], v[104:105]
	v_pk_add_f32 v[168:169], v[100:101], v[104:105] neg_lo:[0,1] neg_hi:[0,1]
	v_pk_add_f32 v[180:181], v[178:179], v[106:107]
	v_pk_add_f32 v[126:127], v[178:179], v[106:107] neg_lo:[0,1] neg_hi:[0,1]
	v_pk_add_f32 v[100:101], v[188:189], v[180:181]
	v_pk_add_f32 v[104:105], v[188:189], v[180:181] neg_lo:[0,1] neg_hi:[0,1]
	v_pk_add_f32 v[178:179], v[168:169], v[126:127] op_sel:[0,1] op_sel_hi:[1,0] neg_lo:[0,1]
	v_pk_add_f32 v[106:107], v[168:169], v[126:127] op_sel:[0,1] op_sel_hi:[1,0] neg_hi:[0,1]
	v_pk_add_f32 v[118:119], v[108:109], v[112:113]
	v_pk_add_f32 v[182:183], v[108:109], v[112:113] neg_lo:[0,1] neg_hi:[0,1]
	v_pk_add_f32 v[110:111], v[176:177], v[114:115]
	v_pk_add_f32 v[102:103], v[176:177], v[114:115] neg_lo:[0,1] neg_hi:[0,1]
	v_pk_add_f32 v[108:109], v[118:119], v[110:111]
	v_pk_add_f32 v[112:113], v[118:119], v[110:111] neg_lo:[0,1] neg_hi:[0,1]
	v_pk_add_f32 v[176:177], v[182:183], v[102:103] op_sel:[0,1] op_sel_hi:[1,0] neg_lo:[0,1]
	v_pk_add_f32 v[114:115], v[182:183], v[102:103] op_sel:[0,1] op_sel_hi:[1,0] neg_hi:[0,1]
	v_pk_add_f32 v[184:185], v[116:117], v[120:121]
	v_pk_add_f32 v[186:187], v[116:117], v[120:121] neg_lo:[0,1] neg_hi:[0,1]
	v_pk_add_f32 v[188:189], v[166:167], v[122:123]
	v_pk_add_f32 v[168:169], v[166:167], v[122:123] neg_lo:[0,1] neg_hi:[0,1]
	v_pk_add_f32 v[116:117], v[184:185], v[188:189]
	v_pk_add_f32 v[120:121], v[184:185], v[188:189] neg_lo:[0,1] neg_hi:[0,1]
	v_pk_add_f32 v[166:167], v[186:187], v[168:169] op_sel:[0,1] op_sel_hi:[1,0] neg_lo:[0,1]
	v_pk_add_f32 v[122:123], v[186:187], v[168:169] op_sel:[0,1] op_sel_hi:[1,0] neg_hi:[0,1]
	v_pk_add_f32 v[180:181], v[124:125], v[128:129]
	v_pk_add_f32 v[126:127], v[124:125], v[128:129] neg_lo:[0,1] neg_hi:[0,1]
	v_pk_add_f32 v[118:119], v[174:175], v[130:131]
	v_pk_add_f32 v[182:183], v[174:175], v[130:131] neg_lo:[0,1] neg_hi:[0,1]
	v_pk_add_f32 v[124:125], v[180:181], v[118:119]
; template <bool INV> __device__ __forceinline__ f32x2 cmul_tw(f32x2 a, f32x2 w) { return INV ? cmulc(a, w) : cmul(a, w); }
; template <bool INV> __device__ __forceinline__ void dft16(f32x2 (&x)[16]) {
;     constexpr float C1 = 0.92387953251128674f, S1 = 0.38268343236508977f, C2 = 0.70710678118654752f;
; #pragma unroll
;     for (int b = 0; b < 4; ++b) dft4<INV>(x[b], x[4 + b], x[8 + b], x[12 + b]);
;     const f32x2 w1 = {C1, -S1}, w2 = {C2, -C2}, w3 = {S1, -C1}, w4 = {0.f, -1.f}, w6 = {-C2, -C2}, w9 = {-C1, S1};
;     x[4 * 1 + 1] = cmul_tw<INV>(x[5], w1); x[4 * 1 + 2] = cmul_tw<INV>(x[6], w2); x[4 * 1 + 3] = cmul_tw<INV>(x[7], w3);
;     x[4 * 2 + 1] = cmul_tw<INV>(x[9], w2); x[4 * 2 + 2] = cmul_tw<INV>(x[10], w4); x[4 * 2 + 3] = cmul_tw<INV>(x[11], w6);
;     x[4 * 3 + 1] = cmul_tw<INV>(x[13], w3); x[4 * 3 + 2] = cmul_tw<INV>(x[14], w6); x[4 * 3 + 3] = cmul_tw<INV>(x[15], w9);
; #pragma unroll
;     for (int c = 0; c < 4; ++c) dft4<INV>(x[4 * c], x[4 * c + 1], x[4 * c + 2], x[4 * c + 3]);
;     f32x2 y[16];
; #pragma unroll
;     for (int k = 0; k < 16; ++k) y[k] = x[4 * (k & 3) + (k >> 2)];
; #pragma unroll
;     for (int k = 0; k < 16; ++k) x[k] = y[k];
; __device__ __forceinline__ void fft_inv2(LAS f32x2* B, const LAS f32x2* TW2, int tid) {
;     ...
;     dft16<true>(x);
; #pragma unroll
;     for (int r = 0; r < 16; ++r) B[fpad(base + 32 * r)] = x[r];
	v_pk_add_f32 v[128:129], v[180:181], v[118:119] neg_lo:[0,1] neg_hi:[0,1]
	v_pk_add_f32 v[174:175], v[126:127], v[182:183] op_sel:[0,1] op_sel_hi:[1,0] neg_lo:[0,1]
	v_pk_add_f32 v[130:131], v[126:127], v[182:183] op_sel:[0,1] op_sel_hi:[1,0] neg_hi:[0,1]
	v_pk_mul_f32 v[110:111], v[176:177], s[68:69] op_sel:[1,1] op_sel_hi:[0,1]
	v_pk_fma_f32 v[176:177], v[176:177], s[68:69], v[110:111] op_sel_hi:[1,0,1] neg_hi:[0,0,1]
	v_pk_mul_f32 v[102:103], v[166:167], s[84:85] op_sel:[1,1] op_sel_hi:[0,1]
	v_pk_fma_f32 v[166:167], v[166:167], s[84:85], v[102:103] op_sel_hi:[1,0,1] neg_hi:[0,0,1]
	v_pk_mul_f32 v[184:185], v[174:175], s[88:89] op_sel:[1,1] op_sel_hi:[0,1]
	v_pk_fma_f32 v[174:175], v[174:175], s[88:89], v[184:185] op_sel_hi:[1,0,1] neg_hi:[0,0,1]
	v_pk_mul_f32 v[186:187], v[112:113], s[84:85] op_sel:[1,1] op_sel_hi:[0,1]
	v_pk_fma_f32 v[112:113], v[112:113], s[84:85], v[186:187] op_sel_hi:[1,0,1] neg_hi:[0,0,1]
	v_pk_mul_f32 v[188:189], v[128:129], s[90:91] op_sel:[1,1] op_sel_hi:[0,1]
	v_pk_fma_f32 v[128:129], v[128:129], s[90:91], v[188:189] op_sel_hi:[1,0,1] neg_hi:[0,0,1]
	v_pk_mul_f32 v[168:169], v[114:115], s[88:89] op_sel:[1,1] op_sel_hi:[0,1]
	v_pk_fma_f32 v[114:115], v[114:115], s[88:89], v[168:169] op_sel_hi:[1,0,1] neg_hi:[0,0,1]
	v_pk_mul_f32 v[180:181], v[122:123], s[90:91] op_sel:[1,1] op_sel_hi:[0,1]
	v_pk_fma_f32 v[122:123], v[122:123], s[90:91], v[180:181] op_sel_hi:[1,0,1] neg_hi:[0,0,1]
	v_pk_mul_f32 v[126:127], v[130:131], s[98:99] op_sel:[1,1] op_sel_hi:[0,1]
	v_pk_fma_f32 v[130:131], v[130:131], s[98:99], v[126:127] op_sel_hi:[1,0,1] neg_hi:[0,0,1]
	v_pk_add_f32 v[118:119], v[100:101], v[116:117]
	v_pk_add_f32 v[182:183], v[100:101], v[116:117] neg_lo:[0,1] neg_hi:[0,1]
	v_pk_add_f32 v[110:111], v[108:109], v[124:125]
	v_pk_add_f32 v[102:103], v[108:109], v[124:125] neg_lo:[0,1] neg_hi:[0,1]
	v_pk_add_f32 v[100:101], v[118:119], v[110:111]
	v_pk_add_f32 v[116:117], v[118:119], v[110:111] neg_lo:[0,1] neg_hi:[0,1]
	v_pk_add_f32 v[108:109], v[182:183], v[102:103] op_sel:[0,1] op_sel_hi:[1,0] neg_lo:[0,1]
	v_pk_add_f32 v[124:125], v[182:183], v[102:103] op_sel:[0,1] op_sel_hi:[1,0] neg_hi:[0,1]
	v_pk_add_f32 v[184:185], v[178:179], v[166:167]
	v_pk_add_f32 v[186:187], v[178:179], v[166:167] neg_lo:[0,1] neg_hi:[0,1]
	v_pk_add_f32 v[188:189], v[176:177], v[174:175]
	v_pk_add_f32 v[168:169], v[176:177], v[174:175] neg_lo:[0,1] neg_hi:[0,1]
	v_pk_add_f32 v[178:179], v[184:185], v[188:189]
	v_pk_add_f32 v[166:167], v[184:185], v[188:189] neg_lo:[0,1] neg_hi:[0,1]
	v_pk_add_f32 v[176:177], v[186:187], v[168:169] op_sel:[0,1] op_sel_hi:[1,0] neg_lo:[0,1]
	v_pk_add_f32 v[174:175], v[186:187], v[168:169] op_sel:[0,1] op_sel_hi:[1,0] neg_hi:[0,1]
	v_pk_add_f32 v[180:181], v[104:105], v[120:121] op_sel:[0,1] op_sel_hi:[1,0] neg_lo:[0,1]
	v_pk_add_f32 v[126:127], v[104:105], v[120:121] op_sel:[0,1] op_sel_hi:[1,0] neg_hi:[0,1]
	v_pk_add_f32 v[118:119], v[112:113], v[128:129]
	v_pk_add_f32 v[182:183], v[112:113], v[128:129] neg_lo:[0,1] neg_hi:[0,1]
	v_pk_add_f32 v[104:105], v[180:181], v[118:119]
	v_pk_add_f32 v[120:121], v[180:181], v[118:119] neg_lo:[0,1] neg_hi:[0,1]
	v_pk_add_f32 v[112:113], v[126:127], v[182:183] op_sel:[0,1] op_sel_hi:[1,0] neg_lo:[0,1]
	v_pk_add_f32 v[128:129], v[126:127], v[182:183] op_sel:[0,1] op_sel_hi:[1,0] neg_hi:[0,1]
	v_pk_add_f32 v[110:111], v[106:107], v[122:123]
	v_pk_add_f32 v[102:103], v[106:107], v[122:123] neg_lo:[0,1] neg_hi:[0,1]
	v_pk_add_f32 v[184:185], v[114:115], v[130:131]
	v_pk_add_f32 v[186:187], v[114:115], v[130:131] neg_lo:[0,1] neg_hi:[0,1]
	v_pk_add_f32 v[106:107], v[110:111], v[184:185]
	v_pk_add_f32 v[122:123], v[110:111], v[184:185] neg_lo:[0,1] neg_hi:[0,1]
	v_pk_add_f32 v[114:115], v[102:103], v[186:187] op_sel:[0,1] op_sel_hi:[1,0] neg_lo:[0,1]
	v_pk_add_f32 v[130:131], v[102:103], v[186:187] op_sel:[0,1] op_sel_hi:[1,0] neg_hi:[0,1]
	ds_write_b64 v5, v[100:101]
	ds_write_b64 v5, v[178:179] offset:264
	ds_write_b64 v5, v[104:105] offset:528
	ds_write_b64 v5, v[106:107] offset:792
	ds_write_b64 v5, v[108:109] offset:1056
	ds_write_b64 v5, v[176:177] offset:1320
	ds_write_b64 v5, v[112:113] offset:1584
	ds_write_b64 v5, v[114:115] offset:1848
	ds_write_b64 v5, v[116:117] offset:2112
	ds_write_b64 v5, v[166:167] offset:2376
	ds_write_b64 v5, v[120:121] offset:2640
	ds_write_b64 v5, v[122:123] offset:2904
	ds_write_b64 v5, v[124:125] offset:3168
	ds_write_b64 v5, v[174:175] offset:3432
	ds_write_b64 v5, v[128:129] offset:3696
	ds_write_b64 v5, v[130:131] offset:3960
	s_waitcnt lgkmcnt(0)
	s_barrier
	s_cbranch_vccz .Lhfft_st6
	s_sleep 2
; #define LAS __attribute__((address_space(3)))
; __device__ __forceinline__ f32x2 cmulc(f32x2 a, f32x2 b) { return (f32x2){a.x * b.x + a.y * b.y, a.y * b.x - a.x * b.y}; }
; __device__ __forceinline__ void dft16_inv_lo(f32x2 (&x)[16]) {
;     constexpr float C1 = 0.92387953251128674f, S1 = 0.38268343236508977f, C2 = 0.70710678118654752f;
; #pragma unroll
;     for (int b = 0; b < 4; ++b) dft4<true>(x[b], x[4 + b], x[8 + b], x[12 + b]);
;     const f32x2 w1 = {C1, -S1}, w2 = {C2, -C2}, w3 = {S1, -C1}, w4 = {0.f, -1.f}, w6 = {-C2, -C2}, w9 = {-C1, S1};
;     x[5] = cmulc(x[5], w1); x[6] = cmulc(x[6], w2); x[7] = cmulc(x[7], w3);
;     x[9] = cmulc(x[9], w2); x[10] = cmulc(x[10], w4); x[11] = cmulc(x[11], w6);
;     x[13] = cmulc(x[13], w3); x[14] = cmulc(x[14], w6); x[15] = cmulc(x[15], w9);
; __device__ __forceinline__ void fft_inv1(f32x2 (&x)[16], const LAS f32x2* B, int n2, const f32x2 (&w)[16]) {
;     asm volatile("" : "+v"(n2));
;     x[0] = B[fpad(n2)];
; #pragma unroll
;     for (int k = 1; k < 16; ++k) x[k] = cmulc(B[fpad(512 * k + n2)], w[k]);
;     dft16_inv_lo(x);
.Lhfft_st6:
	ds_read_b64 v[100:101], v3
	ds_read_b64 v[108:109], v3 offset:16896
	ds_read_b64 v[116:117], v3 offset:33792
	ds_read_b64 v[124:125], v3 offset:50688
	ds_read_b64 v[178:179], v3 offset:4224
	ds_read_b64 v[176:177], v3 offset:21120
	ds_read_b64 v[166:167], v3 offset:38016
	ds_read_b64 v[174:175], v3 offset:54912
	ds_read_b64 v[104:105], v3 offset:8448
	ds_read_b64 v[112:113], v3 offset:25344
	ds_read_b64 v[120:121], v3 offset:42240
	ds_read_b64 v[128:129], v3 offset:59136
	ds_read_b64 v[106:107], v3 offset:12672
	ds_read_b64 v[114:115], v3 offset:29568
	ds_read_b64 v[122:123], v3 offset:46464
	ds_read_b64 v[130:131], v3 offset:63360
	s_waitcnt lgkmcnt(14)
	v_pk_mul_f32 v[188:189], v[108:109], v[12:13] op_sel:[1,1] op_sel_hi:[0,1]
	v_pk_fma_f32 v[108:109], v[108:109], v[12:13], v[188:189] op_sel_hi:[1,0,1] neg_hi:[0,0,1]
	s_waitcnt lgkmcnt(13)
	v_pk_mul_f32 v[168:169], v[116:117], v[20:21] op_sel:[1,1] op_sel_hi:[0,1]
	v_pk_fma_f32 v[116:117], v[116:117], v[20:21], v[168:169] op_sel_hi:[1,0,1] neg_hi:[0,0,1]
	s_waitcnt lgkmcnt(12)
	v_pk_mul_f32 v[180:181], v[124:125], v[28:29] op_sel:[1,1] op_sel_hi:[0,1]
	v_pk_fma_f32 v[124:125], v[124:125], v[28:29], v[180:181] op_sel_hi:[1,0,1] neg_hi:[0,0,1]
	s_waitcnt lgkmcnt(11)
	v_pk_mul_f32 v[126:127], v[178:179], v[6:7] op_sel:[1,1] op_sel_hi:[0,1]
	v_pk_fma_f32 v[178:179], v[178:179], v[6:7], v[126:127] op_sel_hi:[1,0,1] neg_hi:[0,0,1]
	s_waitcnt lgkmcnt(10)
	v_pk_mul_f32 v[118:119], v[176:177], v[14:15] op_sel:[1,1] op_sel_hi:[0,1]
	v_pk_fma_f32 v[176:177], v[176:177], v[14:15], v[118:119] op_sel_hi:[1,0,1] neg_hi:[0,0,1]
	s_waitcnt lgkmcnt(9)
	v_pk_mul_f32 v[182:183], v[166:167], v[22:23] op_sel:[1,1] op_sel_hi:[0,1]
	v_pk_fma_f32 v[166:167], v[166:167], v[22:23], v[182:183] op_sel_hi:[1,0,1] neg_hi:[0,0,1]
	s_waitcnt lgkmcnt(8)
	v_pk_mul_f32 v[110:111], v[174:175], v[30:31] op_sel:[1,1] op_sel_hi:[0,1]
	v_pk_fma_f32 v[174:175], v[174:175], v[30:31], v[110:111] op_sel_hi:[1,0,1] neg_hi:[0,0,1]
	s_waitcnt lgkmcnt(7)
	v_pk_mul_f32 v[102:103], v[104:105], v[8:9] op_sel:[1,1] op_sel_hi:[0,1]
	v_pk_fma_f32 v[104:105], v[104:105], v[8:9], v[102:103] op_sel_hi:[1,0,1] neg_hi:[0,0,1]
	s_waitcnt lgkmcnt(6)
	v_pk_mul_f32 v[184:185], v[112:113], v[16:17] op_sel:[1,1] op_sel_hi:[0,1]
	v_pk_fma_f32 v[112:113], v[112:113], v[16:17], v[184:185] op_sel_hi:[1,0,1] neg_hi:[0,0,1]
	s_waitcnt lgkmcnt(5)
	v_pk_mul_f32 v[186:187], v[120:121], v[24:25] op_sel:[1,1] op_sel_hi:[0,1]
	v_pk_fma_f32 v[120:121], v[120:121], v[24:25], v[186:187] op_sel_hi:[1,0,1] neg_hi:[0,0,1]
	s_waitcnt lgkmcnt(4)
	v_pk_mul_f32 v[188:189], v[128:129], v[32:33] op_sel:[1,1] op_sel_hi:[0,1]
	v_pk_fma_f32 v[128:129], v[128:129], v[32:33], v[188:189] op_sel_hi:[1,0,1] neg_hi:[0,0,1]
	s_waitcnt lgkmcnt(3)
	v_pk_mul_f32 v[168:169], v[106:107], v[10:11] op_sel:[1,1] op_sel_hi:[0,1]
	v_pk_fma_f32 v[106:107], v[106:107], v[10:11], v[168:169] op_sel_hi:[1,0,1] neg_hi:[0,0,1]
	s_waitcnt lgkmcnt(2)
	v_pk_mul_f32 v[180:181], v[114:115], v[18:19] op_sel:[1,1] op_sel_hi:[0,1]
	v_pk_fma_f32 v[114:115], v[114:115], v[18:19], v[180:181] op_sel_hi:[1,0,1] neg_hi:[0,0,1]
	s_waitcnt lgkmcnt(1)
	v_pk_mul_f32 v[126:127], v[122:123], v[26:27] op_sel:[1,1] op_sel_hi:[0,1]
	v_pk_fma_f32 v[122:123], v[122:123], v[26:27], v[126:127] op_sel_hi:[1,0,1] neg_hi:[0,0,1]
	s_waitcnt lgkmcnt(0)
	v_pk_mul_f32 v[118:119], v[130:131], v[34:35] op_sel:[1,1] op_sel_hi:[0,1]
	v_pk_fma_f32 v[130:131], v[130:131], v[34:35], v[118:119] op_sel_hi:[1,0,1] neg_hi:[0,0,1]
	v_pk_add_f32 v[182:183], v[100:101], v[116:117]
	v_pk_add_f32 v[110:111], v[100:101], v[116:117] neg_lo:[0,1] neg_hi:[0,1]
	v_pk_add_f32 v[102:103], v[108:109], v[124:125]
	v_pk_add_f32 v[184:185], v[108:109], v[124:125] neg_lo:[0,1] neg_hi:[0,1]
	v_pk_add_f32 v[100:101], v[182:183], v[102:103]
	v_pk_add_f32 v[116:117], v[182:183], v[102:103] neg_lo:[0,1] neg_hi:[0,1]
	v_pk_add_f32 v[108:109], v[110:111], v[184:185] op_sel:[0,1] op_sel_hi:[1,0] neg_lo:[0,1]
	v_pk_add_f32 v[124:125], v[110:111], v[184:185] op_sel:[0,1] op_sel_hi:[1,0] neg_hi:[0,1]
	v_pk_add_f32 v[186:187], v[178:179], v[166:167]
	v_pk_add_f32 v[188:189], v[178:179], v[166:167] neg_lo:[0,1] neg_hi:[0,1]
	v_pk_add_f32 v[168:169], v[176:177], v[174:175]
	v_pk_add_f32 v[180:181], v[176:177], v[174:175] neg_lo:[0,1] neg_hi:[0,1]
	v_pk_add_f32 v[178:179], v[186:187], v[168:169]
	v_pk_add_f32 v[166:167], v[186:187], v[168:169] neg_lo:[0,1] neg_hi:[0,1]
	v_pk_add_f32 v[176:177], v[188:189], v[180:181] op_sel:[0,1] op_sel_hi:[1,0] neg_lo:[0,1]
	v_pk_add_f32 v[174:175], v[188:189], v[180:181] op_sel:[0,1] op_sel_hi:[1,0] neg_hi:[0,1]
	v_pk_add_f32 v[126:127], v[104:105], v[120:121]
	v_pk_add_f32 v[118:119], v[104:105], v[120:121] neg_lo:[0,1] neg_hi:[0,1]
	v_pk_add_f32 v[182:183], v[112:113], v[128:129]
	v_pk_add_f32 v[110:111], v[112:113], v[128:129] neg_lo:[0,1] neg_hi:[0,1]
	v_pk_add_f32 v[104:105], v[126:127], v[182:183]
	v_pk_add_f32 v[120:121], v[126:127], v[182:183] neg_lo:[0,1] neg_hi:[0,1]
	v_pk_add_f32 v[112:113], v[118:119], v[110:111] op_sel:[0,1] op_sel_hi:[1,0] neg_lo:[0,1]
	v_pk_add_f32 v[128:129], v[118:119], v[110:111] op_sel:[0,1] op_sel_hi:[1,0] neg_hi:[0,1]
	v_pk_add_f32 v[102:103], v[106:107], v[122:123]
	v_pk_add_f32 v[184:185], v[106:107], v[122:123] neg_lo:[0,1] neg_hi:[0,1]
	v_pk_add_f32 v[186:187], v[114:115], v[130:131]
	v_pk_add_f32 v[188:189], v[114:115], v[130:131] neg_lo:[0,1] neg_hi:[0,1]
	v_pk_add_f32 v[106:107], v[102:103], v[186:187]
	v_pk_add_f32 v[122:123], v[102:103], v[186:187] neg_lo:[0,1] neg_hi:[0,1]
	v_pk_add_f32 v[114:115], v[184:185], v[188:189] op_sel:[0,1] op_sel_hi:[1,0] neg_lo:[0,1]
; __device__ __forceinline__ f32x2 cmulc(f32x2 a, f32x2 b) { return (f32x2){a.x * b.x + a.y * b.y, a.y * b.x - a.x * b.y}; }
; #define WG_SYNC() do { asm volatile("s_waitcnt lgkmcnt(0)" ::: "memory"); __builtin_amdgcn_s_barrier(); asm volatile("" ::: "memory"); } while (0)
; __device__ __forceinline__ void dft16_inv_lo(f32x2 (&x)[16]) {
;     constexpr float C1 = 0.92387953251128674f, S1 = 0.38268343236508977f, C2 = 0.70710678118654752f;
; #pragma unroll
;     for (int b = 0; b < 4; ++b) dft4<true>(x[b], x[4 + b], x[8 + b], x[12 + b]);
;     const f32x2 w1 = {C1, -S1}, w2 = {C2, -C2}, w3 = {S1, -C1}, w4 = {0.f, -1.f}, w6 = {-C2, -C2}, w9 = {-C1, S1};
;     x[5] = cmulc(x[5], w1); x[6] = cmulc(x[6], w2); x[7] = cmulc(x[7], w3);
;     x[9] = cmulc(x[9], w2); x[10] = cmulc(x[10], w4); x[11] = cmulc(x[11], w6);
;     x[13] = cmulc(x[13], w3); x[14] = cmulc(x[14], w6); x[15] = cmulc(x[15], w9);
;     f32x2 y[8];
; #pragma unroll
;     for (int c = 0; c < 4; ++c) { const f32x2 t0 = x[4 * c] + x[4 * c + 2], t1 = x[4 * c] - x[4 * c + 2], t2 = x[4 * c + 1] + x[4 * c + 3], t3 = x[4 * c + 1] - x[4 * c + 3];
;         y[c] = t0 + t2; y[4 + c] = t1 + (f32x2){-t3.y, t3.x}; }
; #pragma unroll
;     for (int k = 0; k < 8; ++k) x[k] = y[k];
; }
; __device__ __forceinline__ void hyena_fft(LAS unsigned char* lds, int layer, int G, const int wave_s) {
;     ...
;             { const float fb0 = fbias[c];
; #pragma unroll
;               for (int r = 0; r < 8; ++r) { uz[r][0] = ux[r][0] * (x[r].x + fb0 * uz[r][0]); uz[r][1] = ux[r][1] * (x[r].y + fb0 * uz[r][1]); } }
;             WG_SYNC();
;             hy_stage(pl0, PHY, (HY / 4) + unit, jc, tid);
;             WG_SYNC();
	v_pk_add_f32 v[130:131], v[184:185], v[188:189] op_sel:[0,1] op_sel_hi:[1,0] neg_hi:[0,1]
	v_pk_mul_f32 v[168:169], v[176:177], s[68:69] op_sel:[1,1] op_sel_hi:[0,1]
	v_pk_fma_f32 v[176:177], v[176:177], s[68:69], v[168:169] op_sel_hi:[1,0,1] neg_hi:[0,0,1]
	v_pk_mul_f32 v[180:181], v[112:113], s[84:85] op_sel:[1,1] op_sel_hi:[0,1]
	v_pk_fma_f32 v[112:113], v[112:113], s[84:85], v[180:181] op_sel_hi:[1,0,1] neg_hi:[0,0,1]
	v_pk_mul_f32 v[126:127], v[114:115], s[88:89] op_sel:[1,1] op_sel_hi:[0,1]
	v_pk_fma_f32 v[114:115], v[114:115], s[88:89], v[126:127] op_sel_hi:[1,0,1] neg_hi:[0,0,1]
	v_pk_mul_f32 v[118:119], v[166:167], s[84:85] op_sel:[1,1] op_sel_hi:[0,1]
	v_pk_fma_f32 v[166:167], v[166:167], s[84:85], v[118:119] op_sel_hi:[1,0,1] neg_hi:[0,0,1]
	v_pk_mul_f32 v[182:183], v[122:123], s[90:91] op_sel:[1,1] op_sel_hi:[0,1]
	v_pk_fma_f32 v[122:123], v[122:123], s[90:91], v[182:183] op_sel_hi:[1,0,1] neg_hi:[0,0,1]
	v_pk_mul_f32 v[110:111], v[174:175], s[88:89] op_sel:[1,1] op_sel_hi:[0,1]
	v_pk_fma_f32 v[174:175], v[174:175], s[88:89], v[110:111] op_sel_hi:[1,0,1] neg_hi:[0,0,1]
	v_pk_mul_f32 v[102:103], v[128:129], s[90:91] op_sel:[1,1] op_sel_hi:[0,1]
	v_pk_fma_f32 v[128:129], v[128:129], s[90:91], v[102:103] op_sel_hi:[1,0,1] neg_hi:[0,0,1]
	v_pk_mul_f32 v[184:185], v[130:131], s[98:99] op_sel:[1,1] op_sel_hi:[0,1]
	v_pk_fma_f32 v[130:131], v[130:131], s[98:99], v[184:185] op_sel_hi:[1,0,1] neg_hi:[0,0,1]
	v_pk_add_f32 v[186:187], v[100:101], v[104:105]
	v_pk_add_f32 v[188:189], v[100:101], v[104:105] neg_lo:[0,1] neg_hi:[0,1]
	v_pk_add_f32 v[168:169], v[178:179], v[106:107]
	v_pk_add_f32 v[180:181], v[178:179], v[106:107] neg_lo:[0,1] neg_hi:[0,1]
	v_pk_add_f32 v[100:101], v[186:187], v[168:169]
	v_pk_add_f32 v[178:179], v[188:189], v[180:181] op_sel:[0,1] op_sel_hi:[1,0] neg_lo:[0,1]
	v_pk_add_f32 v[126:127], v[108:109], v[112:113]
	v_pk_add_f32 v[118:119], v[108:109], v[112:113] neg_lo:[0,1] neg_hi:[0,1]
	v_pk_add_f32 v[182:183], v[176:177], v[114:115]
	v_pk_add_f32 v[110:111], v[176:177], v[114:115] neg_lo:[0,1] neg_hi:[0,1]
	v_pk_add_f32 v[108:109], v[126:127], v[182:183]
	v_pk_add_f32 v[176:177], v[118:119], v[110:111] op_sel:[0,1] op_sel_hi:[1,0] neg_lo:[0,1]
	v_pk_add_f32 v[102:103], v[116:117], v[120:121] op_sel:[0,1] op_sel_hi:[1,0] neg_lo:[0,1]
	v_pk_add_f32 v[184:185], v[116:117], v[120:121] op_sel:[0,1] op_sel_hi:[1,0] neg_hi:[0,1]
	v_pk_add_f32 v[186:187], v[166:167], v[122:123]
	v_pk_add_f32 v[188:189], v[166:167], v[122:123] neg_lo:[0,1] neg_hi:[0,1]
	v_pk_add_f32 v[116:117], v[102:103], v[186:187]
	v_pk_add_f32 v[166:167], v[184:185], v[188:189] op_sel:[0,1] op_sel_hi:[1,0] neg_lo:[0,1]
	v_pk_add_f32 v[168:169], v[124:125], v[128:129]
	v_pk_add_f32 v[180:181], v[124:125], v[128:129] neg_lo:[0,1] neg_hi:[0,1]
	v_pk_add_f32 v[126:127], v[174:175], v[130:131]
	v_pk_add_f32 v[118:119], v[174:175], v[130:131] neg_lo:[0,1] neg_hi:[0,1]
	v_pk_add_f32 v[124:125], v[168:169], v[126:127]
	v_pk_add_f32 v[174:175], v[180:181], v[118:119] op_sel:[0,1] op_sel_hi:[1,0] neg_lo:[0,1]
	s_load_dword s35, s[50:51], 0x0
	s_waitcnt lgkmcnt(0)
	v_mov_b32_e32 v194, s35
	v_pk_fma_f32 v[182:183], v[132:133], v[194:195], v[100:101] op_sel_hi:[1,0,1]
	v_pk_mul_f32 v[132:133], v[148:149], v[182:183]
	v_pk_fma_f32 v[110:111], v[134:135], v[194:195], v[108:109] op_sel_hi:[1,0,1]
	v_pk_mul_f32 v[134:135], v[150:151], v[110:111]
	v_pk_fma_f32 v[102:103], v[136:137], v[194:195], v[116:117] op_sel_hi:[1,0,1]
	v_pk_mul_f32 v[136:137], v[152:153], v[102:103]
	v_pk_fma_f32 v[184:185], v[138:139], v[194:195], v[124:125] op_sel_hi:[1,0,1]
	v_pk_mul_f32 v[138:139], v[154:155], v[184:185]
	v_pk_fma_f32 v[186:187], v[140:141], v[194:195], v[178:179] op_sel_hi:[1,0,1]
	v_pk_mul_f32 v[140:141], v[158:159], v[186:187]
	v_pk_fma_f32 v[188:189], v[142:143], v[194:195], v[176:177] op_sel_hi:[1,0,1]
	v_pk_mul_f32 v[142:143], v[160:161], v[188:189]
	v_pk_fma_f32 v[168:169], v[144:145], v[194:195], v[166:167] op_sel_hi:[1,0,1]
	v_pk_mul_f32 v[144:145], v[162:163], v[168:169]
	v_pk_fma_f32 v[180:181], v[146:147], v[194:195], v[174:175] op_sel_hi:[1,0,1]
	v_pk_mul_f32 v[146:147], v[164:165], v[180:181]
	s_waitcnt lgkmcnt(0)
	s_barrier
	s_cbranch_vccz .Lhfft_st7
	s_sleep 2
.Lhfft_st7:
	s_waitcnt vmcnt(7)
	v_perm_b32 v126, 0, v58, s15
	v_perm_b32 v127, 0, v60, s15
	ds_write_b64 v206, v[126:127]
	s_waitcnt vmcnt(6)
	v_perm_b32 v118, 0, v62, s15
	v_perm_b32 v119, 0, v64, s15
	ds_write_b64 v206, v[118:119] offset:4096
	s_waitcnt vmcnt(5)
	v_perm_b32 v182, 0, v66, s15
	v_perm_b32 v183, 0, v68, s15
	ds_write_b64 v206, v[182:183] offset:8192
	s_waitcnt vmcnt(4)
	v_perm_b32 v110, 0, v70, s15
	v_perm_b32 v111, 0, v72, s15
	ds_write_b64 v206, v[110:111] offset:12288
	s_waitcnt vmcnt(3)
	v_perm_b32 v102, 0, v74, s15
	v_perm_b32 v103, 0, v76, s15
	ds_write_b64 v206, v[102:103] offset:16384
	s_waitcnt vmcnt(2)
	v_perm_b32 v184, 0, v78, s15
	v_perm_b32 v185, 0, v80, s15
	ds_write_b64 v206, v[184:185] offset:20480
	s_waitcnt vmcnt(1)
	v_perm_b32 v186, 0, v82, s15
	v_perm_b32 v187, 0, v84, s15
	ds_write_b64 v206, v[186:187] offset:24576
	s_waitcnt vmcnt(0)
	v_perm_b32 v188, 0, v86, s15
	v_perm_b32 v189, 0, v88, s15
	ds_write_b64 v206, v[188:189] offset:28672
	s_waitcnt lgkmcnt(0)
	s_barrier
	s_cbranch_vccz .Lhfft_st8
	s_sleep 2
; #define LAS __attribute__((address_space(3)))
; #define WG_SYNC() do { asm volatile("s_waitcnt lgkmcnt(0)" ::: "memory"); __builtin_amdgcn_s_barrier(); asm volatile("" ::: "memory"); } while (0)
; __device__ __forceinline__ void hy_sconv(const LAS float* plane, float w0, float w1, float w2, float cb, int n2, float (&u)[8][2]) {
;     asm volatile("" : "+v"(n2));
; #pragma unroll
;     for (int r = 0; r < 8; ++r)
; #pragma unroll
;         for (int b = 0; b < 2; ++b) { const int t = n2 + 512 * r, row = b * SEQ + t;
;             float a = cb + w1 * plane[row];
;             if (t > 0) a += w0 * plane[row - 1];
;             if (t < SEQ - 1) a += w2 * plane[row + 1];
;             u[r][b] = a; }
; }
; __device__ __forceinline__ void hyena_fft(LAS unsigned char* lds, int layer, int G, const int wave_s) {
;     ...
;             hy_sconv(pl0, cw[HY + c], cw[3 * HY + HY + c], cw[6 * HY + HY + c], cb[HY + c], n2, ux);
;             WG_SYNC();
.Lhfft_st8:
	v_mov_b32_e32 v168, s17
	v_mov_b32_e32 v169, s23
	v_mov_b32_e32 v180, s25
	v_mov_b32_e32 v181, s26
	ds_read_b32 v126, v208
	ds_read_b32 v118, v210
	ds_read_b32 v182, v208 offset:4
	ds_read_b32 v127, v208 offset:16384
	ds_read_b32 v119, v210 offset:16384
	ds_read_b32 v183, v208 offset:16388
	ds_read_b32 v110, v208 offset:2048
	ds_read_b32 v102, v208 offset:2044
	ds_read_b32 v184, v208 offset:2052
	ds_read_b32 v111, v208 offset:18432
	ds_read_b32 v103, v208 offset:18428
	ds_read_b32 v185, v208 offset:18436
	s_waitcnt lgkmcnt(10)
	v_cndmask_b32_e64 v118, v118, 0, s[10:11]
	s_waitcnt lgkmcnt(7)
	v_cndmask_b32_e64 v119, v119, 0, s[10:11]
	v_pk_fma_f32 v[148:149], v[168:169], v[126:127], v[180:181] op_sel:[1,0,1]
	v_pk_fma_f32 v[148:149], v[168:169], v[118:119], v[148:149] op_sel_hi:[0,1,1]
	s_waitcnt lgkmcnt(6)
	v_pk_fma_f32 v[148:149], v[180:181], v[182:183], v[148:149] op_sel_hi:[0,1,1]
	s_waitcnt lgkmcnt(2)
	v_pk_fma_f32 v[150:151], v[168:169], v[110:111], v[180:181] op_sel:[1,0,1]
	s_waitcnt lgkmcnt(1)
	v_pk_fma_f32 v[150:151], v[168:169], v[102:103], v[150:151] op_sel_hi:[0,1,1]
	s_waitcnt lgkmcnt(0)
	v_pk_fma_f32 v[150:151], v[180:181], v[184:185], v[150:151] op_sel_hi:[0,1,1]
	ds_read_b32 v186, v208 offset:4096
	ds_read_b32 v188, v208 offset:4092
	ds_read_b32 v126, v208 offset:4100
	ds_read_b32 v187, v208 offset:20480
	ds_read_b32 v189, v208 offset:20476
	ds_read_b32 v127, v208 offset:20484
	ds_read_b32 v118, v208 offset:6144
	ds_read_b32 v182, v208 offset:6140
	ds_read_b32 v110, v208 offset:6148
	ds_read_b32 v119, v208 offset:22528
	ds_read_b32 v183, v208 offset:22524
	ds_read_b32 v111, v208 offset:22532
	s_waitcnt lgkmcnt(8)
	v_pk_fma_f32 v[152:153], v[168:169], v[186:187], v[180:181] op_sel:[1,0,1]
	s_waitcnt lgkmcnt(7)
	v_pk_fma_f32 v[152:153], v[168:169], v[188:189], v[152:153] op_sel_hi:[0,1,1]
	s_waitcnt lgkmcnt(6)
	v_pk_fma_f32 v[152:153], v[180:181], v[126:127], v[152:153] op_sel_hi:[0,1,1]
	s_waitcnt lgkmcnt(2)
	v_pk_fma_f32 v[154:155], v[168:169], v[118:119], v[180:181] op_sel:[1,0,1]
	s_waitcnt lgkmcnt(1)
	v_pk_fma_f32 v[154:155], v[168:169], v[182:183], v[154:155] op_sel_hi:[0,1,1]
	s_waitcnt lgkmcnt(0)
	v_pk_fma_f32 v[154:155], v[180:181], v[110:111], v[154:155] op_sel_hi:[0,1,1]
	ds_read_b32 v102, v208 offset:8192
	ds_read_b32 v184, v208 offset:8188
	ds_read_b32 v186, v208 offset:8196
	ds_read_b32 v103, v208 offset:24576
	ds_read_b32 v185, v208 offset:24572
	ds_read_b32 v187, v208 offset:24580
	ds_read_b32 v188, v208 offset:10240
	ds_read_b32 v126, v208 offset:10236
	ds_read_b32 v118, v208 offset:10244
	ds_read_b32 v189, v208 offset:26624
	ds_read_b32 v127, v208 offset:26620
	ds_read_b32 v119, v208 offset:26628
	s_waitcnt lgkmcnt(8)
	v_pk_fma_f32 v[158:159], v[168:169], v[102:103], v[180:181] op_sel:[1,0,1]
	s_waitcnt lgkmcnt(7)
	v_pk_fma_f32 v[158:159], v[168:169], v[184:185], v[158:159] op_sel_hi:[0,1,1]
	s_waitcnt lgkmcnt(6)
	v_pk_fma_f32 v[158:159], v[180:181], v[186:187], v[158:159] op_sel_hi:[0,1,1]
	s_waitcnt lgkmcnt(2)
	v_pk_fma_f32 v[160:161], v[168:169], v[188:189], v[180:181] op_sel:[1,0,1]
	s_waitcnt lgkmcnt(1)
	v_pk_fma_f32 v[160:161], v[168:169], v[126:127], v[160:161] op_sel_hi:[0,1,1]
	s_waitcnt lgkmcnt(0)
	v_pk_fma_f32 v[160:161], v[180:181], v[118:119], v[160:161] op_sel_hi:[0,1,1]
	ds_read_b32 v182, v208 offset:12288
	ds_read_b32 v110, v208 offset:12284
	ds_read_b32 v102, v208 offset:12292
	ds_read_b32 v183, v208 offset:28672
	ds_read_b32 v111, v208 offset:28668
	ds_read_b32 v103, v208 offset:28676
	ds_read_b32 v184, v208 offset:14336
	ds_read_b32 v186, v208 offset:14332
	ds_read_b32 v188, v208 offset:14340
	ds_read_b32 v185, v208 offset:30720
	ds_read_b32 v187, v208 offset:30716
	ds_read_b32 v189, v208 offset:30724
	s_waitcnt lgkmcnt(8)
	v_pk_fma_f32 v[162:163], v[168:169], v[182:183], v[180:181] op_sel:[1,0,1]
	s_waitcnt lgkmcnt(7)
	v_pk_fma_f32 v[162:163], v[168:169], v[110:111], v[162:163] op_sel_hi:[0,1,1]
	s_waitcnt lgkmcnt(6)
	v_pk_fma_f32 v[162:163], v[180:181], v[102:103], v[162:163] op_sel_hi:[0,1,1]
	s_waitcnt lgkmcnt(3)
	v_cndmask_b32_e64 v188, v188, 0, s[28:29]
	s_waitcnt lgkmcnt(0)
	v_cndmask_b32_e64 v189, v189, 0, s[28:29]
	v_pk_fma_f32 v[164:165], v[168:169], v[184:185], v[180:181] op_sel:[1,0,1]
	v_pk_fma_f32 v[164:165], v[168:169], v[186:187], v[164:165] op_sel_hi:[0,1,1]
	v_pk_fma_f32 v[164:165], v[180:181], v[188:189], v[164:165] op_sel_hi:[0,1,1]
	s_waitcnt lgkmcnt(0)
	s_barrier
	s_cbranch_vccz .Lhfft_st9
	s_sleep 2
; #define LAS __attribute__((address_space(3)))
; __device__ __forceinline__ f32x2 cmul(f32x2 a, f32x2 b) { return (f32x2){a.x * b.x - a.y * b.y, a.x * b.y + a.y * b.x}; }
; __device__ __forceinline__ void dft16_fwd_lo(f32x2 (&x)[16]) {
;     constexpr float C1 = 0.92387953251128674f, S1 = 0.38268343236508977f, C2 = 0.70710678118654752f;
; #pragma unroll
;     for (int b = 0; b < 4; ++b) { const f32x2 x0 = x[b], x1 = x[4 + b]; const f32x2 j1 = {x1.y, -x1.x};
;         x[b] = x0 + x1; x[4 + b] = x0 + j1; x[8 + b] = x0 - x1; x[12 + b] = x0 - j1; }
;     const f32x2 w1 = {C1, -S1}, w2 = {C2, -C2}, w3 = {S1, -C1}, w4 = {0.f, -1.f}, w6 = {-C2, -C2}, w9 = {-C1, S1};
;     x[5] = cmul(x[5], w1); x[6] = cmul(x[6], w2); x[7] = cmul(x[7], w3);
;     x[9] = cmul(x[9], w2); x[10] = cmul(x[10], w4); x[11] = cmul(x[11], w6);
;     x[13] = cmul(x[13], w3); x[14] = cmul(x[14], w6); x[15] = cmul(x[15], w9);
; #pragma unroll
;     for (int c = 0; c < 4; ++c) dft4<false>(x[4 * c], x[4 * c + 1], x[4 * c + 2], x[4 * c + 3]);
;     f32x2 y[16];
; #pragma unroll
;     for (int k = 0; k < 16; ++k) y[k] = x[4 * (k & 3) + (k >> 2)];
; #pragma unroll
;     for (int k = 0; k < 16; ++k) x[k] = y[k];
; }
; template <bool LO> __device__ __forceinline__ void fft_fwd1(f32x2 (&x)[16], LAS f32x2* B, int n2, const f32x2 (&w)[16]) {
;     asm volatile("" : "+v"(n2));
;     if (LO) dft16_fwd_lo(x); else dft16<false>(x);
;     B[fpad(n2)] = x[0];
; #pragma unroll
;     for (int k = 1; k < 16; ++k) B[fpad(512 * k + n2)] = cmul(x[k], w[k]);
.Lhfft_st9:
	v_pk_add_f32 v[104:105], v[132:133], v[140:141] neg_lo:[0,1] neg_hi:[0,1]
	v_pk_add_f32 v[106:107], v[132:133], v[140:141] op_sel:[0,1] op_sel_hi:[1,0] neg_lo:[0,1]
	v_pk_add_f32 v[126:127], v[132:133], v[140:141] op_sel:[0,1] op_sel_hi:[1,0] neg_hi:[0,1]
	v_pk_add_f32 v[100:101], v[132:133], v[140:141]
	v_pk_add_f32 v[112:113], v[134:135], v[142:143] neg_lo:[0,1] neg_hi:[0,1]
	v_pk_add_f32 v[114:115], v[134:135], v[142:143] op_sel:[0,1] op_sel_hi:[1,0] neg_lo:[0,1]
	v_pk_add_f32 v[118:119], v[134:135], v[142:143] op_sel:[0,1] op_sel_hi:[1,0] neg_hi:[0,1]
	v_pk_add_f32 v[108:109], v[134:135], v[142:143]
	v_pk_add_f32 v[120:121], v[136:137], v[144:145] neg_lo:[0,1] neg_hi:[0,1]
	v_pk_add_f32 v[122:123], v[136:137], v[144:145] op_sel:[0,1] op_sel_hi:[1,0] neg_lo:[0,1]
	v_pk_add_f32 v[182:183], v[136:137], v[144:145] op_sel:[0,1] op_sel_hi:[1,0] neg_hi:[0,1]
	v_pk_add_f32 v[116:117], v[136:137], v[144:145]
	v_pk_add_f32 v[128:129], v[138:139], v[146:147] neg_lo:[0,1] neg_hi:[0,1]
	v_pk_add_f32 v[130:131], v[138:139], v[146:147] op_sel:[0,1] op_sel_hi:[1,0] neg_lo:[0,1]
	v_pk_add_f32 v[110:111], v[138:139], v[146:147] op_sel:[0,1] op_sel_hi:[1,0] neg_hi:[0,1]
	v_pk_add_f32 v[124:125], v[138:139], v[146:147]
	v_pk_mul_f32 v[102:103], v[118:119], s[68:69] op_sel:[1,1] op_sel_hi:[0,1]
	v_pk_fma_f32 v[118:119], v[118:119], s[68:69], v[102:103] op_sel_hi:[1,0,1] neg_lo:[0,0,1]
	v_pk_mul_f32 v[184:185], v[182:183], s[84:85] op_sel:[1,1] op_sel_hi:[0,1]
	v_pk_fma_f32 v[182:183], v[182:183], s[84:85], v[184:185] op_sel_hi:[1,0,1] neg_lo:[0,0,1]
	v_pk_mul_f32 v[186:187], v[110:111], s[88:89] op_sel:[1,1] op_sel_hi:[0,1]
	v_pk_fma_f32 v[110:111], v[110:111], s[88:89], v[186:187] op_sel_hi:[1,0,1] neg_lo:[0,0,1]
	v_pk_mul_f32 v[188:189], v[112:113], s[84:85] op_sel:[1,1] op_sel_hi:[0,1]
	v_pk_fma_f32 v[112:113], v[112:113], s[84:85], v[188:189] op_sel_hi:[1,0,1] neg_lo:[0,0,1]
	v_pk_mul_f32 v[168:169], v[128:129], s[90:91] op_sel:[1,1] op_sel_hi:[0,1]
	v_pk_fma_f32 v[128:129], v[128:129], s[90:91], v[168:169] op_sel_hi:[1,0,1] neg_lo:[0,0,1]
	v_pk_mul_f32 v[180:181], v[114:115], s[88:89] op_sel:[1,1] op_sel_hi:[0,1]
	v_pk_fma_f32 v[114:115], v[114:115], s[88:89], v[180:181] op_sel_hi:[1,0,1] neg_lo:[0,0,1]
	v_pk_mul_f32 v[178:179], v[122:123], s[90:91] op_sel:[1,1] op_sel_hi:[0,1]
	v_pk_fma_f32 v[122:123], v[122:123], s[90:91], v[178:179] op_sel_hi:[1,0,1] neg_lo:[0,0,1]
	v_pk_mul_f32 v[176:177], v[130:131], s[98:99] op_sel:[1,1] op_sel_hi:[0,1]
	v_pk_fma_f32 v[130:131], v[130:131], s[98:99], v[176:177] op_sel_hi:[1,0,1] neg_lo:[0,0,1]
	v_pk_add_f32 v[166:167], v[100:101], v[116:117]
	v_pk_add_f32 v[174:175], v[100:101], v[116:117] neg_lo:[0,1] neg_hi:[0,1]
	v_pk_add_f32 v[102:103], v[108:109], v[124:125]
	v_pk_add_f32 v[184:185], v[108:109], v[124:125] neg_lo:[0,1] neg_hi:[0,1]
	v_pk_add_f32 v[100:101], v[166:167], v[102:103]
	v_pk_add_f32 v[116:117], v[166:167], v[102:103] neg_lo:[0,1] neg_hi:[0,1]
	v_pk_add_f32 v[108:109], v[174:175], v[184:185] op_sel:[0,1] op_sel_hi:[1,0] neg_hi:[0,1]
	v_pk_add_f32 v[124:125], v[174:175], v[184:185] op_sel:[0,1] op_sel_hi:[1,0] neg_lo:[0,1]
	v_pk_add_f32 v[186:187], v[126:127], v[182:183]
	v_pk_add_f32 v[188:189], v[126:127], v[182:183] neg_lo:[0,1] neg_hi:[0,1]
	v_pk_add_f32 v[168:169], v[118:119], v[110:111]
	v_pk_add_f32 v[180:181], v[118:119], v[110:111] neg_lo:[0,1] neg_hi:[0,1]
	v_pk_add_f32 v[126:127], v[186:187], v[168:169]
	v_pk_add_f32 v[182:183], v[186:187], v[168:169] neg_lo:[0,1] neg_hi:[0,1]
	v_pk_add_f32 v[118:119], v[188:189], v[180:181] op_sel:[0,1] op_sel_hi:[1,0] neg_hi:[0,1]
	v_pk_add_f32 v[110:111], v[188:189], v[180:181] op_sel:[0,1] op_sel_hi:[1,0] neg_lo:[0,1]
	v_pk_add_f32 v[178:179], v[104:105], v[120:121] op_sel:[0,1] op_sel_hi:[1,0] neg_hi:[0,1]
	v_pk_add_f32 v[176:177], v[104:105], v[120:121] op_sel:[0,1] op_sel_hi:[1,0] neg_lo:[0,1]
	v_pk_add_f32 v[166:167], v[112:113], v[128:129]
	v_pk_add_f32 v[174:175], v[112:113], v[128:129] neg_lo:[0,1] neg_hi:[0,1]
	v_pk_add_f32 v[104:105], v[178:179], v[166:167]
	v_pk_add_f32 v[120:121], v[178:179], v[166:167] neg_lo:[0,1] neg_hi:[0,1]
	v_pk_add_f32 v[112:113], v[176:177], v[174:175] op_sel:[0,1] op_sel_hi:[1,0] neg_hi:[0,1]
	v_pk_add_f32 v[128:129], v[176:177], v[174:175] op_sel:[0,1] op_sel_hi:[1,0] neg_lo:[0,1]
	v_pk_add_f32 v[102:103], v[106:107], v[122:123]
	v_pk_add_f32 v[184:185], v[106:107], v[122:123] neg_lo:[0,1] neg_hi:[0,1]
	v_pk_add_f32 v[186:187], v[114:115], v[130:131]
	v_pk_add_f32 v[188:189], v[114:115], v[130:131] neg_lo:[0,1] neg_hi:[0,1]
	v_pk_add_f32 v[106:107], v[102:103], v[186:187]
	v_pk_add_f32 v[122:123], v[102:103], v[186:187] neg_lo:[0,1] neg_hi:[0,1]
	v_pk_add_f32 v[114:115], v[184:185], v[188:189] op_sel:[0,1] op_sel_hi:[1,0] neg_hi:[0,1]
	v_pk_add_f32 v[130:131], v[184:185], v[188:189] op_sel:[0,1] op_sel_hi:[1,0] neg_lo:[0,1]
	ds_write_b64 v3, v[100:101]
	v_pk_mul_f32 v[180:181], v[126:127], v[6:7] op_sel:[1,1] op_sel_hi:[0,1]
	v_pk_fma_f32 v[168:169], v[126:127], v[6:7], v[180:181] op_sel_hi:[1,0,1] neg_lo:[0,0,1]
	ds_write_b64 v3, v[168:169] offset:4224
	v_pk_mul_f32 v[176:177], v[104:105], v[8:9] op_sel:[1,1] op_sel_hi:[0,1]
	v_pk_fma_f32 v[178:179], v[104:105], v[8:9], v[176:177] op_sel_hi:[1,0,1] neg_lo:[0,0,1]
	ds_write_b64 v3, v[178:179] offset:8448
	v_pk_mul_f32 v[174:175], v[106:107], v[10:11] op_sel:[1,1] op_sel_hi:[0,1]
	v_pk_fma_f32 v[166:167], v[106:107], v[10:11], v[174:175] op_sel_hi:[1,0,1] neg_lo:[0,0,1]
	ds_write_b64 v3, v[166:167] offset:12672
	v_pk_mul_f32 v[184:185], v[108:109], v[12:13] op_sel:[1,1] op_sel_hi:[0,1]
	v_pk_fma_f32 v[102:103], v[108:109], v[12:13], v[184:185] op_sel_hi:[1,0,1] neg_lo:[0,0,1]
; #define LAS __attribute__((address_space(3)))
; __device__ __forceinline__ f32x2 cmul(f32x2 a, f32x2 b) { return (f32x2){a.x * b.x - a.y * b.y, a.x * b.y + a.y * b.x}; }
; template <bool INV> __device__ __forceinline__ void dft16(f32x2 (&x)[16]) {
;     constexpr float C1 = 0.92387953251128674f, S1 = 0.38268343236508977f, C2 = 0.70710678118654752f;
; #pragma unroll
;     for (int b = 0; b < 4; ++b) dft4<INV>(x[b], x[4 + b], x[8 + b], x[12 + b]);
; template <bool LO> __device__ __forceinline__ void fft_fwd1(f32x2 (&x)[16], LAS f32x2* B, int n2, const f32x2 (&w)[16]) {
;     ...
;     if (LO) dft16_fwd_lo(x); else dft16<false>(x);
;     B[fpad(n2)] = x[0];
; #pragma unroll
;     for (int k = 1; k < 16; ++k) B[fpad(512 * k + n2)] = cmul(x[k], w[k]);
; }
; __device__ __forceinline__ void fft_fwd2(LAS f32x2* B, const LAS f32x2* TW2, int tid) {
;     asm volatile("" : "+v"(tid));
;     const int b = tid >> 5, n2 = tid & 31, base = 512 * b + n2; f32x2 x[16];
; #pragma unroll
;     for (int r = 0; r < 16; ++r) x[r] = B[fpad(base + 32 * r)];
;     dft16<false>(x);
	ds_write_b64 v3, v[102:103] offset:16896
	v_pk_mul_f32 v[188:189], v[118:119], v[14:15] op_sel:[1,1] op_sel_hi:[0,1]
	v_pk_fma_f32 v[186:187], v[118:119], v[14:15], v[188:189] op_sel_hi:[1,0,1] neg_lo:[0,0,1]
	ds_write_b64 v3, v[186:187] offset:21120
	v_pk_mul_f32 v[168:169], v[112:113], v[16:17] op_sel:[1,1] op_sel_hi:[0,1]
	v_pk_fma_f32 v[180:181], v[112:113], v[16:17], v[168:169] op_sel_hi:[1,0,1] neg_lo:[0,0,1]
	ds_write_b64 v3, v[180:181] offset:25344
	v_pk_mul_f32 v[178:179], v[114:115], v[18:19] op_sel:[1,1] op_sel_hi:[0,1]
	v_pk_fma_f32 v[176:177], v[114:115], v[18:19], v[178:179] op_sel_hi:[1,0,1] neg_lo:[0,0,1]
	ds_write_b64 v3, v[176:177] offset:29568
	v_pk_mul_f32 v[166:167], v[116:117], v[20:21] op_sel:[1,1] op_sel_hi:[0,1]
	v_pk_fma_f32 v[174:175], v[116:117], v[20:21], v[166:167] op_sel_hi:[1,0,1] neg_lo:[0,0,1]
	ds_write_b64 v3, v[174:175] offset:33792
	v_pk_mul_f32 v[102:103], v[182:183], v[22:23] op_sel:[1,1] op_sel_hi:[0,1]
	v_pk_fma_f32 v[184:185], v[182:183], v[22:23], v[102:103] op_sel_hi:[1,0,1] neg_lo:[0,0,1]
	ds_write_b64 v3, v[184:185] offset:38016
	v_pk_mul_f32 v[186:187], v[120:121], v[24:25] op_sel:[1,1] op_sel_hi:[0,1]
	v_pk_fma_f32 v[188:189], v[120:121], v[24:25], v[186:187] op_sel_hi:[1,0,1] neg_lo:[0,0,1]
	ds_write_b64 v3, v[188:189] offset:42240
	v_pk_mul_f32 v[180:181], v[122:123], v[26:27] op_sel:[1,1] op_sel_hi:[0,1]
	v_pk_fma_f32 v[168:169], v[122:123], v[26:27], v[180:181] op_sel_hi:[1,0,1] neg_lo:[0,0,1]
	ds_write_b64 v3, v[168:169] offset:46464
	v_pk_mul_f32 v[176:177], v[124:125], v[28:29] op_sel:[1,1] op_sel_hi:[0,1]
	v_pk_fma_f32 v[178:179], v[124:125], v[28:29], v[176:177] op_sel_hi:[1,0,1] neg_lo:[0,0,1]
	ds_write_b64 v3, v[178:179] offset:50688
	v_pk_mul_f32 v[174:175], v[110:111], v[30:31] op_sel:[1,1] op_sel_hi:[0,1]
	v_pk_fma_f32 v[166:167], v[110:111], v[30:31], v[174:175] op_sel_hi:[1,0,1] neg_lo:[0,0,1]
	ds_write_b64 v3, v[166:167] offset:54912
	v_pk_mul_f32 v[184:185], v[128:129], v[32:33] op_sel:[1,1] op_sel_hi:[0,1]
	v_pk_fma_f32 v[102:103], v[128:129], v[32:33], v[184:185] op_sel_hi:[1,0,1] neg_lo:[0,0,1]
	ds_write_b64 v3, v[102:103] offset:59136
	v_pk_mul_f32 v[188:189], v[130:131], v[34:35] op_sel:[1,1] op_sel_hi:[0,1]
	v_pk_fma_f32 v[186:187], v[130:131], v[34:35], v[188:189] op_sel_hi:[1,0,1] neg_lo:[0,0,1]
	ds_write_b64 v3, v[186:187] offset:63360
	s_waitcnt lgkmcnt(0)
	s_barrier
	s_cbranch_vccz .Lhfft_st10
	s_sleep 2
.Lhfft_st10:
	ds_read_b64 v[100:101], v5
	ds_read_b64 v[108:109], v5 offset:1056
	ds_read_b64 v[116:117], v5 offset:2112
	ds_read_b64 v[124:125], v5 offset:3168
	ds_read_b64 v[126:127], v5 offset:264
	ds_read_b64 v[118:119], v5 offset:1320
	ds_read_b64 v[182:183], v5 offset:2376
	ds_read_b64 v[110:111], v5 offset:3432
	ds_read_b64 v[104:105], v5 offset:528
	ds_read_b64 v[112:113], v5 offset:1584
	ds_read_b64 v[120:121], v5 offset:2640
	ds_read_b64 v[128:129], v5 offset:3696
	s_waitcnt lgkmcnt(8)
	ds_read_b64 v[106:107], v5 offset:792
	ds_read_b64 v[114:115], v5 offset:1848
	ds_read_b64 v[122:123], v5 offset:2904
	ds_read_b64 v[130:131], v5 offset:3960
	v_pk_add_f32 v[180:181], v[100:101], v[116:117]
	v_pk_add_f32 v[168:169], v[100:101], v[116:117] neg_lo:[0,1] neg_hi:[0,1]
	v_pk_add_f32 v[176:177], v[108:109], v[124:125]
	v_pk_add_f32 v[178:179], v[108:109], v[124:125] neg_lo:[0,1] neg_hi:[0,1]
	v_pk_add_f32 v[100:101], v[180:181], v[176:177]
	v_pk_add_f32 v[116:117], v[180:181], v[176:177] neg_lo:[0,1] neg_hi:[0,1]
	v_pk_add_f32 v[108:109], v[168:169], v[178:179] op_sel:[0,1] op_sel_hi:[1,0] neg_hi:[0,1]
	v_pk_add_f32 v[124:125], v[168:169], v[178:179] op_sel:[0,1] op_sel_hi:[1,0] neg_lo:[0,1]
	s_waitcnt lgkmcnt(9)
	v_pk_add_f32 v[174:175], v[126:127], v[182:183]
	v_pk_add_f32 v[166:167], v[126:127], v[182:183] neg_lo:[0,1] neg_hi:[0,1]
	s_waitcnt lgkmcnt(8)
	v_pk_add_f32 v[184:185], v[118:119], v[110:111]
	v_pk_add_f32 v[102:103], v[118:119], v[110:111] neg_lo:[0,1] neg_hi:[0,1]
	v_pk_add_f32 v[126:127], v[174:175], v[184:185]
	v_pk_add_f32 v[182:183], v[174:175], v[184:185] neg_lo:[0,1] neg_hi:[0,1]
	v_pk_add_f32 v[118:119], v[166:167], v[102:103] op_sel:[0,1] op_sel_hi:[1,0] neg_hi:[0,1]
	v_pk_add_f32 v[110:111], v[166:167], v[102:103] op_sel:[0,1] op_sel_hi:[1,0] neg_lo:[0,1]
	s_waitcnt lgkmcnt(5)
	v_pk_add_f32 v[188:189], v[104:105], v[120:121]
	v_pk_add_f32 v[186:187], v[104:105], v[120:121] neg_lo:[0,1] neg_hi:[0,1]
	s_waitcnt lgkmcnt(4)
	v_pk_add_f32 v[180:181], v[112:113], v[128:129]
	v_pk_add_f32 v[168:169], v[112:113], v[128:129] neg_lo:[0,1] neg_hi:[0,1]
	v_pk_add_f32 v[104:105], v[188:189], v[180:181]
	v_pk_add_f32 v[120:121], v[188:189], v[180:181] neg_lo:[0,1] neg_hi:[0,1]
	v_pk_add_f32 v[112:113], v[186:187], v[168:169] op_sel:[0,1] op_sel_hi:[1,0] neg_hi:[0,1]
	v_pk_add_f32 v[128:129], v[186:187], v[168:169] op_sel:[0,1] op_sel_hi:[1,0] neg_lo:[0,1]
	s_waitcnt lgkmcnt(1)
	v_pk_add_f32 v[176:177], v[106:107], v[122:123]
	v_pk_add_f32 v[178:179], v[106:107], v[122:123] neg_lo:[0,1] neg_hi:[0,1]
	s_waitcnt lgkmcnt(0)
; __device__ __forceinline__ f32x2 cmul(f32x2 a, f32x2 b) { return (f32x2){a.x * b.x - a.y * b.y, a.x * b.y + a.y * b.x}; }
; template <bool INV> __device__ __forceinline__ f32x2 cmul_tw(f32x2 a, f32x2 w) { return INV ? cmulc(a, w) : cmul(a, w); }
; template <bool INV> __device__ __forceinline__ void dft16(f32x2 (&x)[16]) {
;     ...
;     const f32x2 w1 = {C1, -S1}, w2 = {C2, -C2}, w3 = {S1, -C1}, w4 = {0.f, -1.f}, w6 = {-C2, -C2}, w9 = {-C1, S1};
;     x[4 * 1 + 1] = cmul_tw<INV>(x[5], w1); x[4 * 1 + 2] = cmul_tw<INV>(x[6], w2); x[4 * 1 + 3] = cmul_tw<INV>(x[7], w3);
;     x[4 * 2 + 1] = cmul_tw<INV>(x[9], w2); x[4 * 2 + 2] = cmul_tw<INV>(x[10], w4); x[4 * 2 + 3] = cmul_tw<INV>(x[11], w6);
;     x[4 * 3 + 1] = cmul_tw<INV>(x[13], w3); x[4 * 3 + 2] = cmul_tw<INV>(x[14], w6); x[4 * 3 + 3] = cmul_tw<INV>(x[15], w9);
; #pragma unroll
;     for (int c = 0; c < 4; ++c) dft4<INV>(x[4 * c], x[4 * c + 1], x[4 * c + 2], x[4 * c + 3]);
;     f32x2 y[16];
; #pragma unroll
;     for (int k = 0; k < 16; ++k) y[k] = x[4 * (k & 3) + (k >> 2)];
; #pragma unroll
;     for (int k = 0; k < 16; ++k) x[k] = y[k];
; __device__ __forceinline__ void fft_fwd2(LAS f32x2* B, const LAS f32x2* TW2, int tid) {
;     ...
;     dft16<false>(x);
;     B[fpad(base)] = x[0];
; #pragma unroll
;     for (int k = 1; k < 16; ++k) B[fpad(base + 32 * k)] = cmul(x[k], TW2[k * 32 + n2]);
; }
	v_pk_add_f32 v[174:175], v[114:115], v[130:131]
	v_pk_add_f32 v[166:167], v[114:115], v[130:131] neg_lo:[0,1] neg_hi:[0,1]
	v_pk_add_f32 v[106:107], v[176:177], v[174:175]
	v_pk_add_f32 v[122:123], v[176:177], v[174:175] neg_lo:[0,1] neg_hi:[0,1]
	v_pk_add_f32 v[114:115], v[178:179], v[166:167] op_sel:[0,1] op_sel_hi:[1,0] neg_hi:[0,1]
	v_pk_add_f32 v[130:131], v[178:179], v[166:167] op_sel:[0,1] op_sel_hi:[1,0] neg_lo:[0,1]
	v_pk_mul_f32 v[184:185], v[118:119], s[68:69] op_sel:[1,1] op_sel_hi:[0,1]
	v_pk_fma_f32 v[118:119], v[118:119], s[68:69], v[184:185] op_sel_hi:[1,0,1] neg_lo:[0,0,1]
	v_pk_mul_f32 v[102:103], v[112:113], s[84:85] op_sel:[1,1] op_sel_hi:[0,1]
	v_pk_fma_f32 v[112:113], v[112:113], s[84:85], v[102:103] op_sel_hi:[1,0,1] neg_lo:[0,0,1]
	v_pk_mul_f32 v[188:189], v[114:115], s[88:89] op_sel:[1,1] op_sel_hi:[0,1]
	v_pk_fma_f32 v[114:115], v[114:115], s[88:89], v[188:189] op_sel_hi:[1,0,1] neg_lo:[0,0,1]
	v_pk_mul_f32 v[186:187], v[182:183], s[84:85] op_sel:[1,1] op_sel_hi:[0,1]
	v_pk_fma_f32 v[182:183], v[182:183], s[84:85], v[186:187] op_sel_hi:[1,0,1] neg_lo:[0,0,1]
	v_pk_mul_f32 v[180:181], v[122:123], s[90:91] op_sel:[1,1] op_sel_hi:[0,1]
	v_pk_fma_f32 v[122:123], v[122:123], s[90:91], v[180:181] op_sel_hi:[1,0,1] neg_lo:[0,0,1]
	v_pk_mul_f32 v[168:169], v[110:111], s[88:89] op_sel:[1,1] op_sel_hi:[0,1]
	v_pk_fma_f32 v[110:111], v[110:111], s[88:89], v[168:169] op_sel_hi:[1,0,1] neg_lo:[0,0,1]
	v_pk_mul_f32 v[176:177], v[128:129], s[90:91] op_sel:[1,1] op_sel_hi:[0,1]
	v_pk_fma_f32 v[128:129], v[128:129], s[90:91], v[176:177] op_sel_hi:[1,0,1] neg_lo:[0,0,1]
	v_pk_mul_f32 v[178:179], v[130:131], s[98:99] op_sel:[1,1] op_sel_hi:[0,1]
	v_pk_fma_f32 v[130:131], v[130:131], s[98:99], v[178:179] op_sel_hi:[1,0,1] neg_lo:[0,0,1]
	v_pk_add_f32 v[174:175], v[100:101], v[104:105]
	v_pk_add_f32 v[166:167], v[100:101], v[104:105] neg_lo:[0,1] neg_hi:[0,1]
	v_pk_add_f32 v[184:185], v[126:127], v[106:107]
	v_pk_add_f32 v[102:103], v[126:127], v[106:107] neg_lo:[0,1] neg_hi:[0,1]
	v_pk_add_f32 v[100:101], v[174:175], v[184:185]
	v_pk_add_f32 v[104:105], v[174:175], v[184:185] neg_lo:[0,1] neg_hi:[0,1]
	v_pk_add_f32 v[126:127], v[166:167], v[102:103] op_sel:[0,1] op_sel_hi:[1,0] neg_hi:[0,1]
	v_pk_add_f32 v[106:107], v[166:167], v[102:103] op_sel:[0,1] op_sel_hi:[1,0] neg_lo:[0,1]
	v_pk_add_f32 v[188:189], v[108:109], v[112:113]
	v_pk_add_f32 v[186:187], v[108:109], v[112:113] neg_lo:[0,1] neg_hi:[0,1]
	v_pk_add_f32 v[180:181], v[118:119], v[114:115]
	v_pk_add_f32 v[168:169], v[118:119], v[114:115] neg_lo:[0,1] neg_hi:[0,1]
	v_pk_add_f32 v[108:109], v[188:189], v[180:181]
	v_pk_add_f32 v[112:113], v[188:189], v[180:181] neg_lo:[0,1] neg_hi:[0,1]
	v_pk_add_f32 v[118:119], v[186:187], v[168:169] op_sel:[0,1] op_sel_hi:[1,0] neg_hi:[0,1]
	v_pk_add_f32 v[114:115], v[186:187], v[168:169] op_sel:[0,1] op_sel_hi:[1,0] neg_lo:[0,1]
	v_pk_add_f32 v[176:177], v[116:117], v[120:121] op_sel:[0,1] op_sel_hi:[1,0] neg_hi:[0,1]
	v_pk_add_f32 v[178:179], v[116:117], v[120:121] op_sel:[0,1] op_sel_hi:[1,0] neg_lo:[0,1]
	v_pk_add_f32 v[174:175], v[182:183], v[122:123]
	v_pk_add_f32 v[166:167], v[182:183], v[122:123] neg_lo:[0,1] neg_hi:[0,1]
	v_pk_add_f32 v[116:117], v[176:177], v[174:175]
	v_pk_add_f32 v[120:121], v[176:177], v[174:175] neg_lo:[0,1] neg_hi:[0,1]
	v_pk_add_f32 v[182:183], v[178:179], v[166:167] op_sel:[0,1] op_sel_hi:[1,0] neg_hi:[0,1]
	v_pk_add_f32 v[122:123], v[178:179], v[166:167] op_sel:[0,1] op_sel_hi:[1,0] neg_lo:[0,1]
	v_pk_add_f32 v[184:185], v[124:125], v[128:129]
	v_pk_add_f32 v[102:103], v[124:125], v[128:129] neg_lo:[0,1] neg_hi:[0,1]
	v_pk_add_f32 v[188:189], v[110:111], v[130:131]
	v_pk_add_f32 v[186:187], v[110:111], v[130:131] neg_lo:[0,1] neg_hi:[0,1]
	v_pk_add_f32 v[124:125], v[184:185], v[188:189]
	v_pk_add_f32 v[128:129], v[184:185], v[188:189] neg_lo:[0,1] neg_hi:[0,1]
	v_pk_add_f32 v[110:111], v[102:103], v[186:187] op_sel:[0,1] op_sel_hi:[1,0] neg_hi:[0,1]
	v_pk_add_f32 v[130:131], v[102:103], v[186:187] op_sel:[0,1] op_sel_hi:[1,0] neg_lo:[0,1]
	ds_write_b64 v5, v[100:101]
	ds_read_b64 v[180:181], v56 offset:256
	ds_read_b64 v[168:169], v56 offset:512
	ds_read_b64 v[176:177], v56 offset:768
	ds_read_b64 v[178:179], v56 offset:1024
	s_waitcnt lgkmcnt(3)
	v_pk_mul_f32 v[174:175], v[108:109], v[180:181] op_sel:[1,1] op_sel_hi:[0,1]
	v_pk_fma_f32 v[108:109], v[108:109], v[180:181], v[174:175] op_sel_hi:[1,0,1] neg_lo:[0,0,1]
	ds_write_b64 v5, v[108:109] offset:264
	s_waitcnt lgkmcnt(3)
	v_pk_mul_f32 v[166:167], v[116:117], v[168:169] op_sel:[1,1] op_sel_hi:[0,1]
	v_pk_fma_f32 v[116:117], v[116:117], v[168:169], v[166:167] op_sel_hi:[1,0,1] neg_lo:[0,0,1]
	ds_write_b64 v5, v[116:117] offset:528
	s_waitcnt lgkmcnt(3)
	v_pk_mul_f32 v[184:185], v[124:125], v[176:177] op_sel:[1,1] op_sel_hi:[0,1]
	v_pk_fma_f32 v[124:125], v[124:125], v[176:177], v[184:185] op_sel_hi:[1,0,1] neg_lo:[0,0,1]
	ds_write_b64 v5, v[124:125] offset:792
	s_waitcnt lgkmcnt(3)
	v_pk_mul_f32 v[102:103], v[126:127], v[178:179] op_sel:[1,1] op_sel_hi:[0,1]
	v_pk_fma_f32 v[126:127], v[126:127], v[178:179], v[102:103] op_sel_hi:[1,0,1] neg_lo:[0,0,1]
	ds_write_b64 v5, v[126:127] offset:1056
	ds_read_b64 v[188:189], v56 offset:1280
	ds_read_b64 v[186:187], v56 offset:1536
	ds_read_b64 v[174:175], v56 offset:1792
	ds_read_b64 v[166:167], v56 offset:2048
	s_waitcnt lgkmcnt(3)
	v_pk_mul_f32 v[184:185], v[118:119], v[188:189] op_sel:[1,1] op_sel_hi:[0,1]
	v_pk_fma_f32 v[118:119], v[118:119], v[188:189], v[184:185] op_sel_hi:[1,0,1] neg_lo:[0,0,1]
	ds_write_b64 v5, v[118:119] offset:1320
	s_waitcnt lgkmcnt(3)
; #define LAS __attribute__((address_space(3)))
; __device__ __forceinline__ f32x2 cmul(f32x2 a, f32x2 b) { return (f32x2){a.x * b.x - a.y * b.y, a.x * b.y + a.y * b.x}; }
; __device__ __forceinline__ void fft_fwd2(LAS f32x2* B, const LAS f32x2* TW2, int tid) {
;     ...
;     B[fpad(base)] = x[0];
; #pragma unroll
;     for (int k = 1; k < 16; ++k) B[fpad(base + 32 * k)] = cmul(x[k], TW2[k * 32 + n2]);
; }
; template <int MODE> __device__ __forceinline__ void fft_pair32(LAS f32x2* B, const LAS f32x2* F, int wave, int lane) {
;     ...
;     const int hi = lane >> 5, blk = 32 * wave + (lane & 31); const float sg = hi ? -1.f : 1.f;
;     LAS f32x2* p = B + 33 * blk; f32x2 v[16];
; #pragma unroll
;     for (int j = 0; j < 16; ++j) { const f32x2 d = p[j] + p[j + 16] * sg;
;         const f32x2 w = {hi ? CS[j] : 1.f, hi ? -SN[j] : 0.f}; v[j] = j == 0 ? d : cmul(d, w); }
;     dft16<false>(v);
	v_pk_mul_f32 v[102:103], v[182:183], v[186:187] op_sel:[1,1] op_sel_hi:[0,1]
	v_pk_fma_f32 v[182:183], v[182:183], v[186:187], v[102:103] op_sel_hi:[1,0,1] neg_lo:[0,0,1]
	ds_write_b64 v5, v[182:183] offset:1584
	s_waitcnt lgkmcnt(3)
	v_pk_mul_f32 v[180:181], v[110:111], v[174:175] op_sel:[1,1] op_sel_hi:[0,1]
	v_pk_fma_f32 v[110:111], v[110:111], v[174:175], v[180:181] op_sel_hi:[1,0,1] neg_lo:[0,0,1]
	ds_write_b64 v5, v[110:111] offset:1848
	s_waitcnt lgkmcnt(3)
	v_pk_mul_f32 v[168:169], v[104:105], v[166:167] op_sel:[1,1] op_sel_hi:[0,1]
	v_pk_fma_f32 v[104:105], v[104:105], v[166:167], v[168:169] op_sel_hi:[1,0,1] neg_lo:[0,0,1]
	ds_write_b64 v5, v[104:105] offset:2112
	ds_read_b64 v[176:177], v56 offset:2304
	ds_read_b64 v[178:179], v56 offset:2560
	ds_read_b64 v[184:185], v56 offset:2816
	ds_read_b64 v[102:103], v56 offset:3072
	s_waitcnt lgkmcnt(3)
	v_pk_mul_f32 v[180:181], v[112:113], v[176:177] op_sel:[1,1] op_sel_hi:[0,1]
	v_pk_fma_f32 v[112:113], v[112:113], v[176:177], v[180:181] op_sel_hi:[1,0,1] neg_lo:[0,0,1]
	ds_write_b64 v5, v[112:113] offset:2376
	s_waitcnt lgkmcnt(3)
	v_pk_mul_f32 v[168:169], v[120:121], v[178:179] op_sel:[1,1] op_sel_hi:[0,1]
	v_pk_fma_f32 v[120:121], v[120:121], v[178:179], v[168:169] op_sel_hi:[1,0,1] neg_lo:[0,0,1]
	ds_write_b64 v5, v[120:121] offset:2640
	s_waitcnt lgkmcnt(3)
	v_pk_mul_f32 v[188:189], v[128:129], v[184:185] op_sel:[1,1] op_sel_hi:[0,1]
	v_pk_fma_f32 v[128:129], v[128:129], v[184:185], v[188:189] op_sel_hi:[1,0,1] neg_lo:[0,0,1]
	ds_write_b64 v5, v[128:129] offset:2904
	s_waitcnt lgkmcnt(3)
	v_pk_mul_f32 v[186:187], v[106:107], v[102:103] op_sel:[1,1] op_sel_hi:[0,1]
	v_pk_fma_f32 v[106:107], v[106:107], v[102:103], v[186:187] op_sel_hi:[1,0,1] neg_lo:[0,0,1]
	ds_write_b64 v5, v[106:107] offset:3168
	ds_read_b64 v[174:175], v56 offset:3328
	ds_read_b64 v[166:167], v56 offset:3584
	ds_read_b64 v[180:181], v56 offset:3840
	s_waitcnt lgkmcnt(2)
	v_pk_mul_f32 v[168:169], v[114:115], v[174:175] op_sel:[1,1] op_sel_hi:[0,1]
	v_pk_fma_f32 v[114:115], v[114:115], v[174:175], v[168:169] op_sel_hi:[1,0,1] neg_lo:[0,0,1]
	ds_write_b64 v5, v[114:115] offset:3432
	s_waitcnt lgkmcnt(2)
	v_pk_mul_f32 v[188:189], v[122:123], v[166:167] op_sel:[1,1] op_sel_hi:[0,1]
	v_pk_fma_f32 v[122:123], v[122:123], v[166:167], v[188:189] op_sel_hi:[1,0,1] neg_lo:[0,0,1]
	ds_write_b64 v5, v[122:123] offset:3696
	s_waitcnt lgkmcnt(2)
	v_pk_mul_f32 v[186:187], v[130:131], v[180:181] op_sel:[1,1] op_sel_hi:[0,1]
	v_pk_fma_f32 v[130:131], v[130:131], v[180:181], v[186:187] op_sel_hi:[1,0,1] neg_lo:[0,0,1]
	ds_write_b64 v5, v[130:131] offset:3960
	s_waitcnt lgkmcnt(0)
	ds_read_b64 v[100:101], v156
	ds_read_b64 v[176:177], v156 offset:128
	ds_read_b64 v[108:109], v156 offset:8
	ds_read_b64 v[178:179], v156 offset:136
	ds_read_b64 v[116:117], v156 offset:16
	ds_read_b64 v[184:185], v156 offset:144
	ds_read_b64 v[124:125], v156 offset:24
	ds_read_b64 v[102:103], v156 offset:152
	s_waitcnt lgkmcnt(6)
	v_pk_fma_f32 v[100:101], v[176:177], v[190:191], v[100:101] op_sel_hi:[1,0,1]
	s_waitcnt lgkmcnt(4)
	v_pk_fma_f32 v[108:109], v[178:179], v[190:191], v[108:109] op_sel_hi:[1,0,1]
	v_pk_mul_f32 v[168:169], v[108:109], v[36:37] op_sel:[1,1] op_sel_hi:[0,1]
	v_pk_fma_f32 v[108:109], v[108:109], v[36:37], v[168:169] op_sel_hi:[1,0,1] neg_lo:[0,0,1]
	s_waitcnt lgkmcnt(2)
	v_pk_fma_f32 v[116:117], v[184:185], v[190:191], v[116:117] op_sel_hi:[1,0,1]
	v_pk_mul_f32 v[188:189], v[116:117], v[38:39] op_sel:[1,1] op_sel_hi:[0,1]
	v_pk_fma_f32 v[116:117], v[116:117], v[38:39], v[188:189] op_sel_hi:[1,0,1] neg_lo:[0,0,1]
	s_waitcnt lgkmcnt(0)
	v_pk_fma_f32 v[124:125], v[102:103], v[190:191], v[124:125] op_sel_hi:[1,0,1]
	v_pk_mul_f32 v[186:187], v[124:125], v[40:41] op_sel:[1,1] op_sel_hi:[0,1]
	v_pk_fma_f32 v[124:125], v[124:125], v[40:41], v[186:187] op_sel_hi:[1,0,1] neg_lo:[0,0,1]
	ds_read_b64 v[126:127], v156 offset:32
	ds_read_b64 v[174:175], v156 offset:160
	ds_read_b64 v[118:119], v156 offset:40
	ds_read_b64 v[166:167], v156 offset:168
	ds_read_b64 v[182:183], v156 offset:48
	ds_read_b64 v[180:181], v156 offset:176
	ds_read_b64 v[110:111], v156 offset:56
	ds_read_b64 v[168:169], v156 offset:184
	s_waitcnt lgkmcnt(6)
	v_pk_fma_f32 v[126:127], v[174:175], v[190:191], v[126:127] op_sel_hi:[1,0,1]
	v_pk_mul_f32 v[188:189], v[126:127], v[42:43] op_sel:[1,1] op_sel_hi:[0,1]
	v_pk_fma_f32 v[126:127], v[126:127], v[42:43], v[188:189] op_sel_hi:[1,0,1] neg_lo:[0,0,1]
	s_waitcnt lgkmcnt(4)
	v_pk_fma_f32 v[118:119], v[166:167], v[190:191], v[118:119] op_sel_hi:[1,0,1]
	v_pk_mul_f32 v[186:187], v[118:119], v[44:45] op_sel:[1,1] op_sel_hi:[0,1]
	v_pk_fma_f32 v[118:119], v[118:119], v[44:45], v[186:187] op_sel_hi:[1,0,1] neg_lo:[0,0,1]
	s_waitcnt lgkmcnt(2)
	v_pk_fma_f32 v[182:183], v[180:181], v[190:191], v[182:183] op_sel_hi:[1,0,1]
	v_pk_mul_f32 v[176:177], v[182:183], v[46:47] op_sel:[1,1] op_sel_hi:[0,1]
	v_pk_fma_f32 v[182:183], v[182:183], v[46:47], v[176:177] op_sel_hi:[1,0,1] neg_lo:[0,0,1]
	s_waitcnt lgkmcnt(0)
	v_pk_fma_f32 v[110:111], v[168:169], v[190:191], v[110:111] op_sel_hi:[1,0,1]
	v_pk_mul_f32 v[178:179], v[110:111], v[48:49] op_sel:[1,1] op_sel_hi:[0,1]
	v_pk_fma_f32 v[110:111], v[110:111], v[48:49], v[178:179] op_sel_hi:[1,0,1] neg_lo:[0,0,1]
	ds_read_b64 v[104:105], v156 offset:64
	ds_read_b64 v[184:185], v156 offset:192
	ds_read_b64 v[112:113], v156 offset:72
	ds_read_b64 v[102:103], v156 offset:200
	ds_read_b64 v[120:121], v156 offset:80
	ds_read_b64 v[188:189], v156 offset:208
	ds_read_b64 v[128:129], v156 offset:88
	ds_read_b64 v[186:187], v156 offset:216
	s_waitcnt lgkmcnt(6)
; #define LAS __attribute__((address_space(3)))
; __device__ __forceinline__ f32x2 cmul(f32x2 a, f32x2 b) { return (f32x2){a.x * b.x - a.y * b.y, a.x * b.y + a.y * b.x}; }
; template <bool INV> __device__ __forceinline__ f32x2 cmul_tw(f32x2 a, f32x2 w) { return INV ? cmulc(a, w) : cmul(a, w); }
; template <bool INV> __device__ __forceinline__ void dft16(f32x2 (&x)[16]) {
;     constexpr float C1 = 0.92387953251128674f, S1 = 0.38268343236508977f, C2 = 0.70710678118654752f;
; #pragma unroll
;     for (int b = 0; b < 4; ++b) dft4<INV>(x[b], x[4 + b], x[8 + b], x[12 + b]);
;     const f32x2 w1 = {C1, -S1}, w2 = {C2, -C2}, w3 = {S1, -C1}, w4 = {0.f, -1.f}, w6 = {-C2, -C2}, w9 = {-C1, S1};
;     x[4 * 1 + 1] = cmul_tw<INV>(x[5], w1); x[4 * 1 + 2] = cmul_tw<INV>(x[6], w2); x[4 * 1 + 3] = cmul_tw<INV>(x[7], w3);
;     x[4 * 2 + 1] = cmul_tw<INV>(x[9], w2); x[4 * 2 + 2] = cmul_tw<INV>(x[10], w4); x[4 * 2 + 3] = cmul_tw<INV>(x[11], w6);
;     x[4 * 3 + 1] = cmul_tw<INV>(x[13], w3); x[4 * 3 + 2] = cmul_tw<INV>(x[14], w6); x[4 * 3 + 3] = cmul_tw<INV>(x[15], w9);
; #pragma unroll
;     for (int c = 0; c < 4; ++c) dft4<INV>(x[4 * c], x[4 * c + 1], x[4 * c + 2], x[4 * c + 3]);
; template <int MODE> __device__ __forceinline__ void fft_pair32(LAS f32x2* B, const LAS f32x2* F, int wave, int lane) {
;     ...
;     const int hi = lane >> 5, blk = 32 * wave + (lane & 31); const float sg = hi ? -1.f : 1.f;
;     LAS f32x2* p = B + 33 * blk; f32x2 v[16];
; #pragma unroll
;     for (int j = 0; j < 16; ++j) { const f32x2 d = p[j] + p[j + 16] * sg;
;         const f32x2 w = {hi ? CS[j] : 1.f, hi ? -SN[j] : 0.f}; v[j] = j == 0 ? d : cmul(d, w); }
;     dft16<false>(v);
	v_pk_fma_f32 v[104:105], v[184:185], v[190:191], v[104:105] op_sel_hi:[1,0,1]
	v_pk_mul_f32 v[176:177], v[104:105], v[50:51] op_sel:[1,1] op_sel_hi:[0,1]
	v_pk_fma_f32 v[104:105], v[104:105], v[50:51], v[176:177] op_sel_hi:[1,0,1] neg_lo:[0,0,1]
	s_waitcnt lgkmcnt(4)
	v_pk_fma_f32 v[112:113], v[102:103], v[190:191], v[112:113] op_sel_hi:[1,0,1]
	v_pk_mul_f32 v[178:179], v[112:113], v[52:53] op_sel:[1,1] op_sel_hi:[0,1]
	v_pk_fma_f32 v[112:113], v[112:113], v[52:53], v[178:179] op_sel_hi:[1,0,1] neg_lo:[0,0,1]
	s_waitcnt lgkmcnt(2)
	v_pk_fma_f32 v[120:121], v[188:189], v[190:191], v[120:121] op_sel_hi:[1,0,1]
	v_pk_mul_f32 v[174:175], v[120:121], v[54:55] op_sel:[1,1] op_sel_hi:[0,1]
	v_pk_fma_f32 v[120:121], v[120:121], v[54:55], v[174:175] op_sel_hi:[1,0,1] neg_lo:[0,0,1]
	s_waitcnt lgkmcnt(0)
	v_pk_fma_f32 v[128:129], v[186:187], v[190:191], v[128:129] op_sel_hi:[1,0,1]
	v_pk_mul_f32 v[166:167], v[128:129], v[90:91] op_sel:[1,1] op_sel_hi:[0,1]
	v_pk_fma_f32 v[128:129], v[128:129], v[90:91], v[166:167] op_sel_hi:[1,0,1] neg_lo:[0,0,1]
	ds_read_b64 v[106:107], v156 offset:96
	ds_read_b64 v[180:181], v156 offset:224
	ds_read_b64 v[114:115], v156 offset:104
	ds_read_b64 v[168:169], v156 offset:232
	ds_read_b64 v[122:123], v156 offset:112
	ds_read_b64 v[176:177], v156 offset:240
	ds_read_b64 v[130:131], v156 offset:120
	ds_read_b64 v[178:179], v156 offset:248
	s_waitcnt lgkmcnt(6)
	v_pk_fma_f32 v[106:107], v[180:181], v[190:191], v[106:107] op_sel_hi:[1,0,1]
	v_pk_mul_f32 v[174:175], v[106:107], v[92:93] op_sel:[1,1] op_sel_hi:[0,1]
	v_pk_fma_f32 v[106:107], v[106:107], v[92:93], v[174:175] op_sel_hi:[1,0,1] neg_lo:[0,0,1]
	s_waitcnt lgkmcnt(4)
	v_pk_fma_f32 v[114:115], v[168:169], v[190:191], v[114:115] op_sel_hi:[1,0,1]
	v_pk_mul_f32 v[166:167], v[114:115], v[94:95] op_sel:[1,1] op_sel_hi:[0,1]
	v_pk_fma_f32 v[114:115], v[114:115], v[94:95], v[166:167] op_sel_hi:[1,0,1] neg_lo:[0,0,1]
	s_waitcnt lgkmcnt(2)
	v_pk_fma_f32 v[122:123], v[176:177], v[190:191], v[122:123] op_sel_hi:[1,0,1]
	v_pk_mul_f32 v[184:185], v[122:123], v[96:97] op_sel:[1,1] op_sel_hi:[0,1]
	v_pk_fma_f32 v[122:123], v[122:123], v[96:97], v[184:185] op_sel_hi:[1,0,1] neg_lo:[0,0,1]
	s_waitcnt lgkmcnt(0)
	v_pk_fma_f32 v[130:131], v[178:179], v[190:191], v[130:131] op_sel_hi:[1,0,1]
	v_pk_mul_f32 v[102:103], v[130:131], v[98:99] op_sel:[1,1] op_sel_hi:[0,1]
	v_pk_fma_f32 v[130:131], v[130:131], v[98:99], v[102:103] op_sel_hi:[1,0,1] neg_lo:[0,0,1]
	v_pk_add_f32 v[188:189], v[100:101], v[104:105]
	v_pk_add_f32 v[186:187], v[100:101], v[104:105] neg_lo:[0,1] neg_hi:[0,1]
	v_pk_add_f32 v[174:175], v[126:127], v[106:107]
	v_pk_add_f32 v[166:167], v[126:127], v[106:107] neg_lo:[0,1] neg_hi:[0,1]
	v_pk_add_f32 v[100:101], v[188:189], v[174:175]
	v_pk_add_f32 v[104:105], v[188:189], v[174:175] neg_lo:[0,1] neg_hi:[0,1]
	v_pk_add_f32 v[126:127], v[186:187], v[166:167] op_sel:[0,1] op_sel_hi:[1,0] neg_hi:[0,1]
	v_pk_add_f32 v[106:107], v[186:187], v[166:167] op_sel:[0,1] op_sel_hi:[1,0] neg_lo:[0,1]
	v_pk_add_f32 v[184:185], v[108:109], v[112:113]
	v_pk_add_f32 v[102:103], v[108:109], v[112:113] neg_lo:[0,1] neg_hi:[0,1]
	v_pk_add_f32 v[180:181], v[118:119], v[114:115]
	v_pk_add_f32 v[168:169], v[118:119], v[114:115] neg_lo:[0,1] neg_hi:[0,1]
	v_pk_add_f32 v[108:109], v[184:185], v[180:181]
	v_pk_add_f32 v[112:113], v[184:185], v[180:181] neg_lo:[0,1] neg_hi:[0,1]
	v_pk_add_f32 v[118:119], v[102:103], v[168:169] op_sel:[0,1] op_sel_hi:[1,0] neg_hi:[0,1]
	v_pk_add_f32 v[114:115], v[102:103], v[168:169] op_sel:[0,1] op_sel_hi:[1,0] neg_lo:[0,1]
	v_pk_add_f32 v[176:177], v[116:117], v[120:121]
	v_pk_add_f32 v[178:179], v[116:117], v[120:121] neg_lo:[0,1] neg_hi:[0,1]
	v_pk_add_f32 v[188:189], v[182:183], v[122:123]
	v_pk_add_f32 v[186:187], v[182:183], v[122:123] neg_lo:[0,1] neg_hi:[0,1]
	v_pk_add_f32 v[116:117], v[176:177], v[188:189]
	v_pk_add_f32 v[120:121], v[176:177], v[188:189] neg_lo:[0,1] neg_hi:[0,1]
	v_pk_add_f32 v[182:183], v[178:179], v[186:187] op_sel:[0,1] op_sel_hi:[1,0] neg_hi:[0,1]
	v_pk_add_f32 v[122:123], v[178:179], v[186:187] op_sel:[0,1] op_sel_hi:[1,0] neg_lo:[0,1]
	v_pk_add_f32 v[174:175], v[124:125], v[128:129]
	v_pk_add_f32 v[166:167], v[124:125], v[128:129] neg_lo:[0,1] neg_hi:[0,1]
	v_pk_add_f32 v[184:185], v[110:111], v[130:131]
	v_pk_add_f32 v[102:103], v[110:111], v[130:131] neg_lo:[0,1] neg_hi:[0,1]
	v_pk_add_f32 v[124:125], v[174:175], v[184:185]
	v_pk_add_f32 v[128:129], v[174:175], v[184:185] neg_lo:[0,1] neg_hi:[0,1]
	v_pk_add_f32 v[110:111], v[166:167], v[102:103] op_sel:[0,1] op_sel_hi:[1,0] neg_hi:[0,1]
	v_pk_add_f32 v[130:131], v[166:167], v[102:103] op_sel:[0,1] op_sel_hi:[1,0] neg_lo:[0,1]
	v_pk_mul_f32 v[180:181], v[118:119], s[68:69] op_sel:[1,1] op_sel_hi:[0,1]
	v_pk_fma_f32 v[118:119], v[118:119], s[68:69], v[180:181] op_sel_hi:[1,0,1] neg_lo:[0,0,1]
	v_pk_mul_f32 v[168:169], v[182:183], s[84:85] op_sel:[1,1] op_sel_hi:[0,1]
	v_pk_fma_f32 v[182:183], v[182:183], s[84:85], v[168:169] op_sel_hi:[1,0,1] neg_lo:[0,0,1]
	v_pk_mul_f32 v[176:177], v[110:111], s[88:89] op_sel:[1,1] op_sel_hi:[0,1]
	v_pk_fma_f32 v[110:111], v[110:111], s[88:89], v[176:177] op_sel_hi:[1,0,1] neg_lo:[0,0,1]
	v_pk_mul_f32 v[178:179], v[112:113], s[84:85] op_sel:[1,1] op_sel_hi:[0,1]
	v_pk_fma_f32 v[112:113], v[112:113], s[84:85], v[178:179] op_sel_hi:[1,0,1] neg_lo:[0,0,1]
	v_pk_mul_f32 v[188:189], v[128:129], s[90:91] op_sel:[1,1] op_sel_hi:[0,1]
	v_pk_fma_f32 v[128:129], v[128:129], s[90:91], v[188:189] op_sel_hi:[1,0,1] neg_lo:[0,0,1]
	v_pk_mul_f32 v[186:187], v[114:115], s[88:89] op_sel:[1,1] op_sel_hi:[0,1]
	v_pk_fma_f32 v[114:115], v[114:115], s[88:89], v[186:187] op_sel_hi:[1,0,1] neg_lo:[0,0,1]
; #define LAS __attribute__((address_space(3)))
; __device__ __forceinline__ f32x2 cmul(f32x2 a, f32x2 b) { return (f32x2){a.x * b.x - a.y * b.y, a.x * b.y + a.y * b.x}; }
; template <bool INV> __device__ __forceinline__ f32x2 cmul_tw(f32x2 a, f32x2 w) { return INV ? cmulc(a, w) : cmul(a, w); }
; template <bool INV> __device__ __forceinline__ void dft16(f32x2 (&x)[16]) {
;     constexpr float C1 = 0.92387953251128674f, S1 = 0.38268343236508977f, C2 = 0.70710678118654752f;
; #pragma unroll
;     for (int b = 0; b < 4; ++b) dft4<INV>(x[b], x[4 + b], x[8 + b], x[12 + b]);
;     const f32x2 w1 = {C1, -S1}, w2 = {C2, -C2}, w3 = {S1, -C1}, w4 = {0.f, -1.f}, w6 = {-C2, -C2}, w9 = {-C1, S1};
;     x[4 * 1 + 1] = cmul_tw<INV>(x[5], w1); x[4 * 1 + 2] = cmul_tw<INV>(x[6], w2); x[4 * 1 + 3] = cmul_tw<INV>(x[7], w3);
;     x[4 * 2 + 1] = cmul_tw<INV>(x[9], w2); x[4 * 2 + 2] = cmul_tw<INV>(x[10], w4); x[4 * 2 + 3] = cmul_tw<INV>(x[11], w6);
;     x[4 * 3 + 1] = cmul_tw<INV>(x[13], w3); x[4 * 3 + 2] = cmul_tw<INV>(x[14], w6); x[4 * 3 + 3] = cmul_tw<INV>(x[15], w9);
; #pragma unroll
;     for (int c = 0; c < 4; ++c) dft4<INV>(x[4 * c], x[4 * c + 1], x[4 * c + 2], x[4 * c + 3]);
;     f32x2 y[16];
; #pragma unroll
;     for (int k = 0; k < 16; ++k) y[k] = x[4 * (k & 3) + (k >> 2)];
; #pragma unroll
;     for (int k = 0; k < 16; ++k) x[k] = y[k];
; template <int MODE> __device__ __forceinline__ void fft_pair32(LAS f32x2* B, const LAS f32x2* F, int wave, int lane) {
;     ...
;     const int k1 = blk >> 4, k2 = blk & 15, kb1 = (16 - k1) & 15, b1 = k1 != 0 ? 1 : 0, kb2 = (16 - k2 - b1) & 15, b2 = (k2 != 0 || b1) ? 1 : 0;
;     const LAS f32x2* fa = F + 33 * blk; const LAS f32x2* fb = F + 33 * (16 * kb1 + kb2);
;     const LAS f32x2* fah = fa + hi; const LAS f32x2* fbh = fb + (1 - b2) - hi;
;     constexpr float SC = 1.0f / (2.0f * (float)FN);
; #pragma unroll
;     for (int k = 0; k < 16; ++k) { const f32x2 A = fah[2 * k]; f32x2 Bm = fbh[31 - 2 * k];
;         if (k == 0) { const f32x2 m0 = b2 ? fb[31] : fa[0]; Bm = hi ? Bm : m0; }
;         const f32x2 H = MODE == 0 ? (f32x2){(A.x + Bm.x) * SC, (A.y - Bm.y) * SC} : (f32x2){(A.y + Bm.y) * SC, (Bm.x - A.x) * SC};
;         v[k] = cmul(v[k], H); }
	v_pk_mul_f32 v[174:175], v[122:123], s[90:91] op_sel:[1,1] op_sel_hi:[0,1]
	v_pk_fma_f32 v[122:123], v[122:123], s[90:91], v[174:175] op_sel_hi:[1,0,1] neg_lo:[0,0,1]
	v_pk_mul_f32 v[166:167], v[130:131], s[98:99] op_sel:[1,1] op_sel_hi:[0,1]
	v_pk_fma_f32 v[130:131], v[130:131], s[98:99], v[166:167] op_sel_hi:[1,0,1] neg_lo:[0,0,1]
	v_pk_add_f32 v[184:185], v[100:101], v[116:117]
	v_pk_add_f32 v[102:103], v[100:101], v[116:117] neg_lo:[0,1] neg_hi:[0,1]
	v_pk_add_f32 v[180:181], v[108:109], v[124:125]
	v_pk_add_f32 v[168:169], v[108:109], v[124:125] neg_lo:[0,1] neg_hi:[0,1]
	v_pk_add_f32 v[100:101], v[184:185], v[180:181]
	v_pk_add_f32 v[116:117], v[184:185], v[180:181] neg_lo:[0,1] neg_hi:[0,1]
	v_pk_add_f32 v[108:109], v[102:103], v[168:169] op_sel:[0,1] op_sel_hi:[1,0] neg_hi:[0,1]
	v_pk_add_f32 v[124:125], v[102:103], v[168:169] op_sel:[0,1] op_sel_hi:[1,0] neg_lo:[0,1]
	v_pk_add_f32 v[176:177], v[126:127], v[182:183]
	v_pk_add_f32 v[178:179], v[126:127], v[182:183] neg_lo:[0,1] neg_hi:[0,1]
	v_pk_add_f32 v[188:189], v[118:119], v[110:111]
	v_pk_add_f32 v[186:187], v[118:119], v[110:111] neg_lo:[0,1] neg_hi:[0,1]
	v_pk_add_f32 v[126:127], v[176:177], v[188:189]
	v_pk_add_f32 v[182:183], v[176:177], v[188:189] neg_lo:[0,1] neg_hi:[0,1]
	v_pk_add_f32 v[118:119], v[178:179], v[186:187] op_sel:[0,1] op_sel_hi:[1,0] neg_hi:[0,1]
	v_pk_add_f32 v[110:111], v[178:179], v[186:187] op_sel:[0,1] op_sel_hi:[1,0] neg_lo:[0,1]
	v_pk_add_f32 v[174:175], v[104:105], v[120:121] op_sel:[0,1] op_sel_hi:[1,0] neg_hi:[0,1]
	v_pk_add_f32 v[166:167], v[104:105], v[120:121] op_sel:[0,1] op_sel_hi:[1,0] neg_lo:[0,1]
	v_pk_add_f32 v[184:185], v[112:113], v[128:129]
	v_pk_add_f32 v[102:103], v[112:113], v[128:129] neg_lo:[0,1] neg_hi:[0,1]
	v_pk_add_f32 v[104:105], v[174:175], v[184:185]
	v_pk_add_f32 v[120:121], v[174:175], v[184:185] neg_lo:[0,1] neg_hi:[0,1]
	v_pk_add_f32 v[112:113], v[166:167], v[102:103] op_sel:[0,1] op_sel_hi:[1,0] neg_hi:[0,1]
	v_pk_add_f32 v[128:129], v[166:167], v[102:103] op_sel:[0,1] op_sel_hi:[1,0] neg_lo:[0,1]
	v_pk_add_f32 v[180:181], v[106:107], v[122:123]
	v_pk_add_f32 v[168:169], v[106:107], v[122:123] neg_lo:[0,1] neg_hi:[0,1]
	v_pk_add_f32 v[176:177], v[114:115], v[130:131]
	v_pk_add_f32 v[178:179], v[114:115], v[130:131] neg_lo:[0,1] neg_hi:[0,1]
	v_pk_add_f32 v[106:107], v[180:181], v[176:177]
	v_pk_add_f32 v[122:123], v[180:181], v[176:177] neg_lo:[0,1] neg_hi:[0,1]
	v_pk_add_f32 v[114:115], v[168:169], v[178:179] op_sel:[0,1] op_sel_hi:[1,0] neg_hi:[0,1]
	v_pk_add_f32 v[130:131], v[168:169], v[178:179] op_sel:[0,1] op_sel_hi:[1,0] neg_lo:[0,1]
	ds_read_b64 v[188:189], v200
	ds_read_b64 v[184:185], v204
	ds_read_b64 v[186:187], v200 offset:16
	ds_read_b64 v[102:103], v202 offset:232
	ds_read_b64 v[174:175], v200 offset:32
	ds_read_b64 v[180:181], v202 offset:216
	ds_read_b64 v[166:167], v200 offset:48
	ds_read_b64 v[168:169], v202 offset:200
	s_waitcnt lgkmcnt(6)
	v_pk_add_f32 v[188:189], v[188:189], v[184:185] op_sel:[1,1] op_sel_hi:[0,0] neg_hi:[1,0]
	v_pk_mul_f32 v[176:177], v[100:101], v[188:189] op_sel:[1,1] op_sel_hi:[0,1]
	v_pk_fma_f32 v[100:101], v[100:101], v[188:189], v[176:177] op_sel_hi:[1,0,1] neg_lo:[0,0,1]
	s_waitcnt lgkmcnt(4)
	v_pk_add_f32 v[186:187], v[186:187], v[102:103] op_sel:[1,1] op_sel_hi:[0,0] neg_hi:[1,0]
	v_pk_mul_f32 v[178:179], v[126:127], v[186:187] op_sel:[1,1] op_sel_hi:[0,1]
	v_pk_fma_f32 v[126:127], v[126:127], v[186:187], v[178:179] op_sel_hi:[1,0,1] neg_lo:[0,0,1]
	s_waitcnt lgkmcnt(2)
	v_pk_add_f32 v[174:175], v[174:175], v[180:181] op_sel:[1,1] op_sel_hi:[0,0] neg_hi:[1,0]
	v_pk_mul_f32 v[176:177], v[104:105], v[174:175] op_sel:[1,1] op_sel_hi:[0,1]
	v_pk_fma_f32 v[104:105], v[104:105], v[174:175], v[176:177] op_sel_hi:[1,0,1] neg_lo:[0,0,1]
	s_waitcnt lgkmcnt(0)
	v_pk_add_f32 v[166:167], v[166:167], v[168:169] op_sel:[1,1] op_sel_hi:[0,0] neg_hi:[1,0]
	v_pk_mul_f32 v[178:179], v[106:107], v[166:167] op_sel:[1,1] op_sel_hi:[0,1]
	v_pk_fma_f32 v[106:107], v[106:107], v[166:167], v[178:179] op_sel_hi:[1,0,1] neg_lo:[0,0,1]
	ds_read_b64 v[176:177], v200 offset:64
	ds_read_b64 v[174:175], v202 offset:184
	ds_read_b64 v[178:179], v200 offset:80
	ds_read_b64 v[166:167], v202 offset:168
	ds_read_b64 v[188:189], v200 offset:96
	ds_read_b64 v[184:185], v202 offset:152
	ds_read_b64 v[186:187], v200 offset:112
	ds_read_b64 v[102:103], v202 offset:136
	s_waitcnt lgkmcnt(6)
	v_pk_add_f32 v[176:177], v[176:177], v[174:175] op_sel:[1,1] op_sel_hi:[0,0] neg_hi:[1,0]
	v_pk_mul_f32 v[180:181], v[108:109], v[176:177] op_sel:[1,1] op_sel_hi:[0,1]
	v_pk_fma_f32 v[108:109], v[108:109], v[176:177], v[180:181] op_sel_hi:[1,0,1] neg_lo:[0,0,1]
	s_waitcnt lgkmcnt(4)
	v_pk_add_f32 v[178:179], v[178:179], v[166:167] op_sel:[1,1] op_sel_hi:[0,0] neg_hi:[1,0]
	v_pk_mul_f32 v[168:169], v[118:119], v[178:179] op_sel:[1,1] op_sel_hi:[0,1]
	v_pk_fma_f32 v[118:119], v[118:119], v[178:179], v[168:169] op_sel_hi:[1,0,1] neg_lo:[0,0,1]
	s_waitcnt lgkmcnt(2)
	v_pk_add_f32 v[188:189], v[188:189], v[184:185] op_sel:[1,1] op_sel_hi:[0,0] neg_hi:[1,0]
	v_pk_mul_f32 v[180:181], v[112:113], v[188:189] op_sel:[1,1] op_sel_hi:[0,1]
	v_pk_fma_f32 v[112:113], v[112:113], v[188:189], v[180:181] op_sel_hi:[1,0,1] neg_lo:[0,0,1]
	s_waitcnt lgkmcnt(0)
	v_pk_add_f32 v[186:187], v[186:187], v[102:103] op_sel:[1,1] op_sel_hi:[0,0] neg_hi:[1,0]
	v_pk_mul_f32 v[168:169], v[114:115], v[186:187] op_sel:[1,1] op_sel_hi:[0,1]
	v_pk_fma_f32 v[114:115], v[114:115], v[186:187], v[168:169] op_sel_hi:[1,0,1] neg_lo:[0,0,1]
	ds_read_b64 v[180:181], v200 offset:128
	ds_read_b64 v[188:189], v202 offset:120
	ds_read_b64 v[168:169], v200 offset:144
	ds_read_b64 v[186:187], v202 offset:104
	ds_read_b64 v[176:177], v200 offset:160
	ds_read_b64 v[174:175], v202 offset:88
	ds_read_b64 v[178:179], v200 offset:176
	ds_read_b64 v[166:167], v202 offset:72
	s_waitcnt lgkmcnt(6)
; __device__ __forceinline__ f32x2 cmul(f32x2 a, f32x2 b) { return (f32x2){a.x * b.x - a.y * b.y, a.x * b.y + a.y * b.x}; }
; template <bool INV> __device__ __forceinline__ f32x2 cmul_tw(f32x2 a, f32x2 w) { return INV ? cmulc(a, w) : cmul(a, w); }
; template <bool INV> __device__ __forceinline__ void dft16(f32x2 (&x)[16]) {
;     constexpr float C1 = 0.92387953251128674f, S1 = 0.38268343236508977f, C2 = 0.70710678118654752f;
; #pragma unroll
;     for (int b = 0; b < 4; ++b) dft4<INV>(x[b], x[4 + b], x[8 + b], x[12 + b]);
;     const f32x2 w1 = {C1, -S1}, w2 = {C2, -C2}, w3 = {S1, -C1}, w4 = {0.f, -1.f}, w6 = {-C2, -C2}, w9 = {-C1, S1};
;     x[4 * 1 + 1] = cmul_tw<INV>(x[5], w1); x[4 * 1 + 2] = cmul_tw<INV>(x[6], w2); x[4 * 1 + 3] = cmul_tw<INV>(x[7], w3);
;     x[4 * 2 + 1] = cmul_tw<INV>(x[9], w2); x[4 * 2 + 2] = cmul_tw<INV>(x[10], w4); x[4 * 2 + 3] = cmul_tw<INV>(x[11], w6);
;     x[4 * 3 + 1] = cmul_tw<INV>(x[13], w3); x[4 * 3 + 2] = cmul_tw<INV>(x[14], w6); x[4 * 3 + 3] = cmul_tw<INV>(x[15], w9);
; #pragma unroll
;     for (int c = 0; c < 4; ++c) dft4<INV>(x[4 * c], x[4 * c + 1], x[4 * c + 2], x[4 * c + 3]);
; template <int MODE> __device__ __forceinline__ void fft_pair32(LAS f32x2* B, const LAS f32x2* F, int wave, int lane) {
;     ...
;     for (int k = 0; k < 16; ++k) { const f32x2 A = fah[2 * k]; f32x2 Bm = fbh[31 - 2 * k];
;         if (k == 0) { const f32x2 m0 = b2 ? fb[31] : fa[0]; Bm = hi ? Bm : m0; }
;         const f32x2 H = MODE == 0 ? (f32x2){(A.x + Bm.x) * SC, (A.y - Bm.y) * SC} : (f32x2){(A.y + Bm.y) * SC, (Bm.x - A.x) * SC};
;         v[k] = cmul(v[k], H); }
;     dft16<true>(v);
	v_pk_add_f32 v[180:181], v[180:181], v[188:189] op_sel:[1,1] op_sel_hi:[0,0] neg_hi:[1,0]
	v_pk_mul_f32 v[184:185], v[116:117], v[180:181] op_sel:[1,1] op_sel_hi:[0,1]
	v_pk_fma_f32 v[116:117], v[116:117], v[180:181], v[184:185] op_sel_hi:[1,0,1] neg_lo:[0,0,1]
	s_waitcnt lgkmcnt(4)
	v_pk_add_f32 v[168:169], v[168:169], v[186:187] op_sel:[1,1] op_sel_hi:[0,0] neg_hi:[1,0]
	v_pk_mul_f32 v[102:103], v[182:183], v[168:169] op_sel:[1,1] op_sel_hi:[0,1]
	v_pk_fma_f32 v[182:183], v[182:183], v[168:169], v[102:103] op_sel_hi:[1,0,1] neg_lo:[0,0,1]
	s_waitcnt lgkmcnt(2)
	v_pk_add_f32 v[176:177], v[176:177], v[174:175] op_sel:[1,1] op_sel_hi:[0,0] neg_hi:[1,0]
	v_pk_mul_f32 v[184:185], v[120:121], v[176:177] op_sel:[1,1] op_sel_hi:[0,1]
	v_pk_fma_f32 v[120:121], v[120:121], v[176:177], v[184:185] op_sel_hi:[1,0,1] neg_lo:[0,0,1]
	s_waitcnt lgkmcnt(0)
	v_pk_add_f32 v[178:179], v[178:179], v[166:167] op_sel:[1,1] op_sel_hi:[0,0] neg_hi:[1,0]
	v_pk_mul_f32 v[102:103], v[122:123], v[178:179] op_sel:[1,1] op_sel_hi:[0,1]
	v_pk_fma_f32 v[122:123], v[122:123], v[178:179], v[102:103] op_sel_hi:[1,0,1] neg_lo:[0,0,1]
	ds_read_b64 v[184:185], v200 offset:192
	ds_read_b64 v[176:177], v202 offset:56
	ds_read_b64 v[102:103], v200 offset:208
	ds_read_b64 v[178:179], v202 offset:40
	ds_read_b64 v[180:181], v200 offset:224
	ds_read_b64 v[188:189], v202 offset:24
	ds_read_b64 v[168:169], v200 offset:240
	ds_read_b64 v[186:187], v202 offset:8
	s_waitcnt lgkmcnt(6)
	v_pk_add_f32 v[184:185], v[184:185], v[176:177] op_sel:[1,1] op_sel_hi:[0,0] neg_hi:[1,0]
	v_pk_mul_f32 v[174:175], v[124:125], v[184:185] op_sel:[1,1] op_sel_hi:[0,1]
	v_pk_fma_f32 v[124:125], v[124:125], v[184:185], v[174:175] op_sel_hi:[1,0,1] neg_lo:[0,0,1]
	s_waitcnt lgkmcnt(4)
	v_pk_add_f32 v[102:103], v[102:103], v[178:179] op_sel:[1,1] op_sel_hi:[0,0] neg_hi:[1,0]
	v_pk_mul_f32 v[166:167], v[110:111], v[102:103] op_sel:[1,1] op_sel_hi:[0,1]
	v_pk_fma_f32 v[110:111], v[110:111], v[102:103], v[166:167] op_sel_hi:[1,0,1] neg_lo:[0,0,1]
	s_waitcnt lgkmcnt(2)
	v_pk_add_f32 v[180:181], v[180:181], v[188:189] op_sel:[1,1] op_sel_hi:[0,0] neg_hi:[1,0]
	v_pk_mul_f32 v[174:175], v[128:129], v[180:181] op_sel:[1,1] op_sel_hi:[0,1]
	v_pk_fma_f32 v[128:129], v[128:129], v[180:181], v[174:175] op_sel_hi:[1,0,1] neg_lo:[0,0,1]
	s_waitcnt lgkmcnt(0)
	v_pk_add_f32 v[168:169], v[168:169], v[186:187] op_sel:[1,1] op_sel_hi:[0,0] neg_hi:[1,0]
	v_pk_mul_f32 v[166:167], v[130:131], v[168:169] op_sel:[1,1] op_sel_hi:[0,1]
	v_pk_fma_f32 v[130:131], v[130:131], v[168:169], v[166:167] op_sel_hi:[1,0,1] neg_lo:[0,0,1]
	v_pk_add_f32 v[174:175], v[100:101], v[116:117]
	v_pk_add_f32 v[166:167], v[100:101], v[116:117] neg_lo:[0,1] neg_hi:[0,1]
	v_pk_add_f32 v[184:185], v[108:109], v[124:125]
	v_pk_add_f32 v[102:103], v[108:109], v[124:125] neg_lo:[0,1] neg_hi:[0,1]
	v_pk_add_f32 v[100:101], v[174:175], v[184:185]
	v_pk_add_f32 v[116:117], v[174:175], v[184:185] neg_lo:[0,1] neg_hi:[0,1]
	v_pk_add_f32 v[108:109], v[166:167], v[102:103] op_sel:[0,1] op_sel_hi:[1,0] neg_lo:[0,1]
	v_pk_add_f32 v[124:125], v[166:167], v[102:103] op_sel:[0,1] op_sel_hi:[1,0] neg_hi:[0,1]
	v_pk_add_f32 v[180:181], v[126:127], v[182:183]
	v_pk_add_f32 v[168:169], v[126:127], v[182:183] neg_lo:[0,1] neg_hi:[0,1]
	v_pk_add_f32 v[176:177], v[118:119], v[110:111]
	v_pk_add_f32 v[178:179], v[118:119], v[110:111] neg_lo:[0,1] neg_hi:[0,1]
	v_pk_add_f32 v[126:127], v[180:181], v[176:177]
	v_pk_add_f32 v[182:183], v[180:181], v[176:177] neg_lo:[0,1] neg_hi:[0,1]
	v_pk_add_f32 v[118:119], v[168:169], v[178:179] op_sel:[0,1] op_sel_hi:[1,0] neg_lo:[0,1]
	v_pk_add_f32 v[110:111], v[168:169], v[178:179] op_sel:[0,1] op_sel_hi:[1,0] neg_hi:[0,1]
	v_pk_add_f32 v[188:189], v[104:105], v[120:121]
	v_pk_add_f32 v[186:187], v[104:105], v[120:121] neg_lo:[0,1] neg_hi:[0,1]
	v_pk_add_f32 v[174:175], v[112:113], v[128:129]
	v_pk_add_f32 v[166:167], v[112:113], v[128:129] neg_lo:[0,1] neg_hi:[0,1]
	v_pk_add_f32 v[104:105], v[188:189], v[174:175]
	v_pk_add_f32 v[120:121], v[188:189], v[174:175] neg_lo:[0,1] neg_hi:[0,1]
	v_pk_add_f32 v[112:113], v[186:187], v[166:167] op_sel:[0,1] op_sel_hi:[1,0] neg_lo:[0,1]
	v_pk_add_f32 v[128:129], v[186:187], v[166:167] op_sel:[0,1] op_sel_hi:[1,0] neg_hi:[0,1]
	v_pk_add_f32 v[184:185], v[106:107], v[122:123]
	v_pk_add_f32 v[102:103], v[106:107], v[122:123] neg_lo:[0,1] neg_hi:[0,1]
	v_pk_add_f32 v[180:181], v[114:115], v[130:131]
	v_pk_add_f32 v[168:169], v[114:115], v[130:131] neg_lo:[0,1] neg_hi:[0,1]
	v_pk_add_f32 v[106:107], v[184:185], v[180:181]
	v_pk_add_f32 v[122:123], v[184:185], v[180:181] neg_lo:[0,1] neg_hi:[0,1]
	v_pk_add_f32 v[114:115], v[102:103], v[168:169] op_sel:[0,1] op_sel_hi:[1,0] neg_lo:[0,1]
	v_pk_add_f32 v[130:131], v[102:103], v[168:169] op_sel:[0,1] op_sel_hi:[1,0] neg_hi:[0,1]
	v_pk_mul_f32 v[176:177], v[118:119], s[68:69] op_sel:[1,1] op_sel_hi:[0,1]
	v_pk_fma_f32 v[118:119], v[118:119], s[68:69], v[176:177] op_sel_hi:[1,0,1] neg_hi:[0,0,1]
	v_pk_mul_f32 v[178:179], v[112:113], s[84:85] op_sel:[1,1] op_sel_hi:[0,1]
	v_pk_fma_f32 v[112:113], v[112:113], s[84:85], v[178:179] op_sel_hi:[1,0,1] neg_hi:[0,0,1]
	v_pk_mul_f32 v[188:189], v[114:115], s[88:89] op_sel:[1,1] op_sel_hi:[0,1]
	v_pk_fma_f32 v[114:115], v[114:115], s[88:89], v[188:189] op_sel_hi:[1,0,1] neg_hi:[0,0,1]
	v_pk_mul_f32 v[186:187], v[182:183], s[84:85] op_sel:[1,1] op_sel_hi:[0,1]
	v_pk_fma_f32 v[182:183], v[182:183], s[84:85], v[186:187] op_sel_hi:[1,0,1] neg_hi:[0,0,1]
	v_pk_mul_f32 v[174:175], v[122:123], s[90:91] op_sel:[1,1] op_sel_hi:[0,1]
	v_pk_fma_f32 v[122:123], v[122:123], s[90:91], v[174:175] op_sel_hi:[1,0,1] neg_hi:[0,0,1]
; __device__ __forceinline__ f32x2 cmulc(f32x2 a, f32x2 b) { return (f32x2){a.x * b.x + a.y * b.y, a.y * b.x - a.x * b.y}; }
; template <bool INV> __device__ __forceinline__ f32x2 cmul_tw(f32x2 a, f32x2 w) { return INV ? cmulc(a, w) : cmul(a, w); }
; template <bool INV> __device__ __forceinline__ void dft16(f32x2 (&x)[16]) {
;     constexpr float C1 = 0.92387953251128674f, S1 = 0.38268343236508977f, C2 = 0.70710678118654752f;
; #pragma unroll
;     for (int b = 0; b < 4; ++b) dft4<INV>(x[b], x[4 + b], x[8 + b], x[12 + b]);
;     const f32x2 w1 = {C1, -S1}, w2 = {C2, -C2}, w3 = {S1, -C1}, w4 = {0.f, -1.f}, w6 = {-C2, -C2}, w9 = {-C1, S1};
;     x[4 * 1 + 1] = cmul_tw<INV>(x[5], w1); x[4 * 1 + 2] = cmul_tw<INV>(x[6], w2); x[4 * 1 + 3] = cmul_tw<INV>(x[7], w3);
;     x[4 * 2 + 1] = cmul_tw<INV>(x[9], w2); x[4 * 2 + 2] = cmul_tw<INV>(x[10], w4); x[4 * 2 + 3] = cmul_tw<INV>(x[11], w6);
;     x[4 * 3 + 1] = cmul_tw<INV>(x[13], w3); x[4 * 3 + 2] = cmul_tw<INV>(x[14], w6); x[4 * 3 + 3] = cmul_tw<INV>(x[15], w9);
; #pragma unroll
;     for (int c = 0; c < 4; ++c) dft4<INV>(x[4 * c], x[4 * c + 1], x[4 * c + 2], x[4 * c + 3]);
;     f32x2 y[16];
; #pragma unroll
;     for (int k = 0; k < 16; ++k) y[k] = x[4 * (k & 3) + (k >> 2)];
; #pragma unroll
;     for (int k = 0; k < 16; ++k) x[k] = y[k];
; }
; template <int MODE> __device__ __forceinline__ void fft_pair32(LAS f32x2* B, const LAS f32x2* F, int wave, int lane) {
;     ...
;     for (int j = 0; j < 16; ++j) { const f32x2 w = {hi ? CS[j] : 1.f, hi ? -SN[j] : 0.f}; const f32x2 u = j == 0 ? v[j] : cmulc(v[j], w);
;         const auto rx = __builtin_amdgcn_permlane32_swap(__float_as_uint(u.x), __float_as_uint(u.x), false, false);
;         const auto ry = __builtin_amdgcn_permlane32_swap(__float_as_uint(u.y), __float_as_uint(u.y), false, false);
;         const f32x2 a = {__uint_as_float(rx[0]), __uint_as_float(ry[0])}, b = {__uint_as_float(rx[1]), __uint_as_float(ry[1])};
;         p[16 * hi + j] = a + b * sg; }
	v_pk_mul_f32 v[166:167], v[110:111], s[88:89] op_sel:[1,1] op_sel_hi:[0,1]
	v_pk_fma_f32 v[110:111], v[110:111], s[88:89], v[166:167] op_sel_hi:[1,0,1] neg_hi:[0,0,1]
	v_pk_mul_f32 v[184:185], v[128:129], s[90:91] op_sel:[1,1] op_sel_hi:[0,1]
	v_pk_fma_f32 v[128:129], v[128:129], s[90:91], v[184:185] op_sel_hi:[1,0,1] neg_hi:[0,0,1]
	v_pk_mul_f32 v[102:103], v[130:131], s[98:99] op_sel:[1,1] op_sel_hi:[0,1]
	v_pk_fma_f32 v[130:131], v[130:131], s[98:99], v[102:103] op_sel_hi:[1,0,1] neg_hi:[0,0,1]
	v_pk_add_f32 v[180:181], v[100:101], v[104:105]
	v_pk_add_f32 v[168:169], v[100:101], v[104:105] neg_lo:[0,1] neg_hi:[0,1]
	v_pk_add_f32 v[176:177], v[126:127], v[106:107]
	v_pk_add_f32 v[178:179], v[126:127], v[106:107] neg_lo:[0,1] neg_hi:[0,1]
	v_pk_add_f32 v[100:101], v[180:181], v[176:177]
	v_pk_add_f32 v[104:105], v[180:181], v[176:177] neg_lo:[0,1] neg_hi:[0,1]
	v_pk_add_f32 v[126:127], v[168:169], v[178:179] op_sel:[0,1] op_sel_hi:[1,0] neg_lo:[0,1]
	v_pk_add_f32 v[106:107], v[168:169], v[178:179] op_sel:[0,1] op_sel_hi:[1,0] neg_hi:[0,1]
	v_pk_add_f32 v[188:189], v[108:109], v[112:113]
	v_pk_add_f32 v[186:187], v[108:109], v[112:113] neg_lo:[0,1] neg_hi:[0,1]
	v_pk_add_f32 v[174:175], v[118:119], v[114:115]
	v_pk_add_f32 v[166:167], v[118:119], v[114:115] neg_lo:[0,1] neg_hi:[0,1]
	v_pk_add_f32 v[108:109], v[188:189], v[174:175]
	v_pk_add_f32 v[112:113], v[188:189], v[174:175] neg_lo:[0,1] neg_hi:[0,1]
	v_pk_add_f32 v[118:119], v[186:187], v[166:167] op_sel:[0,1] op_sel_hi:[1,0] neg_lo:[0,1]
	v_pk_add_f32 v[114:115], v[186:187], v[166:167] op_sel:[0,1] op_sel_hi:[1,0] neg_hi:[0,1]
	v_pk_add_f32 v[184:185], v[116:117], v[120:121] op_sel:[0,1] op_sel_hi:[1,0] neg_lo:[0,1]
	v_pk_add_f32 v[102:103], v[116:117], v[120:121] op_sel:[0,1] op_sel_hi:[1,0] neg_hi:[0,1]
	v_pk_add_f32 v[180:181], v[182:183], v[122:123]
	v_pk_add_f32 v[168:169], v[182:183], v[122:123] neg_lo:[0,1] neg_hi:[0,1]
	v_pk_add_f32 v[116:117], v[184:185], v[180:181]
	v_pk_add_f32 v[120:121], v[184:185], v[180:181] neg_lo:[0,1] neg_hi:[0,1]
	v_pk_add_f32 v[182:183], v[102:103], v[168:169] op_sel:[0,1] op_sel_hi:[1,0] neg_lo:[0,1]
	v_pk_add_f32 v[122:123], v[102:103], v[168:169] op_sel:[0,1] op_sel_hi:[1,0] neg_hi:[0,1]
	v_pk_add_f32 v[176:177], v[124:125], v[128:129]
	v_pk_add_f32 v[178:179], v[124:125], v[128:129] neg_lo:[0,1] neg_hi:[0,1]
	v_pk_add_f32 v[188:189], v[110:111], v[130:131]
	v_pk_add_f32 v[186:187], v[110:111], v[130:131] neg_lo:[0,1] neg_hi:[0,1]
	v_pk_add_f32 v[124:125], v[176:177], v[188:189]
	v_pk_add_f32 v[128:129], v[176:177], v[188:189] neg_lo:[0,1] neg_hi:[0,1]
	v_pk_add_f32 v[110:111], v[178:179], v[186:187] op_sel:[0,1] op_sel_hi:[1,0] neg_lo:[0,1]
	v_pk_add_f32 v[130:131], v[178:179], v[186:187] op_sel:[0,1] op_sel_hi:[1,0] neg_hi:[0,1]
	v_mov_b32_e32 v174, v100
	v_mov_b32_e32 v175, v101
	v_pk_mul_f32 v[180:181], v[108:109], v[36:37] op_sel:[1,1] op_sel_hi:[0,1]
	v_pk_fma_f32 v[166:167], v[108:109], v[36:37], v[180:181] op_sel_hi:[1,0,1] neg_hi:[0,0,1]
	v_pk_fma_f32 v[108:109], v[108:109], v[36:37], v[180:181] op_sel_hi:[1,0,1] neg_hi:[0,0,1]
	v_pk_mul_f32 v[168:169], v[116:117], v[38:39] op_sel:[1,1] op_sel_hi:[0,1]
	v_pk_fma_f32 v[184:185], v[116:117], v[38:39], v[168:169] op_sel_hi:[1,0,1] neg_hi:[0,0,1]
	v_pk_fma_f32 v[116:117], v[116:117], v[38:39], v[168:169] op_sel_hi:[1,0,1] neg_hi:[0,0,1]
	v_pk_mul_f32 v[176:177], v[124:125], v[40:41] op_sel:[1,1] op_sel_hi:[0,1]
	v_pk_fma_f32 v[102:103], v[124:125], v[40:41], v[176:177] op_sel_hi:[1,0,1] neg_hi:[0,0,1]
	v_pk_fma_f32 v[124:125], v[124:125], v[40:41], v[176:177] op_sel_hi:[1,0,1] neg_hi:[0,0,1]
	s_nop 1
	v_permlane32_swap_b32_e32 v100, v174
	v_permlane32_swap_b32_e32 v101, v175
	v_permlane32_swap_b32_e32 v108, v166
	v_permlane32_swap_b32_e32 v109, v167
	v_permlane32_swap_b32_e32 v116, v184
	v_permlane32_swap_b32_e32 v117, v185
	v_permlane32_swap_b32_e32 v124, v102
	v_permlane32_swap_b32_e32 v125, v103
	v_pk_fma_f32 v[100:101], v[174:175], v[190:191], v[100:101] op_sel_hi:[1,0,1]
	ds_write_b64 v198, v[100:101]
	v_pk_fma_f32 v[108:109], v[166:167], v[190:191], v[108:109] op_sel_hi:[1,0,1]
	ds_write_b64 v198, v[108:109] offset:8
	v_pk_fma_f32 v[116:117], v[184:185], v[190:191], v[116:117] op_sel_hi:[1,0,1]
	ds_write_b64 v198, v[116:117] offset:16
	v_pk_fma_f32 v[124:125], v[102:103], v[190:191], v[124:125] op_sel_hi:[1,0,1]
	ds_write_b64 v198, v[124:125] offset:24
	v_pk_mul_f32 v[168:169], v[126:127], v[42:43] op_sel:[1,1] op_sel_hi:[0,1]
	v_pk_fma_f32 v[178:179], v[126:127], v[42:43], v[168:169] op_sel_hi:[1,0,1] neg_hi:[0,0,1]
	v_pk_fma_f32 v[126:127], v[126:127], v[42:43], v[168:169] op_sel_hi:[1,0,1] neg_hi:[0,0,1]
	v_pk_mul_f32 v[176:177], v[118:119], v[44:45] op_sel:[1,1] op_sel_hi:[0,1]
	v_pk_fma_f32 v[188:189], v[118:119], v[44:45], v[176:177] op_sel_hi:[1,0,1] neg_hi:[0,0,1]
	v_pk_fma_f32 v[118:119], v[118:119], v[44:45], v[176:177] op_sel_hi:[1,0,1] neg_hi:[0,0,1]
	v_pk_mul_f32 v[174:175], v[182:183], v[46:47] op_sel:[1,1] op_sel_hi:[0,1]
	v_pk_fma_f32 v[186:187], v[182:183], v[46:47], v[174:175] op_sel_hi:[1,0,1] neg_hi:[0,0,1]
	v_pk_fma_f32 v[182:183], v[182:183], v[46:47], v[174:175] op_sel_hi:[1,0,1] neg_hi:[0,0,1]
	v_pk_mul_f32 v[166:167], v[110:111], v[48:49] op_sel:[1,1] op_sel_hi:[0,1]
	v_pk_fma_f32 v[180:181], v[110:111], v[48:49], v[166:167] op_sel_hi:[1,0,1] neg_hi:[0,0,1]
	v_pk_fma_f32 v[110:111], v[110:111], v[48:49], v[166:167] op_sel_hi:[1,0,1] neg_hi:[0,0,1]
	s_nop 1
	v_permlane32_swap_b32_e32 v126, v178
	v_permlane32_swap_b32_e32 v127, v179
	v_permlane32_swap_b32_e32 v118, v188
	v_permlane32_swap_b32_e32 v119, v189
	v_permlane32_swap_b32_e32 v182, v186
; #define LAS __attribute__((address_space(3)))
; __device__ __forceinline__ f32x2 cmulc(f32x2 a, f32x2 b) { return (f32x2){a.x * b.x + a.y * b.y, a.y * b.x - a.x * b.y}; }
; __device__ __forceinline__ void fft_inv2(LAS f32x2* B, const LAS f32x2* TW2, int tid) {
;     asm volatile("" : "+v"(tid));
;     const int b = tid >> 5, n2 = tid & 31, base = 512 * b + n2; f32x2 x[16];
;     x[0] = B[fpad(base)];
; #pragma unroll
;     for (int k = 1; k < 16; ++k) x[k] = cmulc(B[fpad(base + 32 * k)], TW2[k * 32 + n2]);
; template <int MODE> __device__ __forceinline__ void fft_pair32(LAS f32x2* B, const LAS f32x2* F, int wave, int lane) {
;     ...
;     for (int j = 0; j < 16; ++j) { const f32x2 w = {hi ? CS[j] : 1.f, hi ? -SN[j] : 0.f}; const f32x2 u = j == 0 ? v[j] : cmulc(v[j], w);
;         const auto rx = __builtin_amdgcn_permlane32_swap(__float_as_uint(u.x), __float_as_uint(u.x), false, false);
;         const auto ry = __builtin_amdgcn_permlane32_swap(__float_as_uint(u.y), __float_as_uint(u.y), false, false);
;         const f32x2 a = {__uint_as_float(rx[0]), __uint_as_float(ry[0])}, b = {__uint_as_float(rx[1]), __uint_as_float(ry[1])};
;         p[16 * hi + j] = a + b * sg; }
	v_permlane32_swap_b32_e32 v183, v187
	v_permlane32_swap_b32_e32 v110, v180
	v_permlane32_swap_b32_e32 v111, v181
	v_pk_fma_f32 v[126:127], v[178:179], v[190:191], v[126:127] op_sel_hi:[1,0,1]
	ds_write_b64 v198, v[126:127] offset:32
	v_pk_fma_f32 v[118:119], v[188:189], v[190:191], v[118:119] op_sel_hi:[1,0,1]
	ds_write_b64 v198, v[118:119] offset:40
	v_pk_fma_f32 v[182:183], v[186:187], v[190:191], v[182:183] op_sel_hi:[1,0,1]
	ds_write_b64 v198, v[182:183] offset:48
	v_pk_fma_f32 v[110:111], v[180:181], v[190:191], v[110:111] op_sel_hi:[1,0,1]
	ds_write_b64 v198, v[110:111] offset:56
	v_pk_mul_f32 v[174:175], v[104:105], v[50:51] op_sel:[1,1] op_sel_hi:[0,1]
	v_pk_fma_f32 v[184:185], v[104:105], v[50:51], v[174:175] op_sel_hi:[1,0,1] neg_hi:[0,0,1]
	v_pk_fma_f32 v[104:105], v[104:105], v[50:51], v[174:175] op_sel_hi:[1,0,1] neg_hi:[0,0,1]
	v_pk_mul_f32 v[166:167], v[112:113], v[52:53] op_sel:[1,1] op_sel_hi:[0,1]
	v_pk_fma_f32 v[102:103], v[112:113], v[52:53], v[166:167] op_sel_hi:[1,0,1] neg_hi:[0,0,1]
	v_pk_fma_f32 v[112:113], v[112:113], v[52:53], v[166:167] op_sel_hi:[1,0,1] neg_hi:[0,0,1]
	v_pk_mul_f32 v[178:179], v[120:121], v[54:55] op_sel:[1,1] op_sel_hi:[0,1]
	v_pk_fma_f32 v[168:169], v[120:121], v[54:55], v[178:179] op_sel_hi:[1,0,1] neg_hi:[0,0,1]
	v_pk_fma_f32 v[120:121], v[120:121], v[54:55], v[178:179] op_sel_hi:[1,0,1] neg_hi:[0,0,1]
	v_pk_mul_f32 v[188:189], v[128:129], v[90:91] op_sel:[1,1] op_sel_hi:[0,1]
	v_pk_fma_f32 v[176:177], v[128:129], v[90:91], v[188:189] op_sel_hi:[1,0,1] neg_hi:[0,0,1]
	v_pk_fma_f32 v[128:129], v[128:129], v[90:91], v[188:189] op_sel_hi:[1,0,1] neg_hi:[0,0,1]
	s_nop 1
	v_permlane32_swap_b32_e32 v104, v184
	v_permlane32_swap_b32_e32 v105, v185
	v_permlane32_swap_b32_e32 v112, v102
	v_permlane32_swap_b32_e32 v113, v103
	v_permlane32_swap_b32_e32 v120, v168
	v_permlane32_swap_b32_e32 v121, v169
	v_permlane32_swap_b32_e32 v128, v176
	v_permlane32_swap_b32_e32 v129, v177
	v_pk_fma_f32 v[104:105], v[184:185], v[190:191], v[104:105] op_sel_hi:[1,0,1]
	ds_write_b64 v198, v[104:105] offset:64
	v_pk_fma_f32 v[112:113], v[102:103], v[190:191], v[112:113] op_sel_hi:[1,0,1]
	ds_write_b64 v198, v[112:113] offset:72
	v_pk_fma_f32 v[120:121], v[168:169], v[190:191], v[120:121] op_sel_hi:[1,0,1]
	ds_write_b64 v198, v[120:121] offset:80
	v_pk_fma_f32 v[128:129], v[176:177], v[190:191], v[128:129] op_sel_hi:[1,0,1]
	ds_write_b64 v198, v[128:129] offset:88
	v_pk_mul_f32 v[178:179], v[106:107], v[92:93] op_sel:[1,1] op_sel_hi:[0,1]
	v_pk_fma_f32 v[186:187], v[106:107], v[92:93], v[178:179] op_sel_hi:[1,0,1] neg_hi:[0,0,1]
	v_pk_fma_f32 v[106:107], v[106:107], v[92:93], v[178:179] op_sel_hi:[1,0,1] neg_hi:[0,0,1]
	v_pk_mul_f32 v[188:189], v[114:115], v[94:95] op_sel:[1,1] op_sel_hi:[0,1]
	v_pk_fma_f32 v[180:181], v[114:115], v[94:95], v[188:189] op_sel_hi:[1,0,1] neg_hi:[0,0,1]
	v_pk_fma_f32 v[114:115], v[114:115], v[94:95], v[188:189] op_sel_hi:[1,0,1] neg_hi:[0,0,1]
	v_pk_mul_f32 v[184:185], v[122:123], v[96:97] op_sel:[1,1] op_sel_hi:[0,1]
	v_pk_fma_f32 v[174:175], v[122:123], v[96:97], v[184:185] op_sel_hi:[1,0,1] neg_hi:[0,0,1]
	v_pk_fma_f32 v[122:123], v[122:123], v[96:97], v[184:185] op_sel_hi:[1,0,1] neg_hi:[0,0,1]
	v_pk_mul_f32 v[102:103], v[130:131], v[98:99] op_sel:[1,1] op_sel_hi:[0,1]
	v_pk_fma_f32 v[166:167], v[130:131], v[98:99], v[102:103] op_sel_hi:[1,0,1] neg_hi:[0,0,1]
	v_pk_fma_f32 v[130:131], v[130:131], v[98:99], v[102:103] op_sel_hi:[1,0,1] neg_hi:[0,0,1]
	s_nop 1
	v_permlane32_swap_b32_e32 v106, v186
	v_permlane32_swap_b32_e32 v107, v187
	v_permlane32_swap_b32_e32 v114, v180
	v_permlane32_swap_b32_e32 v115, v181
	v_permlane32_swap_b32_e32 v122, v174
	v_permlane32_swap_b32_e32 v123, v175
	v_permlane32_swap_b32_e32 v130, v166
	v_permlane32_swap_b32_e32 v131, v167
	v_pk_fma_f32 v[106:107], v[186:187], v[190:191], v[106:107] op_sel_hi:[1,0,1]
	ds_write_b64 v198, v[106:107] offset:96
	v_pk_fma_f32 v[114:115], v[180:181], v[190:191], v[114:115] op_sel_hi:[1,0,1]
	ds_write_b64 v198, v[114:115] offset:104
	v_pk_fma_f32 v[122:123], v[174:175], v[190:191], v[122:123] op_sel_hi:[1,0,1]
	ds_write_b64 v198, v[122:123] offset:112
	v_pk_fma_f32 v[130:131], v[166:167], v[190:191], v[130:131] op_sel_hi:[1,0,1]
	ds_write_b64 v198, v[130:131] offset:120
	s_waitcnt lgkmcnt(0)
	ds_read_b64 v[100:101], v5
	ds_read_b64 v[108:109], v5 offset:264
	ds_read_b64 v[168:169], v56 offset:256
	ds_read_b64 v[116:117], v5 offset:528
	ds_read_b64 v[176:177], v56 offset:512
	ds_read_b64 v[124:125], v5 offset:792
	ds_read_b64 v[178:179], v56 offset:768
	ds_read_b64 v[126:127], v5 offset:1056
	ds_read_b64 v[188:189], v56 offset:1024
	ds_read_b64 v[118:119], v5 offset:1320
	ds_read_b64 v[184:185], v56 offset:1280
	s_waitcnt lgkmcnt(8)
	v_pk_mul_f32 v[102:103], v[108:109], v[168:169] op_sel:[1,1] op_sel_hi:[0,1]
	v_pk_fma_f32 v[108:109], v[108:109], v[168:169], v[102:103] op_sel_hi:[1,0,1] neg_hi:[0,0,1]
	s_waitcnt lgkmcnt(6)
	v_pk_mul_f32 v[186:187], v[116:117], v[176:177] op_sel:[1,1] op_sel_hi:[0,1]
	v_pk_fma_f32 v[116:117], v[116:117], v[176:177], v[186:187] op_sel_hi:[1,0,1] neg_hi:[0,0,1]
	s_waitcnt lgkmcnt(4)
	v_pk_mul_f32 v[180:181], v[124:125], v[178:179] op_sel:[1,1] op_sel_hi:[0,1]
	v_pk_fma_f32 v[124:125], v[124:125], v[178:179], v[180:181] op_sel_hi:[1,0,1] neg_hi:[0,0,1]
	s_waitcnt lgkmcnt(2)
	v_pk_mul_f32 v[174:175], v[126:127], v[188:189] op_sel:[1,1] op_sel_hi:[0,1]
	v_pk_fma_f32 v[126:127], v[126:127], v[188:189], v[174:175] op_sel_hi:[1,0,1] neg_hi:[0,0,1]
	s_waitcnt lgkmcnt(0)
; #define LAS __attribute__((address_space(3)))
; __device__ __forceinline__ f32x2 cmulc(f32x2 a, f32x2 b) { return (f32x2){a.x * b.x + a.y * b.y, a.y * b.x - a.x * b.y}; }
; __device__ __forceinline__ void fft_inv2(LAS f32x2* B, const LAS f32x2* TW2, int tid) {
;     asm volatile("" : "+v"(tid));
;     const int b = tid >> 5, n2 = tid & 31, base = 512 * b + n2; f32x2 x[16];
;     x[0] = B[fpad(base)];
; #pragma unroll
;     for (int k = 1; k < 16; ++k) x[k] = cmulc(B[fpad(base + 32 * k)], TW2[k * 32 + n2]);
	v_pk_mul_f32 v[166:167], v[118:119], v[184:185] op_sel:[1,1] op_sel_hi:[0,1]
	v_pk_fma_f32 v[118:119], v[118:119], v[184:185], v[166:167] op_sel_hi:[1,0,1] neg_hi:[0,0,1]
	ds_read_b64 v[182:183], v5 offset:1584
	ds_read_b64 v[102:103], v56 offset:1536
	ds_read_b64 v[110:111], v5 offset:1848
	ds_read_b64 v[186:187], v56 offset:1792
	ds_read_b64 v[104:105], v5 offset:2112
	ds_read_b64 v[180:181], v56 offset:2048
	ds_read_b64 v[112:113], v5 offset:2376
	ds_read_b64 v[174:175], v56 offset:2304
	ds_read_b64 v[120:121], v5 offset:2640
	ds_read_b64 v[166:167], v56 offset:2560
	s_waitcnt lgkmcnt(8)
	v_pk_mul_f32 v[168:169], v[182:183], v[102:103] op_sel:[1,1] op_sel_hi:[0,1]
	v_pk_fma_f32 v[182:183], v[182:183], v[102:103], v[168:169] op_sel_hi:[1,0,1] neg_hi:[0,0,1]
	s_waitcnt lgkmcnt(6)
	v_pk_mul_f32 v[176:177], v[110:111], v[186:187] op_sel:[1,1] op_sel_hi:[0,1]
	v_pk_fma_f32 v[110:111], v[110:111], v[186:187], v[176:177] op_sel_hi:[1,0,1] neg_hi:[0,0,1]
	s_waitcnt lgkmcnt(4)
	v_pk_mul_f32 v[178:179], v[104:105], v[180:181] op_sel:[1,1] op_sel_hi:[0,1]
	v_pk_fma_f32 v[104:105], v[104:105], v[180:181], v[178:179] op_sel_hi:[1,0,1] neg_hi:[0,0,1]
	s_waitcnt lgkmcnt(2)
	v_pk_mul_f32 v[188:189], v[112:113], v[174:175] op_sel:[1,1] op_sel_hi:[0,1]
	v_pk_fma_f32 v[112:113], v[112:113], v[174:175], v[188:189] op_sel_hi:[1,0,1] neg_hi:[0,0,1]
	s_waitcnt lgkmcnt(0)
	v_pk_mul_f32 v[184:185], v[120:121], v[166:167] op_sel:[1,1] op_sel_hi:[0,1]
	v_pk_fma_f32 v[120:121], v[120:121], v[166:167], v[184:185] op_sel_hi:[1,0,1] neg_hi:[0,0,1]
	ds_read_b64 v[128:129], v5 offset:2904
	ds_read_b64 v[168:169], v56 offset:2816
	ds_read_b64 v[106:107], v5 offset:3168
	ds_read_b64 v[176:177], v56 offset:3072
	ds_read_b64 v[114:115], v5 offset:3432
	ds_read_b64 v[178:179], v56 offset:3328
	ds_read_b64 v[122:123], v5 offset:3696
	ds_read_b64 v[188:189], v56 offset:3584
	ds_read_b64 v[130:131], v5 offset:3960
	ds_read_b64 v[184:185], v56 offset:3840
	s_waitcnt lgkmcnt(8)
	v_pk_mul_f32 v[102:103], v[128:129], v[168:169] op_sel:[1,1] op_sel_hi:[0,1]
	v_pk_fma_f32 v[128:129], v[128:129], v[168:169], v[102:103] op_sel_hi:[1,0,1] neg_hi:[0,0,1]
	s_waitcnt lgkmcnt(6)
	v_pk_mul_f32 v[186:187], v[106:107], v[176:177] op_sel:[1,1] op_sel_hi:[0,1]
	v_pk_fma_f32 v[106:107], v[106:107], v[176:177], v[186:187] op_sel_hi:[1,0,1] neg_hi:[0,0,1]
	s_waitcnt lgkmcnt(4)
	v_pk_mul_f32 v[180:181], v[114:115], v[178:179] op_sel:[1,1] op_sel_hi:[0,1]
	v_pk_fma_f32 v[114:115], v[114:115], v[178:179], v[180:181] op_sel_hi:[1,0,1] neg_hi:[0,0,1]
	s_waitcnt lgkmcnt(2)
	v_pk_mul_f32 v[174:175], v[122:123], v[188:189] op_sel:[1,1] op_sel_hi:[0,1]
	v_pk_fma_f32 v[122:123], v[122:123], v[188:189], v[174:175] op_sel_hi:[1,0,1] neg_hi:[0,0,1]
	s_waitcnt lgkmcnt(0)
; #define LAS __attribute__((address_space(3)))
; __device__ __forceinline__ f32x2 cmulc(f32x2 a, f32x2 b) { return (f32x2){a.x * b.x + a.y * b.y, a.y * b.x - a.x * b.y}; }
; template <bool INV> __device__ __forceinline__ f32x2 cmul_tw(f32x2 a, f32x2 w) { return INV ? cmulc(a, w) : cmul(a, w); }
; template <bool INV> __device__ __forceinline__ void dft16(f32x2 (&x)[16]) {
;     constexpr float C1 = 0.92387953251128674f, S1 = 0.38268343236508977f, C2 = 0.70710678118654752f;
; #pragma unroll
;     for (int b = 0; b < 4; ++b) dft4<INV>(x[b], x[4 + b], x[8 + b], x[12 + b]);
;     const f32x2 w1 = {C1, -S1}, w2 = {C2, -C2}, w3 = {S1, -C1}, w4 = {0.f, -1.f}, w6 = {-C2, -C2}, w9 = {-C1, S1};
;     x[4 * 1 + 1] = cmul_tw<INV>(x[5], w1); x[4 * 1 + 2] = cmul_tw<INV>(x[6], w2); x[4 * 1 + 3] = cmul_tw<INV>(x[7], w3);
;     x[4 * 2 + 1] = cmul_tw<INV>(x[9], w2); x[4 * 2 + 2] = cmul_tw<INV>(x[10], w4); x[4 * 2 + 3] = cmul_tw<INV>(x[11], w6);
;     x[4 * 3 + 1] = cmul_tw<INV>(x[13], w3); x[4 * 3 + 2] = cmul_tw<INV>(x[14], w6); x[4 * 3 + 3] = cmul_tw<INV>(x[15], w9);
; #pragma unroll
;     for (int c = 0; c < 4; ++c) dft4<INV>(x[4 * c], x[4 * c + 1], x[4 * c + 2], x[4 * c + 3]);
;     f32x2 y[16];
; #pragma unroll
;     for (int k = 0; k < 16; ++k) y[k] = x[4 * (k & 3) + (k >> 2)];
; #pragma unroll
;     for (int k = 0; k < 16; ++k) x[k] = y[k];
; __device__ __forceinline__ void fft_inv2(LAS f32x2* B, const LAS f32x2* TW2, int tid) {
;     asm volatile("" : "+v"(tid));
;     const int b = tid >> 5, n2 = tid & 31, base = 512 * b + n2; f32x2 x[16];
;     x[0] = B[fpad(base)];
; #pragma unroll
;     for (int k = 1; k < 16; ++k) x[k] = cmulc(B[fpad(base + 32 * k)], TW2[k * 32 + n2]);
;     dft16<true>(x);
; #pragma unroll
;     for (int r = 0; r < 16; ++r) B[fpad(base + 32 * r)] = x[r];
	v_pk_mul_f32 v[166:167], v[130:131], v[184:185] op_sel:[1,1] op_sel_hi:[0,1]
	v_pk_fma_f32 v[130:131], v[130:131], v[184:185], v[166:167] op_sel_hi:[1,0,1] neg_hi:[0,0,1]
	v_pk_add_f32 v[102:103], v[100:101], v[104:105]
	v_pk_add_f32 v[186:187], v[100:101], v[104:105] neg_lo:[0,1] neg_hi:[0,1]
	v_pk_add_f32 v[180:181], v[126:127], v[106:107]
	v_pk_add_f32 v[174:175], v[126:127], v[106:107] neg_lo:[0,1] neg_hi:[0,1]
	v_pk_add_f32 v[100:101], v[102:103], v[180:181]
	v_pk_add_f32 v[104:105], v[102:103], v[180:181] neg_lo:[0,1] neg_hi:[0,1]
	v_pk_add_f32 v[126:127], v[186:187], v[174:175] op_sel:[0,1] op_sel_hi:[1,0] neg_lo:[0,1]
	v_pk_add_f32 v[106:107], v[186:187], v[174:175] op_sel:[0,1] op_sel_hi:[1,0] neg_hi:[0,1]
	v_pk_add_f32 v[166:167], v[108:109], v[112:113]
	v_pk_add_f32 v[168:169], v[108:109], v[112:113] neg_lo:[0,1] neg_hi:[0,1]
	v_pk_add_f32 v[176:177], v[118:119], v[114:115]
	v_pk_add_f32 v[178:179], v[118:119], v[114:115] neg_lo:[0,1] neg_hi:[0,1]
	v_pk_add_f32 v[108:109], v[166:167], v[176:177]
	v_pk_add_f32 v[112:113], v[166:167], v[176:177] neg_lo:[0,1] neg_hi:[0,1]
	v_pk_add_f32 v[118:119], v[168:169], v[178:179] op_sel:[0,1] op_sel_hi:[1,0] neg_lo:[0,1]
	v_pk_add_f32 v[114:115], v[168:169], v[178:179] op_sel:[0,1] op_sel_hi:[1,0] neg_hi:[0,1]
	v_pk_add_f32 v[188:189], v[116:117], v[120:121]
	v_pk_add_f32 v[184:185], v[116:117], v[120:121] neg_lo:[0,1] neg_hi:[0,1]
	v_pk_add_f32 v[102:103], v[182:183], v[122:123]
	v_pk_add_f32 v[186:187], v[182:183], v[122:123] neg_lo:[0,1] neg_hi:[0,1]
	v_pk_add_f32 v[116:117], v[188:189], v[102:103]
	v_pk_add_f32 v[120:121], v[188:189], v[102:103] neg_lo:[0,1] neg_hi:[0,1]
	v_pk_add_f32 v[182:183], v[184:185], v[186:187] op_sel:[0,1] op_sel_hi:[1,0] neg_lo:[0,1]
	v_pk_add_f32 v[122:123], v[184:185], v[186:187] op_sel:[0,1] op_sel_hi:[1,0] neg_hi:[0,1]
	v_pk_add_f32 v[180:181], v[124:125], v[128:129]
	v_pk_add_f32 v[174:175], v[124:125], v[128:129] neg_lo:[0,1] neg_hi:[0,1]
	v_pk_add_f32 v[166:167], v[110:111], v[130:131]
	v_pk_add_f32 v[168:169], v[110:111], v[130:131] neg_lo:[0,1] neg_hi:[0,1]
	v_pk_add_f32 v[124:125], v[180:181], v[166:167]
	v_pk_add_f32 v[128:129], v[180:181], v[166:167] neg_lo:[0,1] neg_hi:[0,1]
	v_pk_add_f32 v[110:111], v[174:175], v[168:169] op_sel:[0,1] op_sel_hi:[1,0] neg_lo:[0,1]
	v_pk_add_f32 v[130:131], v[174:175], v[168:169] op_sel:[0,1] op_sel_hi:[1,0] neg_hi:[0,1]
	v_pk_mul_f32 v[176:177], v[118:119], s[68:69] op_sel:[1,1] op_sel_hi:[0,1]
	v_pk_fma_f32 v[118:119], v[118:119], s[68:69], v[176:177] op_sel_hi:[1,0,1] neg_hi:[0,0,1]
	v_pk_mul_f32 v[178:179], v[182:183], s[84:85] op_sel:[1,1] op_sel_hi:[0,1]
	v_pk_fma_f32 v[182:183], v[182:183], s[84:85], v[178:179] op_sel_hi:[1,0,1] neg_hi:[0,0,1]
	v_pk_mul_f32 v[188:189], v[110:111], s[88:89] op_sel:[1,1] op_sel_hi:[0,1]
	v_pk_fma_f32 v[110:111], v[110:111], s[88:89], v[188:189] op_sel_hi:[1,0,1] neg_hi:[0,0,1]
	v_pk_mul_f32 v[184:185], v[112:113], s[84:85] op_sel:[1,1] op_sel_hi:[0,1]
	v_pk_fma_f32 v[112:113], v[112:113], s[84:85], v[184:185] op_sel_hi:[1,0,1] neg_hi:[0,0,1]
	v_pk_mul_f32 v[102:103], v[128:129], s[90:91] op_sel:[1,1] op_sel_hi:[0,1]
	v_pk_fma_f32 v[128:129], v[128:129], s[90:91], v[102:103] op_sel_hi:[1,0,1] neg_hi:[0,0,1]
	v_pk_mul_f32 v[186:187], v[114:115], s[88:89] op_sel:[1,1] op_sel_hi:[0,1]
	v_pk_fma_f32 v[114:115], v[114:115], s[88:89], v[186:187] op_sel_hi:[1,0,1] neg_hi:[0,0,1]
	v_pk_mul_f32 v[180:181], v[122:123], s[90:91] op_sel:[1,1] op_sel_hi:[0,1]
	v_pk_fma_f32 v[122:123], v[122:123], s[90:91], v[180:181] op_sel_hi:[1,0,1] neg_hi:[0,0,1]
	v_pk_mul_f32 v[174:175], v[130:131], s[98:99] op_sel:[1,1] op_sel_hi:[0,1]
	v_pk_fma_f32 v[130:131], v[130:131], s[98:99], v[174:175] op_sel_hi:[1,0,1] neg_hi:[0,0,1]
	v_pk_add_f32 v[166:167], v[100:101], v[116:117]
	v_pk_add_f32 v[168:169], v[100:101], v[116:117] neg_lo:[0,1] neg_hi:[0,1]
	v_pk_add_f32 v[176:177], v[108:109], v[124:125]
	v_pk_add_f32 v[178:179], v[108:109], v[124:125] neg_lo:[0,1] neg_hi:[0,1]
	v_pk_add_f32 v[100:101], v[166:167], v[176:177]
	v_pk_add_f32 v[116:117], v[166:167], v[176:177] neg_lo:[0,1] neg_hi:[0,1]
	v_pk_add_f32 v[108:109], v[168:169], v[178:179] op_sel:[0,1] op_sel_hi:[1,0] neg_lo:[0,1]
	v_pk_add_f32 v[124:125], v[168:169], v[178:179] op_sel:[0,1] op_sel_hi:[1,0] neg_hi:[0,1]
	v_pk_add_f32 v[188:189], v[126:127], v[182:183]
	v_pk_add_f32 v[184:185], v[126:127], v[182:183] neg_lo:[0,1] neg_hi:[0,1]
	v_pk_add_f32 v[102:103], v[118:119], v[110:111]
	v_pk_add_f32 v[186:187], v[118:119], v[110:111] neg_lo:[0,1] neg_hi:[0,1]
	v_pk_add_f32 v[126:127], v[188:189], v[102:103]
	v_pk_add_f32 v[182:183], v[188:189], v[102:103] neg_lo:[0,1] neg_hi:[0,1]
	v_pk_add_f32 v[118:119], v[184:185], v[186:187] op_sel:[0,1] op_sel_hi:[1,0] neg_lo:[0,1]
	v_pk_add_f32 v[110:111], v[184:185], v[186:187] op_sel:[0,1] op_sel_hi:[1,0] neg_hi:[0,1]
	v_pk_add_f32 v[180:181], v[104:105], v[120:121] op_sel:[0,1] op_sel_hi:[1,0] neg_lo:[0,1]
	v_pk_add_f32 v[174:175], v[104:105], v[120:121] op_sel:[0,1] op_sel_hi:[1,0] neg_hi:[0,1]
	v_pk_add_f32 v[166:167], v[112:113], v[128:129]
	v_pk_add_f32 v[168:169], v[112:113], v[128:129] neg_lo:[0,1] neg_hi:[0,1]
	v_pk_add_f32 v[104:105], v[180:181], v[166:167]
	v_pk_add_f32 v[120:121], v[180:181], v[166:167] neg_lo:[0,1] neg_hi:[0,1]
	v_pk_add_f32 v[112:113], v[174:175], v[168:169] op_sel:[0,1] op_sel_hi:[1,0] neg_lo:[0,1]
	v_pk_add_f32 v[128:129], v[174:175], v[168:169] op_sel:[0,1] op_sel_hi:[1,0] neg_hi:[0,1]
	v_pk_add_f32 v[176:177], v[106:107], v[122:123]
	v_pk_add_f32 v[178:179], v[106:107], v[122:123] neg_lo:[0,1] neg_hi:[0,1]
	v_pk_add_f32 v[188:189], v[114:115], v[130:131]
	v_pk_add_f32 v[184:185], v[114:115], v[130:131] neg_lo:[0,1] neg_hi:[0,1]
	v_pk_add_f32 v[106:107], v[176:177], v[188:189]
	v_pk_add_f32 v[122:123], v[176:177], v[188:189] neg_lo:[0,1] neg_hi:[0,1]
	v_pk_add_f32 v[114:115], v[178:179], v[184:185] op_sel:[0,1] op_sel_hi:[1,0] neg_lo:[0,1]
	v_pk_add_f32 v[130:131], v[178:179], v[184:185] op_sel:[0,1] op_sel_hi:[1,0] neg_hi:[0,1]
	ds_write_b64 v5, v[100:101]
	ds_write_b64 v5, v[126:127] offset:264
	ds_write_b64 v5, v[104:105] offset:528
	ds_write_b64 v5, v[106:107] offset:792
	ds_write_b64 v5, v[108:109] offset:1056
	ds_write_b64 v5, v[118:119] offset:1320
	ds_write_b64 v5, v[112:113] offset:1584
	ds_write_b64 v5, v[114:115] offset:1848
	ds_write_b64 v5, v[116:117] offset:2112
	ds_write_b64 v5, v[182:183] offset:2376
	ds_write_b64 v5, v[120:121] offset:2640
	ds_write_b64 v5, v[122:123] offset:2904
	ds_write_b64 v5, v[124:125] offset:3168
	ds_write_b64 v5, v[110:111] offset:3432
	ds_write_b64 v5, v[128:129] offset:3696
	ds_write_b64 v5, v[130:131] offset:3960
	s_waitcnt lgkmcnt(0)
	s_barrier
	s_cbranch_vccz .Lhfft_st11
	s_sleep 2
